# v108_all_s_setprio_toggles_removed_from_gemm_kloops
# speedup vs baseline: 1.0181x; 1.0041x over previous
.LBB0_188:
	ds_read_b128 v[152:155], v147
	ds_read_b128 v[156:159], v147 offset:1024
	ds_read_b128 v[160:163], v147 offset:2048
	ds_read_b128 v[164:167], v147 offset:3072
	ds_read_b128 v[168:171], v149
	ds_read_b128 v[172:175], v149 offset:1024
	ds_read_b128 v[176:179], v149 offset:2048
	ds_read_b128 v[180:183], v149 offset:3072
	s_cmp_eq_u32 s8, 12
	s_cselect_b32 s49, s0, s3
	s_cselect_b32 s48, s1, s2
	s_or_b32 s9, s49, 0x80
	v_mov_b32_e32 v136, v135
	ds_read_b128 v[188:191], v150
	ds_read_b128 v[192:195], v150 offset:1024
	ds_read_b128 v[196:199], v150 offset:2048
	ds_read_b128 v[200:203], v150 offset:3072
	ds_read_b128 v[204:207], v150 offset:4096
	ds_read_b128 v[208:211], v150 offset:5120
	ds_read_b128 v[212:215], v150 offset:6144
	ds_read_b128 v[216:219], v150 offset:7168
	s_add_i32 m0, s25, 0xc000
	s_nop 0
	global_load_lds_dwordx4 v136, s[10:11]
	v_mov_b32_e32 v136, v134
	s_add_i32 m0, s25, 0xe000
	s_nop 0
	global_load_lds_dwordx4 v136, s[10:11]
	s_waitcnt vmcnt(8)
	s_waitcnt lgkmcnt(0)
	s_barrier
	s_waitcnt lgkmcnt(0)
	v_mfma_f32_16x16x32_bf16 v[124:127], v[152:155], v[188:191], v[124:127]
	v_mfma_f32_16x16x32_bf16 v[120:123], v[160:163], v[188:191], v[120:123]
	v_mfma_f32_16x16x32_bf16 v[108:111], v[152:155], v[196:199], v[108:111]
	v_mfma_f32_16x16x32_bf16 v[104:107], v[160:163], v[196:199], v[104:107]
	v_mfma_f32_16x16x32_bf16 v[92:95], v[152:155], v[204:207], v[92:95]
	v_mfma_f32_16x16x32_bf16 v[88:91], v[160:163], v[204:207], v[88:91]
	v_mfma_f32_16x16x32_bf16 v[76:79], v[152:155], v[212:215], v[76:79]
	v_mfma_f32_16x16x32_bf16 v[72:75], v[160:163], v[212:215], v[72:75]
	v_mfma_f32_16x16x32_bf16 v[124:127], v[156:159], v[192:195], v[124:127]
	v_mfma_f32_16x16x32_bf16 v[120:123], v[164:167], v[192:195], v[120:123]
	v_mfma_f32_16x16x32_bf16 v[108:111], v[156:159], v[200:203], v[108:111]
	v_mfma_f32_16x16x32_bf16 v[104:107], v[164:167], v[200:203], v[104:107]
	v_mfma_f32_16x16x32_bf16 v[92:95], v[156:159], v[208:211], v[92:95]
	v_mfma_f32_16x16x32_bf16 v[88:91], v[164:167], v[208:211], v[88:91]
	v_mfma_f32_16x16x32_bf16 v[76:79], v[156:159], v[216:219], v[76:79]
	v_mfma_f32_16x16x32_bf16 v[72:75], v[164:167], v[216:219], v[72:75]
	v_mfma_f32_16x16x32_bf16 v[116:119], v[168:171], v[188:191], v[116:119]
	v_mfma_f32_16x16x32_bf16 v[112:115], v[176:179], v[188:191], v[112:115]
	v_mfma_f32_16x16x32_bf16 v[100:103], v[168:171], v[196:199], v[100:103]
	v_mfma_f32_16x16x32_bf16 v[96:99], v[176:179], v[196:199], v[96:99]
	v_mfma_f32_16x16x32_bf16 v[84:87], v[168:171], v[204:207], v[84:87]
	v_mfma_f32_16x16x32_bf16 v[80:83], v[176:179], v[204:207], v[80:83]
	v_mfma_f32_16x16x32_bf16 v[68:71], v[168:171], v[212:215], v[68:71]
	v_mfma_f32_16x16x32_bf16 v[64:67], v[176:179], v[212:215], v[64:67]
	v_mfma_f32_16x16x32_bf16 v[116:119], v[172:175], v[192:195], v[116:119]
	v_mfma_f32_16x16x32_bf16 v[112:115], v[180:183], v[192:195], v[112:115]
	v_mfma_f32_16x16x32_bf16 v[100:103], v[172:175], v[200:203], v[100:103]
	v_mfma_f32_16x16x32_bf16 v[96:99], v[180:183], v[200:203], v[96:99]
	v_mfma_f32_16x16x32_bf16 v[84:87], v[172:175], v[208:211], v[84:87]
	v_mfma_f32_16x16x32_bf16 v[80:83], v[180:183], v[208:211], v[80:83]
	v_mfma_f32_16x16x32_bf16 v[68:71], v[172:175], v[216:219], v[68:71]
	v_mfma_f32_16x16x32_bf16 v[64:67], v[180:183], v[216:219], v[64:67]
	s_barrier
	v_add_u32_e32 v136, s48, v139
	s_add_i32 s50, s41, s24
	ds_read_b128 v[188:191], v150 offset:16384
	ds_read_b128 v[192:195], v150 offset:17408
	ds_read_b128 v[196:199], v150 offset:18432
	ds_read_b128 v[200:203], v150 offset:19456
	ds_read_b128 v[204:207], v150 offset:20480
	ds_read_b128 v[208:211], v150 offset:21504
	ds_read_b128 v[212:215], v150 offset:22528
	ds_read_b128 v[216:219], v150 offset:23552
	s_mov_b32 m0, s50
	s_add_i32 s51, s42, s24
	global_load_lds_dwordx4 v136, s[12:13]
	v_add_u32_e32 v136, s48, v141
	s_add_i32 m0, s50, 0x2000
	s_add_i32 s50, s48, 0x40000
	global_load_lds_dwordx4 v136, s[12:13]
	v_add_u32_e32 v136, s50, v139
	s_mov_b32 m0, s51
	s_nop 0
	global_load_lds_dwordx4 v136, s[12:13]
	v_add_u32_e32 v136, s50, v141
	s_add_i32 m0, s51, 0x2000
	s_nop 0
	global_load_lds_dwordx4 v136, s[12:13]
	v_add_u32_e32 v136, s49, v138
	s_mov_b32 m0, s25
	s_nop 0
	global_load_lds_dwordx4 v136, s[10:11]
	v_add_u32_e32 v136, s49, v140
	s_mov_b32 m0, s26
	s_nop 0
	global_load_lds_dwordx4 v136, s[10:11]
	s_waitcnt vmcnt(8)
	s_waitcnt lgkmcnt(0)
	s_barrier
	s_waitcnt lgkmcnt(0)
	v_mfma_f32_16x16x32_bf16 v[60:63], v[152:155], v[188:191], v[60:63]
	v_mfma_f32_16x16x32_bf16 v[56:59], v[160:163], v[188:191], v[56:59]
	v_mfma_f32_16x16x32_bf16 v[44:47], v[152:155], v[196:199], v[44:47]
	v_mfma_f32_16x16x32_bf16 v[40:43], v[160:163], v[196:199], v[40:43]
	v_mfma_f32_16x16x32_bf16 v[28:31], v[152:155], v[204:207], v[28:31]
	v_mfma_f32_16x16x32_bf16 v[24:27], v[160:163], v[204:207], v[24:27]
	v_mfma_f32_16x16x32_bf16 v[12:15], v[152:155], v[212:215], v[12:15]
	v_mfma_f32_16x16x32_bf16 v[8:11], v[160:163], v[212:215], v[8:11]
	v_mfma_f32_16x16x32_bf16 v[60:63], v[156:159], v[192:195], v[60:63]
	v_mfma_f32_16x16x32_bf16 v[56:59], v[164:167], v[192:195], v[56:59]
	v_mfma_f32_16x16x32_bf16 v[44:47], v[156:159], v[200:203], v[44:47]
	v_mfma_f32_16x16x32_bf16 v[40:43], v[164:167], v[200:203], v[40:43]
	v_mfma_f32_16x16x32_bf16 v[28:31], v[156:159], v[208:211], v[28:31]
	v_mfma_f32_16x16x32_bf16 v[24:27], v[164:167], v[208:211], v[24:27]
	v_mfma_f32_16x16x32_bf16 v[12:15], v[156:159], v[216:219], v[12:15]
	v_mfma_f32_16x16x32_bf16 v[8:11], v[164:167], v[216:219], v[8:11]
	v_mfma_f32_16x16x32_bf16 v[52:55], v[168:171], v[188:191], v[52:55]
	v_mfma_f32_16x16x32_bf16 v[48:51], v[176:179], v[188:191], v[48:51]
	v_mfma_f32_16x16x32_bf16 v[36:39], v[168:171], v[196:199], v[36:39]
	v_mfma_f32_16x16x32_bf16 v[32:35], v[176:179], v[196:199], v[32:35]
	v_mfma_f32_16x16x32_bf16 v[20:23], v[168:171], v[204:207], v[20:23]
	v_mfma_f32_16x16x32_bf16 v[16:19], v[176:179], v[204:207], v[16:19]
	v_mfma_f32_16x16x32_bf16 v[4:7], v[168:171], v[212:215], v[4:7]
	v_mfma_f32_16x16x32_bf16 v[0:3], v[176:179], v[212:215], v[0:3]
	v_mfma_f32_16x16x32_bf16 v[52:55], v[172:175], v[192:195], v[52:55]
	v_mfma_f32_16x16x32_bf16 v[48:51], v[180:183], v[192:195], v[48:51]
	v_mfma_f32_16x16x32_bf16 v[36:39], v[172:175], v[200:203], v[36:39]
	v_mfma_f32_16x16x32_bf16 v[32:35], v[180:183], v[200:203], v[32:35]
	v_mfma_f32_16x16x32_bf16 v[20:23], v[172:175], v[208:211], v[20:23]
	v_mfma_f32_16x16x32_bf16 v[16:19], v[180:183], v[208:211], v[16:19]
	v_mfma_f32_16x16x32_bf16 v[4:7], v[172:175], v[216:219], v[4:7]
	v_mfma_f32_16x16x32_bf16 v[0:3], v[180:183], v[216:219], v[0:3]
	s_barrier
; #define PG8_BAR __builtin_amdgcn_s_barrier()
;     ...
;         if constexpr (Epi::MIDHOOK) {
;             for (int t = 0; t < 4; t += 2) PG8_ITER(t);
;             E.mid(acc, cur, wr, wc, fr, fq);
;             for (int t = 4; t < nt; t += 2) PG8_ITER(t);
;         } else {
;             for (int t = 0; t < nt; t += 2) PG8_ITER(t);
;         }
;     ...
;         if constexpr (ALIGN_EPI) { if (wr == 0) PG8_BAR; }
	s_add_i32 s50, 0, 0x18000
	v_add_u32_e32 v136, s50, v143
	s_add_i32 s51, 0, 0x1c000
	ds_read_b128 v[152:155], v136
	ds_read_b128 v[156:159], v136 offset:1024
	ds_read_b128 v[160:163], v136 offset:2048
	ds_read_b128 v[164:167], v136 offset:3072
	v_add_u32_e32 v136, s51, v143
	ds_read_b128 v[168:171], v136
	ds_read_b128 v[172:175], v136 offset:1024
	ds_read_b128 v[176:179], v136 offset:2048
	ds_read_b128 v[180:183], v136 offset:3072
	s_add_i32 s49, s49, 0x40000
	v_add_u32_e32 v136, s49, v138
	s_mov_b32 m0, s27
	ds_read_b128 v[188:191], v150 offset:32768
	ds_read_b128 v[192:195], v150 offset:33792
	ds_read_b128 v[196:199], v150 offset:34816
	ds_read_b128 v[200:203], v150 offset:35840
	ds_read_b128 v[204:207], v150 offset:36864
	ds_read_b128 v[208:211], v150 offset:37888
	ds_read_b128 v[212:215], v150 offset:38912
	ds_read_b128 v[216:219], v150 offset:39936
	s_nop 0
	global_load_lds_dwordx4 v136, s[10:11]
	v_add_u32_e32 v136, s49, v140
	s_mov_b32 m0, s28
	s_nop 0
	global_load_lds_dwordx4 v136, s[10:11]
	s_waitcnt vmcnt(8)
	s_waitcnt lgkmcnt(0)
	s_barrier
	s_waitcnt lgkmcnt(0)
	v_mfma_f32_16x16x32_bf16 v[124:127], v[152:155], v[188:191], v[124:127]
	v_mfma_f32_16x16x32_bf16 v[120:123], v[160:163], v[188:191], v[120:123]
	v_mfma_f32_16x16x32_bf16 v[108:111], v[152:155], v[196:199], v[108:111]
	v_mfma_f32_16x16x32_bf16 v[104:107], v[160:163], v[196:199], v[104:107]
	v_mfma_f32_16x16x32_bf16 v[92:95], v[152:155], v[204:207], v[92:95]
	v_mfma_f32_16x16x32_bf16 v[88:91], v[160:163], v[204:207], v[88:91]
	v_mfma_f32_16x16x32_bf16 v[76:79], v[152:155], v[212:215], v[76:79]
	v_mfma_f32_16x16x32_bf16 v[72:75], v[160:163], v[212:215], v[72:75]
	v_mfma_f32_16x16x32_bf16 v[124:127], v[156:159], v[192:195], v[124:127]
	v_mfma_f32_16x16x32_bf16 v[120:123], v[164:167], v[192:195], v[120:123]
	v_mfma_f32_16x16x32_bf16 v[108:111], v[156:159], v[200:203], v[108:111]
	v_mfma_f32_16x16x32_bf16 v[104:107], v[164:167], v[200:203], v[104:107]
	v_mfma_f32_16x16x32_bf16 v[92:95], v[156:159], v[208:211], v[92:95]
	v_mfma_f32_16x16x32_bf16 v[88:91], v[164:167], v[208:211], v[88:91]
	v_mfma_f32_16x16x32_bf16 v[76:79], v[156:159], v[216:219], v[76:79]
	v_mfma_f32_16x16x32_bf16 v[72:75], v[164:167], v[216:219], v[72:75]
	v_mfma_f32_16x16x32_bf16 v[116:119], v[168:171], v[188:191], v[116:119]
	v_mfma_f32_16x16x32_bf16 v[112:115], v[176:179], v[188:191], v[112:115]
	v_mfma_f32_16x16x32_bf16 v[100:103], v[168:171], v[196:199], v[100:103]
	v_mfma_f32_16x16x32_bf16 v[96:99], v[176:179], v[196:199], v[96:99]
	v_mfma_f32_16x16x32_bf16 v[84:87], v[168:171], v[204:207], v[84:87]
	v_mfma_f32_16x16x32_bf16 v[80:83], v[176:179], v[204:207], v[80:83]
	v_mfma_f32_16x16x32_bf16 v[68:71], v[168:171], v[212:215], v[68:71]
	v_mfma_f32_16x16x32_bf16 v[64:67], v[176:179], v[212:215], v[64:67]
	v_mfma_f32_16x16x32_bf16 v[116:119], v[172:175], v[192:195], v[116:119]
	v_mfma_f32_16x16x32_bf16 v[112:115], v[180:183], v[192:195], v[112:115]
	v_mfma_f32_16x16x32_bf16 v[100:103], v[172:175], v[200:203], v[100:103]
	v_mfma_f32_16x16x32_bf16 v[96:99], v[180:183], v[200:203], v[96:99]
	v_mfma_f32_16x16x32_bf16 v[84:87], v[172:175], v[208:211], v[84:87]
	v_mfma_f32_16x16x32_bf16 v[80:83], v[180:183], v[208:211], v[80:83]
	v_mfma_f32_16x16x32_bf16 v[68:71], v[172:175], v[216:219], v[68:71]
	v_mfma_f32_16x16x32_bf16 v[64:67], v[180:183], v[216:219], v[64:67]
	s_barrier
	s_or_b32 s49, s48, 0x80
	v_add_u32_e32 v136, s49, v139
	s_add_i32 s50, s50, s24
	ds_read_b128 v[188:191], v150 offset:49152
	ds_read_b128 v[192:195], v150 offset:50176
	ds_read_b128 v[196:199], v150 offset:51200
	ds_read_b128 v[200:203], v150 offset:52224
	ds_read_b128 v[204:207], v150 offset:53248
	ds_read_b128 v[208:211], v150 offset:54272
	ds_read_b128 v[212:215], v150 offset:55296
	ds_read_b128 v[216:219], v150 offset:56320
	s_mov_b32 m0, s50
	s_add_i32 s48, s48, 0x40080
	global_load_lds_dwordx4 v136, s[12:13]
	v_add_u32_e32 v136, s49, v141
	s_add_i32 m0, s50, 0x2000
	s_add_i32 s49, s51, s24
	global_load_lds_dwordx4 v136, s[12:13]
	v_add_u32_e32 v136, s48, v139
	s_mov_b32 m0, s49
	s_nop 0
	global_load_lds_dwordx4 v136, s[12:13]
	v_add_u32_e32 v136, s48, v141
	s_add_i32 m0, s49, 0x2000
	s_nop 0
	global_load_lds_dwordx4 v136, s[12:13]
	v_add_u32_e32 v136, s9, v138
	s_mov_b32 m0, s30
	s_nop 0
	global_load_lds_dwordx4 v136, s[10:11]
	v_add_u32_e32 v136, s9, v140
	s_mov_b32 m0, s31
	s_nop 0
	global_load_lds_dwordx4 v136, s[10:11]
	s_waitcnt vmcnt(8)
	s_waitcnt lgkmcnt(0)
	s_barrier
	s_waitcnt lgkmcnt(0)
	v_mfma_f32_16x16x32_bf16 v[60:63], v[152:155], v[188:191], v[60:63]
	v_mfma_f32_16x16x32_bf16 v[56:59], v[160:163], v[188:191], v[56:59]
	v_mfma_f32_16x16x32_bf16 v[44:47], v[152:155], v[196:199], v[44:47]
	v_mfma_f32_16x16x32_bf16 v[40:43], v[160:163], v[196:199], v[40:43]
	v_mfma_f32_16x16x32_bf16 v[28:31], v[152:155], v[204:207], v[28:31]
	v_mfma_f32_16x16x32_bf16 v[24:27], v[160:163], v[204:207], v[24:27]
	v_mfma_f32_16x16x32_bf16 v[12:15], v[152:155], v[212:215], v[12:15]
	v_mfma_f32_16x16x32_bf16 v[8:11], v[160:163], v[212:215], v[8:11]
	v_mfma_f32_16x16x32_bf16 v[60:63], v[156:159], v[192:195], v[60:63]
	v_mfma_f32_16x16x32_bf16 v[56:59], v[164:167], v[192:195], v[56:59]
	v_mfma_f32_16x16x32_bf16 v[44:47], v[156:159], v[200:203], v[44:47]
	v_mfma_f32_16x16x32_bf16 v[40:43], v[164:167], v[200:203], v[40:43]
	v_mfma_f32_16x16x32_bf16 v[28:31], v[156:159], v[208:211], v[28:31]
	v_mfma_f32_16x16x32_bf16 v[24:27], v[164:167], v[208:211], v[24:27]
	v_mfma_f32_16x16x32_bf16 v[12:15], v[156:159], v[216:219], v[12:15]
	v_mfma_f32_16x16x32_bf16 v[8:11], v[164:167], v[216:219], v[8:11]
	v_mfma_f32_16x16x32_bf16 v[52:55], v[168:171], v[188:191], v[52:55]
	v_mfma_f32_16x16x32_bf16 v[48:51], v[176:179], v[188:191], v[48:51]
	v_mfma_f32_16x16x32_bf16 v[36:39], v[168:171], v[196:199], v[36:39]
	v_mfma_f32_16x16x32_bf16 v[32:35], v[176:179], v[196:199], v[32:35]
	v_mfma_f32_16x16x32_bf16 v[20:23], v[168:171], v[204:207], v[20:23]
	v_mfma_f32_16x16x32_bf16 v[16:19], v[176:179], v[204:207], v[16:19]
	v_mfma_f32_16x16x32_bf16 v[4:7], v[168:171], v[212:215], v[4:7]
	v_mfma_f32_16x16x32_bf16 v[0:3], v[176:179], v[212:215], v[0:3]
	v_mfma_f32_16x16x32_bf16 v[52:55], v[172:175], v[192:195], v[52:55]
	v_mfma_f32_16x16x32_bf16 v[48:51], v[180:183], v[192:195], v[48:51]
	v_mfma_f32_16x16x32_bf16 v[36:39], v[172:175], v[200:203], v[36:39]
	v_mfma_f32_16x16x32_bf16 v[32:35], v[180:183], v[200:203], v[32:35]
	v_mfma_f32_16x16x32_bf16 v[20:23], v[172:175], v[208:211], v[20:23]
	v_mfma_f32_16x16x32_bf16 v[16:19], v[180:183], v[208:211], v[16:19]
	v_mfma_f32_16x16x32_bf16 v[4:7], v[172:175], v[216:219], v[4:7]
	v_mfma_f32_16x16x32_bf16 v[0:3], v[180:183], v[216:219], v[0:3]
	s_barrier
	s_add_i32 s8, s8, 2
	s_addk_i32 s2, 0x100
	s_addk_i32 s3, 0x100
	v_add_u32_e32 v134, 0x100, v134
	s_cmp_gt_u32 s8, 13
	v_add_u32_e32 v135, 0x100, v135
	s_cbranch_scc0 .LBB0_188
	s_and_b64 vcc, exec, s[18:19]
	s_cbranch_vccz .LBB0_191
	s_barrier

.LBB0_468:
	ds_read_b128 v[148:151], v145
	ds_read_b128 v[152:155], v145 offset:1024
	ds_read_b128 v[156:159], v145 offset:2048
	ds_read_b128 v[160:163], v145 offset:3072
	ds_read_b128 v[164:167], v146
	ds_read_b128 v[168:171], v146 offset:1024
	ds_read_b128 v[172:175], v146 offset:2048
	ds_read_b128 v[176:179], v146 offset:3072
	s_cmp_eq_u32 s44, 12
	s_cselect_b32 s47, s0, s43
	s_cselect_b32 s46, s1, s42
	s_or_b32 s45, s47, 0x80
	v_mov_b32_e32 v135, v134
	ds_read_b128 v[180:183], v147
	ds_read_b128 v[192:195], v147 offset:1024
	ds_read_b128 v[196:199], v147 offset:2048
	ds_read_b128 v[200:203], v147 offset:3072
	ds_read_b128 v[204:207], v147 offset:4096
	ds_read_b128 v[208:211], v147 offset:5120
	ds_read_b128 v[212:215], v147 offset:6144
	ds_read_b128 v[216:219], v147 offset:7168
	s_add_i32 m0, s22, 0xc000
	s_nop 0
	global_load_lds_dwordx4 v135, s[10:11]
	v_mov_b32_e32 v135, v132
	s_add_i32 m0, s22, 0xe000
	s_nop 0
	global_load_lds_dwordx4 v135, s[10:11]
	s_waitcnt vmcnt(8)
	s_waitcnt lgkmcnt(0)
	s_barrier
	s_waitcnt lgkmcnt(0)
	v_mfma_f32_16x16x32_bf16 v[124:127], v[148:151], v[180:183], v[124:127]
	v_mfma_f32_16x16x32_bf16 v[120:123], v[156:159], v[180:183], v[120:123]
	v_mfma_f32_16x16x32_bf16 v[108:111], v[148:151], v[196:199], v[108:111]
	v_mfma_f32_16x16x32_bf16 v[104:107], v[156:159], v[196:199], v[104:107]
	v_mfma_f32_16x16x32_bf16 v[92:95], v[148:151], v[204:207], v[92:95]
	v_mfma_f32_16x16x32_bf16 v[88:91], v[156:159], v[204:207], v[88:91]
	v_mfma_f32_16x16x32_bf16 v[76:79], v[148:151], v[212:215], v[76:79]
	v_mfma_f32_16x16x32_bf16 v[72:75], v[156:159], v[212:215], v[72:75]
	v_mfma_f32_16x16x32_bf16 v[124:127], v[152:155], v[192:195], v[124:127]
	v_mfma_f32_16x16x32_bf16 v[120:123], v[160:163], v[192:195], v[120:123]
	v_mfma_f32_16x16x32_bf16 v[108:111], v[152:155], v[200:203], v[108:111]
	v_mfma_f32_16x16x32_bf16 v[104:107], v[160:163], v[200:203], v[104:107]
	v_mfma_f32_16x16x32_bf16 v[92:95], v[152:155], v[208:211], v[92:95]
	v_mfma_f32_16x16x32_bf16 v[88:91], v[160:163], v[208:211], v[88:91]
	v_mfma_f32_16x16x32_bf16 v[76:79], v[152:155], v[216:219], v[76:79]
	v_mfma_f32_16x16x32_bf16 v[72:75], v[160:163], v[216:219], v[72:75]
	v_mfma_f32_16x16x32_bf16 v[116:119], v[164:167], v[180:183], v[116:119]
	v_mfma_f32_16x16x32_bf16 v[112:115], v[172:175], v[180:183], v[112:115]
	v_mfma_f32_16x16x32_bf16 v[100:103], v[164:167], v[196:199], v[100:103]
	v_mfma_f32_16x16x32_bf16 v[96:99], v[172:175], v[196:199], v[96:99]
	v_mfma_f32_16x16x32_bf16 v[84:87], v[164:167], v[204:207], v[84:87]
	v_mfma_f32_16x16x32_bf16 v[80:83], v[172:175], v[204:207], v[80:83]
	v_mfma_f32_16x16x32_bf16 v[68:71], v[164:167], v[212:215], v[68:71]
	v_mfma_f32_16x16x32_bf16 v[64:67], v[172:175], v[212:215], v[64:67]
	v_mfma_f32_16x16x32_bf16 v[116:119], v[168:171], v[192:195], v[116:119]
	v_mfma_f32_16x16x32_bf16 v[112:115], v[176:179], v[192:195], v[112:115]
	v_mfma_f32_16x16x32_bf16 v[100:103], v[168:171], v[200:203], v[100:103]
	v_mfma_f32_16x16x32_bf16 v[96:99], v[176:179], v[200:203], v[96:99]
	v_mfma_f32_16x16x32_bf16 v[84:87], v[168:171], v[208:211], v[84:87]
	v_mfma_f32_16x16x32_bf16 v[80:83], v[176:179], v[208:211], v[80:83]
	v_mfma_f32_16x16x32_bf16 v[68:71], v[168:171], v[216:219], v[68:71]
	v_mfma_f32_16x16x32_bf16 v[64:67], v[176:179], v[216:219], v[64:67]
	s_barrier
	v_add_u32_e32 v135, s46, v137
	s_add_i32 s48, s35, s19
	ds_read_b128 v[180:183], v147 offset:16384
	ds_read_b128 v[192:195], v147 offset:17408
	ds_read_b128 v[196:199], v147 offset:18432
	ds_read_b128 v[200:203], v147 offset:19456
	ds_read_b128 v[204:207], v147 offset:20480
	ds_read_b128 v[208:211], v147 offset:21504
	ds_read_b128 v[212:215], v147 offset:22528
	ds_read_b128 v[216:219], v147 offset:23552
	s_mov_b32 m0, s48
	s_add_i32 s49, s36, s19
	global_load_lds_dwordx4 v135, s[12:13]
	v_add_u32_e32 v135, s46, v139
	s_add_i32 m0, s48, 0x2000
	s_add_i32 s48, s46, 0x40000
	global_load_lds_dwordx4 v135, s[12:13]
	v_add_u32_e32 v135, s48, v137
	s_mov_b32 m0, s49
	s_nop 0
	global_load_lds_dwordx4 v135, s[12:13]
	v_add_u32_e32 v135, s48, v139
	s_add_i32 m0, s49, 0x2000
	s_nop 0
	global_load_lds_dwordx4 v135, s[12:13]
	v_add_u32_e32 v135, s47, v136
	s_mov_b32 m0, s22
	s_nop 0
	global_load_lds_dwordx4 v135, s[10:11]
	v_add_u32_e32 v135, s47, v138
	s_mov_b32 m0, s23
	s_nop 0
	global_load_lds_dwordx4 v135, s[10:11]
	s_waitcnt vmcnt(8)
	s_waitcnt lgkmcnt(0)
	s_barrier
	s_waitcnt lgkmcnt(0)
	v_mfma_f32_16x16x32_bf16 v[60:63], v[148:151], v[180:183], v[60:63]
	v_mfma_f32_16x16x32_bf16 v[56:59], v[156:159], v[180:183], v[56:59]
	v_mfma_f32_16x16x32_bf16 v[44:47], v[148:151], v[196:199], v[44:47]
	v_mfma_f32_16x16x32_bf16 v[40:43], v[156:159], v[196:199], v[40:43]
	v_mfma_f32_16x16x32_bf16 v[28:31], v[148:151], v[204:207], v[28:31]
	v_mfma_f32_16x16x32_bf16 v[24:27], v[156:159], v[204:207], v[24:27]
	v_mfma_f32_16x16x32_bf16 v[12:15], v[148:151], v[212:215], v[12:15]
	v_mfma_f32_16x16x32_bf16 v[8:11], v[156:159], v[212:215], v[8:11]
	v_mfma_f32_16x16x32_bf16 v[60:63], v[152:155], v[192:195], v[60:63]
	v_mfma_f32_16x16x32_bf16 v[56:59], v[160:163], v[192:195], v[56:59]
	v_mfma_f32_16x16x32_bf16 v[44:47], v[152:155], v[200:203], v[44:47]
	v_mfma_f32_16x16x32_bf16 v[40:43], v[160:163], v[200:203], v[40:43]
	v_mfma_f32_16x16x32_bf16 v[28:31], v[152:155], v[208:211], v[28:31]
	v_mfma_f32_16x16x32_bf16 v[24:27], v[160:163], v[208:211], v[24:27]
	v_mfma_f32_16x16x32_bf16 v[12:15], v[152:155], v[216:219], v[12:15]
	v_mfma_f32_16x16x32_bf16 v[8:11], v[160:163], v[216:219], v[8:11]
	v_mfma_f32_16x16x32_bf16 v[52:55], v[164:167], v[180:183], v[52:55]
	v_mfma_f32_16x16x32_bf16 v[48:51], v[172:175], v[180:183], v[48:51]
	v_mfma_f32_16x16x32_bf16 v[36:39], v[164:167], v[196:199], v[36:39]
	v_mfma_f32_16x16x32_bf16 v[32:35], v[172:175], v[196:199], v[32:35]
	v_mfma_f32_16x16x32_bf16 v[20:23], v[164:167], v[204:207], v[20:23]
	v_mfma_f32_16x16x32_bf16 v[16:19], v[172:175], v[204:207], v[16:19]
	v_mfma_f32_16x16x32_bf16 v[4:7], v[164:167], v[212:215], v[4:7]
	v_mfma_f32_16x16x32_bf16 v[0:3], v[172:175], v[212:215], v[0:3]
	v_mfma_f32_16x16x32_bf16 v[52:55], v[168:171], v[192:195], v[52:55]
	v_mfma_f32_16x16x32_bf16 v[48:51], v[176:179], v[192:195], v[48:51]
	v_mfma_f32_16x16x32_bf16 v[36:39], v[168:171], v[200:203], v[36:39]
	v_mfma_f32_16x16x32_bf16 v[32:35], v[176:179], v[200:203], v[32:35]
	v_mfma_f32_16x16x32_bf16 v[20:23], v[168:171], v[208:211], v[20:23]
	v_mfma_f32_16x16x32_bf16 v[16:19], v[176:179], v[208:211], v[16:19]
	v_mfma_f32_16x16x32_bf16 v[4:7], v[168:171], v[216:219], v[4:7]
	v_mfma_f32_16x16x32_bf16 v[0:3], v[176:179], v[216:219], v[0:3]
	s_barrier
; #define PG8_BAR __builtin_amdgcn_s_barrier()
;     ...
;         if constexpr (Epi::MIDHOOK) {
;             for (int t = 0; t < 4; t += 2) PG8_ITER(t);
;             E.mid(acc, cur, wr, wc, fr, fq);
;             for (int t = 4; t < nt; t += 2) PG8_ITER(t);
;         } else {
;             for (int t = 0; t < nt; t += 2) PG8_ITER(t);
;         }
;     ...
;         if constexpr (ALIGN_EPI) { if (wr == 0) PG8_BAR; }
	s_add_i32 s48, 0, 0x18000
	v_add_u32_e32 v135, s48, v141
	s_add_i32 s49, 0, 0x1c000
	ds_read_b128 v[148:151], v135
	ds_read_b128 v[152:155], v135 offset:1024
	ds_read_b128 v[156:159], v135 offset:2048
	ds_read_b128 v[160:163], v135 offset:3072
	v_add_u32_e32 v135, s49, v141
	ds_read_b128 v[164:167], v135
	ds_read_b128 v[168:171], v135 offset:1024
	ds_read_b128 v[172:175], v135 offset:2048
	ds_read_b128 v[176:179], v135 offset:3072
	s_add_i32 s47, s47, 0x40000
	v_add_u32_e32 v135, s47, v136
	s_mov_b32 m0, s24
	ds_read_b128 v[180:183], v147 offset:32768
	ds_read_b128 v[192:195], v147 offset:33792
	ds_read_b128 v[196:199], v147 offset:34816
	ds_read_b128 v[200:203], v147 offset:35840
	ds_read_b128 v[204:207], v147 offset:36864
	ds_read_b128 v[208:211], v147 offset:37888
	ds_read_b128 v[212:215], v147 offset:38912
	ds_read_b128 v[216:219], v147 offset:39936
	s_nop 0
	global_load_lds_dwordx4 v135, s[10:11]
	v_add_u32_e32 v135, s47, v138
	s_mov_b32 m0, s25
	s_nop 0
	global_load_lds_dwordx4 v135, s[10:11]
	s_waitcnt vmcnt(8)
	s_waitcnt lgkmcnt(0)
	s_barrier
	s_waitcnt lgkmcnt(0)
	v_mfma_f32_16x16x32_bf16 v[124:127], v[148:151], v[180:183], v[124:127]
	v_mfma_f32_16x16x32_bf16 v[120:123], v[156:159], v[180:183], v[120:123]
	v_mfma_f32_16x16x32_bf16 v[108:111], v[148:151], v[196:199], v[108:111]
	v_mfma_f32_16x16x32_bf16 v[104:107], v[156:159], v[196:199], v[104:107]
	v_mfma_f32_16x16x32_bf16 v[92:95], v[148:151], v[204:207], v[92:95]
	v_mfma_f32_16x16x32_bf16 v[88:91], v[156:159], v[204:207], v[88:91]
	v_mfma_f32_16x16x32_bf16 v[76:79], v[148:151], v[212:215], v[76:79]
	v_mfma_f32_16x16x32_bf16 v[72:75], v[156:159], v[212:215], v[72:75]
	v_mfma_f32_16x16x32_bf16 v[124:127], v[152:155], v[192:195], v[124:127]
	v_mfma_f32_16x16x32_bf16 v[120:123], v[160:163], v[192:195], v[120:123]
	v_mfma_f32_16x16x32_bf16 v[108:111], v[152:155], v[200:203], v[108:111]
	v_mfma_f32_16x16x32_bf16 v[104:107], v[160:163], v[200:203], v[104:107]
	v_mfma_f32_16x16x32_bf16 v[92:95], v[152:155], v[208:211], v[92:95]
	v_mfma_f32_16x16x32_bf16 v[88:91], v[160:163], v[208:211], v[88:91]
	v_mfma_f32_16x16x32_bf16 v[76:79], v[152:155], v[216:219], v[76:79]
	v_mfma_f32_16x16x32_bf16 v[72:75], v[160:163], v[216:219], v[72:75]
	v_mfma_f32_16x16x32_bf16 v[116:119], v[164:167], v[180:183], v[116:119]
	v_mfma_f32_16x16x32_bf16 v[112:115], v[172:175], v[180:183], v[112:115]
	v_mfma_f32_16x16x32_bf16 v[100:103], v[164:167], v[196:199], v[100:103]
	v_mfma_f32_16x16x32_bf16 v[96:99], v[172:175], v[196:199], v[96:99]
	v_mfma_f32_16x16x32_bf16 v[84:87], v[164:167], v[204:207], v[84:87]
	v_mfma_f32_16x16x32_bf16 v[80:83], v[172:175], v[204:207], v[80:83]
	v_mfma_f32_16x16x32_bf16 v[68:71], v[164:167], v[212:215], v[68:71]
	v_mfma_f32_16x16x32_bf16 v[64:67], v[172:175], v[212:215], v[64:67]
	v_mfma_f32_16x16x32_bf16 v[116:119], v[168:171], v[192:195], v[116:119]
	v_mfma_f32_16x16x32_bf16 v[112:115], v[176:179], v[192:195], v[112:115]
	v_mfma_f32_16x16x32_bf16 v[100:103], v[168:171], v[200:203], v[100:103]
	v_mfma_f32_16x16x32_bf16 v[96:99], v[176:179], v[200:203], v[96:99]
	v_mfma_f32_16x16x32_bf16 v[84:87], v[168:171], v[208:211], v[84:87]
	v_mfma_f32_16x16x32_bf16 v[80:83], v[176:179], v[208:211], v[80:83]
	v_mfma_f32_16x16x32_bf16 v[68:71], v[168:171], v[216:219], v[68:71]
	v_mfma_f32_16x16x32_bf16 v[64:67], v[176:179], v[216:219], v[64:67]
	s_barrier
	s_or_b32 s47, s46, 0x80
	v_add_u32_e32 v135, s47, v137
	s_add_i32 s48, s48, s19
	ds_read_b128 v[180:183], v147 offset:49152
	ds_read_b128 v[192:195], v147 offset:50176
	ds_read_b128 v[196:199], v147 offset:51200
	ds_read_b128 v[200:203], v147 offset:52224
	ds_read_b128 v[204:207], v147 offset:53248
	ds_read_b128 v[208:211], v147 offset:54272
	ds_read_b128 v[212:215], v147 offset:55296
	ds_read_b128 v[216:219], v147 offset:56320
	s_mov_b32 m0, s48
	s_add_i32 s46, s46, 0x40080
	global_load_lds_dwordx4 v135, s[12:13]
	v_add_u32_e32 v135, s47, v139
	s_add_i32 m0, s48, 0x2000
	s_add_i32 s47, s49, s19
	global_load_lds_dwordx4 v135, s[12:13]
	v_add_u32_e32 v135, s46, v137
	s_mov_b32 m0, s47
	s_nop 0
	global_load_lds_dwordx4 v135, s[12:13]
	v_add_u32_e32 v135, s46, v139
	s_add_i32 m0, s47, 0x2000
	s_nop 0
	global_load_lds_dwordx4 v135, s[12:13]
	v_add_u32_e32 v135, s45, v136
	s_mov_b32 m0, s30
	s_nop 0
	global_load_lds_dwordx4 v135, s[10:11]
	v_add_u32_e32 v135, s45, v138
	s_mov_b32 m0, s31
	s_nop 0
	global_load_lds_dwordx4 v135, s[10:11]
	s_waitcnt vmcnt(8)
	s_waitcnt lgkmcnt(0)
	s_barrier
	s_waitcnt lgkmcnt(0)
	v_mfma_f32_16x16x32_bf16 v[60:63], v[148:151], v[180:183], v[60:63]
	v_mfma_f32_16x16x32_bf16 v[56:59], v[156:159], v[180:183], v[56:59]
	v_mfma_f32_16x16x32_bf16 v[44:47], v[148:151], v[196:199], v[44:47]
	v_mfma_f32_16x16x32_bf16 v[40:43], v[156:159], v[196:199], v[40:43]
	v_mfma_f32_16x16x32_bf16 v[28:31], v[148:151], v[204:207], v[28:31]
	v_mfma_f32_16x16x32_bf16 v[24:27], v[156:159], v[204:207], v[24:27]
	v_mfma_f32_16x16x32_bf16 v[12:15], v[148:151], v[212:215], v[12:15]
	v_mfma_f32_16x16x32_bf16 v[8:11], v[156:159], v[212:215], v[8:11]
	v_mfma_f32_16x16x32_bf16 v[60:63], v[152:155], v[192:195], v[60:63]
	v_mfma_f32_16x16x32_bf16 v[56:59], v[160:163], v[192:195], v[56:59]
	v_mfma_f32_16x16x32_bf16 v[44:47], v[152:155], v[200:203], v[44:47]
	v_mfma_f32_16x16x32_bf16 v[40:43], v[160:163], v[200:203], v[40:43]
	v_mfma_f32_16x16x32_bf16 v[28:31], v[152:155], v[208:211], v[28:31]
	v_mfma_f32_16x16x32_bf16 v[24:27], v[160:163], v[208:211], v[24:27]
	v_mfma_f32_16x16x32_bf16 v[12:15], v[152:155], v[216:219], v[12:15]
	v_mfma_f32_16x16x32_bf16 v[8:11], v[160:163], v[216:219], v[8:11]
	v_mfma_f32_16x16x32_bf16 v[52:55], v[164:167], v[180:183], v[52:55]
	v_mfma_f32_16x16x32_bf16 v[48:51], v[172:175], v[180:183], v[48:51]
	v_mfma_f32_16x16x32_bf16 v[36:39], v[164:167], v[196:199], v[36:39]
	v_mfma_f32_16x16x32_bf16 v[32:35], v[172:175], v[196:199], v[32:35]
	v_mfma_f32_16x16x32_bf16 v[20:23], v[164:167], v[204:207], v[20:23]
	v_mfma_f32_16x16x32_bf16 v[16:19], v[172:175], v[204:207], v[16:19]
	v_mfma_f32_16x16x32_bf16 v[4:7], v[164:167], v[212:215], v[4:7]
	v_mfma_f32_16x16x32_bf16 v[0:3], v[172:175], v[212:215], v[0:3]
	v_mfma_f32_16x16x32_bf16 v[52:55], v[168:171], v[192:195], v[52:55]
	v_mfma_f32_16x16x32_bf16 v[48:51], v[176:179], v[192:195], v[48:51]
	v_mfma_f32_16x16x32_bf16 v[36:39], v[168:171], v[200:203], v[36:39]
	v_mfma_f32_16x16x32_bf16 v[32:35], v[176:179], v[200:203], v[32:35]
	v_mfma_f32_16x16x32_bf16 v[20:23], v[168:171], v[208:211], v[20:23]
	v_mfma_f32_16x16x32_bf16 v[16:19], v[176:179], v[208:211], v[16:19]
	v_mfma_f32_16x16x32_bf16 v[4:7], v[168:171], v[216:219], v[4:7]
	v_mfma_f32_16x16x32_bf16 v[0:3], v[176:179], v[216:219], v[0:3]
	s_barrier
	s_add_i32 s44, s44, 2
	s_addk_i32 s42, 0x100
	s_addk_i32 s43, 0x100
	v_add_u32_e32 v132, 0x100, v132
	s_cmp_gt_u32 s44, 13
	v_add_u32_e32 v134, 0x100, v134
	s_cbranch_scc0 .LBB0_468
	s_and_b64 vcc, exec, s[16:17]
	s_cbranch_vccz .LBB0_471
	s_barrier

.LBB0_523:
	ds_read_b128 v[148:151], v145
	ds_read_b128 v[152:155], v145 offset:1024
	ds_read_b128 v[156:159], v145 offset:2048
	ds_read_b128 v[160:163], v145 offset:3072
	ds_read_b128 v[164:167], v146
	ds_read_b128 v[168:171], v146 offset:1024
	ds_read_b128 v[172:175], v146 offset:2048
	ds_read_b128 v[176:179], v146 offset:3072
	s_cmp_eq_u32 s40, 12
	s_cselect_b32 s43, s0, s39
	s_cselect_b32 s42, s1, s38
	s_or_b32 s41, s43, 0x80
	v_mov_b32_e32 v135, v134
	ds_read_b128 v[180:183], v147
	ds_read_b128 v[192:195], v147 offset:1024
	ds_read_b128 v[196:199], v147 offset:2048
	ds_read_b128 v[200:203], v147 offset:3072
	ds_read_b128 v[204:207], v147 offset:4096
	ds_read_b128 v[208:211], v147 offset:5120
	ds_read_b128 v[212:215], v147 offset:6144
	ds_read_b128 v[216:219], v147 offset:7168
	s_add_i32 m0, s18, 0xc000
	s_nop 0
	global_load_lds_dwordx4 v135, s[8:9]
	v_mov_b32_e32 v135, v132
	s_add_i32 m0, s18, 0xe000
	s_nop 0
	global_load_lds_dwordx4 v135, s[8:9]
	s_waitcnt vmcnt(8)
	s_waitcnt lgkmcnt(0)
	s_barrier
	s_waitcnt lgkmcnt(0)
	v_mfma_f32_16x16x32_bf16 v[124:127], v[148:151], v[180:183], v[124:127]
	v_mfma_f32_16x16x32_bf16 v[120:123], v[156:159], v[180:183], v[120:123]
	v_mfma_f32_16x16x32_bf16 v[108:111], v[148:151], v[196:199], v[108:111]
	v_mfma_f32_16x16x32_bf16 v[104:107], v[156:159], v[196:199], v[104:107]
	v_mfma_f32_16x16x32_bf16 v[92:95], v[148:151], v[204:207], v[92:95]
	v_mfma_f32_16x16x32_bf16 v[88:91], v[156:159], v[204:207], v[88:91]
	v_mfma_f32_16x16x32_bf16 v[76:79], v[148:151], v[212:215], v[76:79]
	v_mfma_f32_16x16x32_bf16 v[72:75], v[156:159], v[212:215], v[72:75]
	v_mfma_f32_16x16x32_bf16 v[124:127], v[152:155], v[192:195], v[124:127]
	v_mfma_f32_16x16x32_bf16 v[120:123], v[160:163], v[192:195], v[120:123]
	v_mfma_f32_16x16x32_bf16 v[108:111], v[152:155], v[200:203], v[108:111]
	v_mfma_f32_16x16x32_bf16 v[104:107], v[160:163], v[200:203], v[104:107]
	v_mfma_f32_16x16x32_bf16 v[92:95], v[152:155], v[208:211], v[92:95]
	v_mfma_f32_16x16x32_bf16 v[88:91], v[160:163], v[208:211], v[88:91]
	v_mfma_f32_16x16x32_bf16 v[76:79], v[152:155], v[216:219], v[76:79]
	v_mfma_f32_16x16x32_bf16 v[72:75], v[160:163], v[216:219], v[72:75]
	v_mfma_f32_16x16x32_bf16 v[116:119], v[164:167], v[180:183], v[116:119]
	v_mfma_f32_16x16x32_bf16 v[112:115], v[172:175], v[180:183], v[112:115]
	v_mfma_f32_16x16x32_bf16 v[100:103], v[164:167], v[196:199], v[100:103]
	v_mfma_f32_16x16x32_bf16 v[96:99], v[172:175], v[196:199], v[96:99]
	v_mfma_f32_16x16x32_bf16 v[84:87], v[164:167], v[204:207], v[84:87]
	v_mfma_f32_16x16x32_bf16 v[80:83], v[172:175], v[204:207], v[80:83]
	v_mfma_f32_16x16x32_bf16 v[68:71], v[164:167], v[212:215], v[68:71]
	v_mfma_f32_16x16x32_bf16 v[64:67], v[172:175], v[212:215], v[64:67]
	v_mfma_f32_16x16x32_bf16 v[116:119], v[168:171], v[192:195], v[116:119]
	v_mfma_f32_16x16x32_bf16 v[112:115], v[176:179], v[192:195], v[112:115]
	v_mfma_f32_16x16x32_bf16 v[100:103], v[168:171], v[200:203], v[100:103]
	v_mfma_f32_16x16x32_bf16 v[96:99], v[176:179], v[200:203], v[96:99]
	v_mfma_f32_16x16x32_bf16 v[84:87], v[168:171], v[208:211], v[84:87]
	v_mfma_f32_16x16x32_bf16 v[80:83], v[176:179], v[208:211], v[80:83]
	v_mfma_f32_16x16x32_bf16 v[68:71], v[168:171], v[216:219], v[68:71]
	v_mfma_f32_16x16x32_bf16 v[64:67], v[176:179], v[216:219], v[64:67]
	s_barrier
	v_add_u32_e32 v135, s42, v137
	s_add_i32 s44, s30, s17
	ds_read_b128 v[180:183], v147 offset:16384
	ds_read_b128 v[192:195], v147 offset:17408
	ds_read_b128 v[196:199], v147 offset:18432
	ds_read_b128 v[200:203], v147 offset:19456
	ds_read_b128 v[204:207], v147 offset:20480
	ds_read_b128 v[208:211], v147 offset:21504
	ds_read_b128 v[212:215], v147 offset:22528
	ds_read_b128 v[216:219], v147 offset:23552
	s_mov_b32 m0, s44
	s_add_i32 s45, s31, s17
	global_load_lds_dwordx4 v135, s[10:11]
	v_add_u32_e32 v135, s42, v139
	s_add_i32 m0, s44, 0x2000
	s_add_i32 s44, s42, 0x40000
	global_load_lds_dwordx4 v135, s[10:11]
	v_add_u32_e32 v135, s44, v137
	s_mov_b32 m0, s45
	s_nop 0
	global_load_lds_dwordx4 v135, s[10:11]
	v_add_u32_e32 v135, s44, v139
	s_add_i32 m0, s45, 0x2000
	s_nop 0
	global_load_lds_dwordx4 v135, s[10:11]
	v_add_u32_e32 v135, s43, v136
	s_mov_b32 m0, s18
	s_nop 0
	global_load_lds_dwordx4 v135, s[8:9]
	v_add_u32_e32 v135, s43, v138
	s_mov_b32 m0, s19
	s_nop 0
	global_load_lds_dwordx4 v135, s[8:9]
	s_waitcnt vmcnt(8)
	s_waitcnt lgkmcnt(0)
	s_barrier
	s_waitcnt lgkmcnt(0)
	v_mfma_f32_16x16x32_bf16 v[60:63], v[148:151], v[180:183], v[60:63]
	v_mfma_f32_16x16x32_bf16 v[56:59], v[156:159], v[180:183], v[56:59]
	v_mfma_f32_16x16x32_bf16 v[44:47], v[148:151], v[196:199], v[44:47]
	v_mfma_f32_16x16x32_bf16 v[40:43], v[156:159], v[196:199], v[40:43]
	v_mfma_f32_16x16x32_bf16 v[28:31], v[148:151], v[204:207], v[28:31]
	v_mfma_f32_16x16x32_bf16 v[24:27], v[156:159], v[204:207], v[24:27]
	v_mfma_f32_16x16x32_bf16 v[12:15], v[148:151], v[212:215], v[12:15]
	v_mfma_f32_16x16x32_bf16 v[8:11], v[156:159], v[212:215], v[8:11]
	v_mfma_f32_16x16x32_bf16 v[60:63], v[152:155], v[192:195], v[60:63]
	v_mfma_f32_16x16x32_bf16 v[56:59], v[160:163], v[192:195], v[56:59]
	v_mfma_f32_16x16x32_bf16 v[44:47], v[152:155], v[200:203], v[44:47]
	v_mfma_f32_16x16x32_bf16 v[40:43], v[160:163], v[200:203], v[40:43]
	v_mfma_f32_16x16x32_bf16 v[28:31], v[152:155], v[208:211], v[28:31]
	v_mfma_f32_16x16x32_bf16 v[24:27], v[160:163], v[208:211], v[24:27]
	v_mfma_f32_16x16x32_bf16 v[12:15], v[152:155], v[216:219], v[12:15]
	v_mfma_f32_16x16x32_bf16 v[8:11], v[160:163], v[216:219], v[8:11]
	v_mfma_f32_16x16x32_bf16 v[52:55], v[164:167], v[180:183], v[52:55]
	v_mfma_f32_16x16x32_bf16 v[48:51], v[172:175], v[180:183], v[48:51]
	v_mfma_f32_16x16x32_bf16 v[36:39], v[164:167], v[196:199], v[36:39]
	v_mfma_f32_16x16x32_bf16 v[32:35], v[172:175], v[196:199], v[32:35]
	v_mfma_f32_16x16x32_bf16 v[20:23], v[164:167], v[204:207], v[20:23]
	v_mfma_f32_16x16x32_bf16 v[16:19], v[172:175], v[204:207], v[16:19]
	v_mfma_f32_16x16x32_bf16 v[4:7], v[164:167], v[212:215], v[4:7]
	v_mfma_f32_16x16x32_bf16 v[0:3], v[172:175], v[212:215], v[0:3]
	v_mfma_f32_16x16x32_bf16 v[52:55], v[168:171], v[192:195], v[52:55]
	v_mfma_f32_16x16x32_bf16 v[48:51], v[176:179], v[192:195], v[48:51]
	v_mfma_f32_16x16x32_bf16 v[36:39], v[168:171], v[200:203], v[36:39]
	v_mfma_f32_16x16x32_bf16 v[32:35], v[176:179], v[200:203], v[32:35]
	v_mfma_f32_16x16x32_bf16 v[20:23], v[168:171], v[208:211], v[20:23]
	v_mfma_f32_16x16x32_bf16 v[16:19], v[176:179], v[208:211], v[16:19]
	v_mfma_f32_16x16x32_bf16 v[4:7], v[168:171], v[216:219], v[4:7]
	v_mfma_f32_16x16x32_bf16 v[0:3], v[176:179], v[216:219], v[0:3]
	s_barrier
; #define PG8_BAR __builtin_amdgcn_s_barrier()
;     ...
;         if constexpr (Epi::MIDHOOK) {
;             for (int t = 0; t < 4; t += 2) PG8_ITER(t);
;             E.mid(acc, cur, wr, wc, fr, fq);
;             for (int t = 4; t < nt; t += 2) PG8_ITER(t);
;         } else {
;             for (int t = 0; t < nt; t += 2) PG8_ITER(t);
;         }
;     ...
;         if constexpr (ALIGN_EPI) { if (wr == 0) PG8_BAR; }
	s_add_i32 s44, 0, 0x18000
	v_add_u32_e32 v135, s44, v141
	s_add_i32 s45, 0, 0x1c000
	ds_read_b128 v[148:151], v135
	ds_read_b128 v[152:155], v135 offset:1024
	ds_read_b128 v[156:159], v135 offset:2048
	ds_read_b128 v[160:163], v135 offset:3072
	v_add_u32_e32 v135, s45, v141
	ds_read_b128 v[164:167], v135
	ds_read_b128 v[168:171], v135 offset:1024
	ds_read_b128 v[172:175], v135 offset:2048
	ds_read_b128 v[176:179], v135 offset:3072
	s_add_i32 s43, s43, 0x40000
	v_add_u32_e32 v135, s43, v136
	s_mov_b32 m0, s20
	ds_read_b128 v[180:183], v147 offset:32768
	ds_read_b128 v[192:195], v147 offset:33792
	ds_read_b128 v[196:199], v147 offset:34816
	ds_read_b128 v[200:203], v147 offset:35840
	ds_read_b128 v[204:207], v147 offset:36864
	ds_read_b128 v[208:211], v147 offset:37888
	ds_read_b128 v[212:215], v147 offset:38912
	ds_read_b128 v[216:219], v147 offset:39936
	s_nop 0
	global_load_lds_dwordx4 v135, s[8:9]
	v_add_u32_e32 v135, s43, v138
	s_mov_b32 m0, s21
	s_nop 0
	global_load_lds_dwordx4 v135, s[8:9]
	s_waitcnt vmcnt(8)
	s_waitcnt lgkmcnt(0)
	s_barrier
	s_waitcnt lgkmcnt(0)
	v_mfma_f32_16x16x32_bf16 v[124:127], v[148:151], v[180:183], v[124:127]
	v_mfma_f32_16x16x32_bf16 v[120:123], v[156:159], v[180:183], v[120:123]
	v_mfma_f32_16x16x32_bf16 v[108:111], v[148:151], v[196:199], v[108:111]
	v_mfma_f32_16x16x32_bf16 v[104:107], v[156:159], v[196:199], v[104:107]
	v_mfma_f32_16x16x32_bf16 v[92:95], v[148:151], v[204:207], v[92:95]
	v_mfma_f32_16x16x32_bf16 v[88:91], v[156:159], v[204:207], v[88:91]
	v_mfma_f32_16x16x32_bf16 v[76:79], v[148:151], v[212:215], v[76:79]
	v_mfma_f32_16x16x32_bf16 v[72:75], v[156:159], v[212:215], v[72:75]
	v_mfma_f32_16x16x32_bf16 v[124:127], v[152:155], v[192:195], v[124:127]
	v_mfma_f32_16x16x32_bf16 v[120:123], v[160:163], v[192:195], v[120:123]
	v_mfma_f32_16x16x32_bf16 v[108:111], v[152:155], v[200:203], v[108:111]
	v_mfma_f32_16x16x32_bf16 v[104:107], v[160:163], v[200:203], v[104:107]
	v_mfma_f32_16x16x32_bf16 v[92:95], v[152:155], v[208:211], v[92:95]
	v_mfma_f32_16x16x32_bf16 v[88:91], v[160:163], v[208:211], v[88:91]
	v_mfma_f32_16x16x32_bf16 v[76:79], v[152:155], v[216:219], v[76:79]
	v_mfma_f32_16x16x32_bf16 v[72:75], v[160:163], v[216:219], v[72:75]
	v_mfma_f32_16x16x32_bf16 v[116:119], v[164:167], v[180:183], v[116:119]
	v_mfma_f32_16x16x32_bf16 v[112:115], v[172:175], v[180:183], v[112:115]
	v_mfma_f32_16x16x32_bf16 v[100:103], v[164:167], v[196:199], v[100:103]
	v_mfma_f32_16x16x32_bf16 v[96:99], v[172:175], v[196:199], v[96:99]
	v_mfma_f32_16x16x32_bf16 v[84:87], v[164:167], v[204:207], v[84:87]
	v_mfma_f32_16x16x32_bf16 v[80:83], v[172:175], v[204:207], v[80:83]
	v_mfma_f32_16x16x32_bf16 v[68:71], v[164:167], v[212:215], v[68:71]
	v_mfma_f32_16x16x32_bf16 v[64:67], v[172:175], v[212:215], v[64:67]
	v_mfma_f32_16x16x32_bf16 v[116:119], v[168:171], v[192:195], v[116:119]
	v_mfma_f32_16x16x32_bf16 v[112:115], v[176:179], v[192:195], v[112:115]
	v_mfma_f32_16x16x32_bf16 v[100:103], v[168:171], v[200:203], v[100:103]
	v_mfma_f32_16x16x32_bf16 v[96:99], v[176:179], v[200:203], v[96:99]
	v_mfma_f32_16x16x32_bf16 v[84:87], v[168:171], v[208:211], v[84:87]
	v_mfma_f32_16x16x32_bf16 v[80:83], v[176:179], v[208:211], v[80:83]
	v_mfma_f32_16x16x32_bf16 v[68:71], v[168:171], v[216:219], v[68:71]
	v_mfma_f32_16x16x32_bf16 v[64:67], v[176:179], v[216:219], v[64:67]
	s_barrier
	s_or_b32 s43, s42, 0x80
	v_add_u32_e32 v135, s43, v137
	s_add_i32 s44, s44, s17
	ds_read_b128 v[180:183], v147 offset:49152
	ds_read_b128 v[192:195], v147 offset:50176
	ds_read_b128 v[196:199], v147 offset:51200
	ds_read_b128 v[200:203], v147 offset:52224
	ds_read_b128 v[204:207], v147 offset:53248
	ds_read_b128 v[208:211], v147 offset:54272
	ds_read_b128 v[212:215], v147 offset:55296
	ds_read_b128 v[216:219], v147 offset:56320
	s_mov_b32 m0, s44
	s_add_i32 s42, s42, 0x40080
	global_load_lds_dwordx4 v135, s[10:11]
	v_add_u32_e32 v135, s43, v139
	s_add_i32 m0, s44, 0x2000
	s_add_i32 s43, s45, s17
	global_load_lds_dwordx4 v135, s[10:11]
	v_add_u32_e32 v135, s42, v137
	s_mov_b32 m0, s43
	s_nop 0
	global_load_lds_dwordx4 v135, s[10:11]
	v_add_u32_e32 v135, s42, v139
	s_add_i32 m0, s43, 0x2000
	s_nop 0
	global_load_lds_dwordx4 v135, s[10:11]
	v_add_u32_e32 v135, s41, v136
	s_mov_b32 m0, s26
	s_nop 0
	global_load_lds_dwordx4 v135, s[8:9]
	v_add_u32_e32 v135, s41, v138
	s_mov_b32 m0, s27
	s_nop 0
	global_load_lds_dwordx4 v135, s[8:9]
	s_waitcnt vmcnt(8)
	s_waitcnt lgkmcnt(0)
	s_barrier
	s_waitcnt lgkmcnt(0)
	v_mfma_f32_16x16x32_bf16 v[60:63], v[148:151], v[180:183], v[60:63]
	v_mfma_f32_16x16x32_bf16 v[56:59], v[156:159], v[180:183], v[56:59]
	v_mfma_f32_16x16x32_bf16 v[44:47], v[148:151], v[196:199], v[44:47]
	v_mfma_f32_16x16x32_bf16 v[40:43], v[156:159], v[196:199], v[40:43]
	v_mfma_f32_16x16x32_bf16 v[28:31], v[148:151], v[204:207], v[28:31]
	v_mfma_f32_16x16x32_bf16 v[24:27], v[156:159], v[204:207], v[24:27]
	v_mfma_f32_16x16x32_bf16 v[12:15], v[148:151], v[212:215], v[12:15]
	v_mfma_f32_16x16x32_bf16 v[8:11], v[156:159], v[212:215], v[8:11]
	v_mfma_f32_16x16x32_bf16 v[60:63], v[152:155], v[192:195], v[60:63]
	v_mfma_f32_16x16x32_bf16 v[56:59], v[160:163], v[192:195], v[56:59]
	v_mfma_f32_16x16x32_bf16 v[44:47], v[152:155], v[200:203], v[44:47]
	v_mfma_f32_16x16x32_bf16 v[40:43], v[160:163], v[200:203], v[40:43]
	v_mfma_f32_16x16x32_bf16 v[28:31], v[152:155], v[208:211], v[28:31]
	v_mfma_f32_16x16x32_bf16 v[24:27], v[160:163], v[208:211], v[24:27]
	v_mfma_f32_16x16x32_bf16 v[12:15], v[152:155], v[216:219], v[12:15]
	v_mfma_f32_16x16x32_bf16 v[8:11], v[160:163], v[216:219], v[8:11]
	v_mfma_f32_16x16x32_bf16 v[52:55], v[164:167], v[180:183], v[52:55]
	v_mfma_f32_16x16x32_bf16 v[48:51], v[172:175], v[180:183], v[48:51]
	v_mfma_f32_16x16x32_bf16 v[36:39], v[164:167], v[196:199], v[36:39]
	v_mfma_f32_16x16x32_bf16 v[32:35], v[172:175], v[196:199], v[32:35]
	v_mfma_f32_16x16x32_bf16 v[20:23], v[164:167], v[204:207], v[20:23]
	v_mfma_f32_16x16x32_bf16 v[16:19], v[172:175], v[204:207], v[16:19]
	v_mfma_f32_16x16x32_bf16 v[4:7], v[164:167], v[212:215], v[4:7]
	v_mfma_f32_16x16x32_bf16 v[0:3], v[172:175], v[212:215], v[0:3]
	v_mfma_f32_16x16x32_bf16 v[52:55], v[168:171], v[192:195], v[52:55]
	v_mfma_f32_16x16x32_bf16 v[48:51], v[176:179], v[192:195], v[48:51]
	v_mfma_f32_16x16x32_bf16 v[36:39], v[168:171], v[200:203], v[36:39]
	v_mfma_f32_16x16x32_bf16 v[32:35], v[176:179], v[200:203], v[32:35]
	v_mfma_f32_16x16x32_bf16 v[20:23], v[168:171], v[208:211], v[20:23]
	v_mfma_f32_16x16x32_bf16 v[16:19], v[176:179], v[208:211], v[16:19]
	v_mfma_f32_16x16x32_bf16 v[4:7], v[168:171], v[216:219], v[4:7]
	v_mfma_f32_16x16x32_bf16 v[0:3], v[176:179], v[216:219], v[0:3]
	s_barrier
	s_add_i32 s40, s40, 2
	s_addk_i32 s38, 0x100
	s_addk_i32 s39, 0x100
	v_add_u32_e32 v132, 0x100, v132
	s_cmp_gt_u32 s40, 13
	v_add_u32_e32 v134, 0x100, v134
	s_cbranch_scc0 .LBB0_523
	s_and_b64 vcc, exec, s[14:15]
	s_cbranch_vccz .LBB0_526
	s_barrier

;     ...
;         if constexpr (Epi::MIDHOOK) {
;             for (int t = 0; t < 4; t += 2) PG8_ITER(t);
.LBB0_598:
	ds_read_b128 v[0:3], v195
	ds_read_b128 v[4:7], v195 offset:1024
	ds_read_b128 v[8:11], v195 offset:2048
	ds_read_b128 v[12:15], v195 offset:3072
	ds_read_b128 v[16:19], v196
	ds_read_b128 v[20:23], v196 offset:1024
	ds_read_b128 v[24:27], v196 offset:2048
	ds_read_b128 v[28:31], v196 offset:3072
	s_mul_i32 s37, s36, 0x2a0000
	s_mul_i32 s38, s35, 0xa0000
	s_add_i32 s1, s44, 0x150880
	s_or_b32 s45, s44, 0x900
	s_or_b32 s51, s44, 0x980
	s_or_b32 s40, s43, 0x100
	v_add_u32_e32 v64, s1, v180
	s_add_i32 s0, s23, 0xc000
	ds_read_b128 v[32:35], v191
	ds_read_b128 v[36:39], v191 offset:1024
	ds_read_b128 v[40:43], v191 offset:2048
	ds_read_b128 v[44:47], v191 offset:3072
	ds_read_b128 v[48:51], v191 offset:4096
	ds_read_b128 v[52:55], v191 offset:5120
	ds_read_b128 v[56:59], v191 offset:6144
	ds_read_b128 v[60:63], v191 offset:7168
	s_mov_b32 m0, s0
	s_nop 0
	global_load_lds_dwordx4 v64, s[12:13]
	v_add_u32_e32 v64, s1, v182
	s_add_i32 s1, s23, 0xe000
	s_mov_b32 m0, s1
	s_nop 0
	global_load_lds_dwordx4 v64, s[12:13]
	s_waitcnt vmcnt(8)
	s_waitcnt lgkmcnt(0)
	s_barrier
	s_waitcnt lgkmcnt(0)
	v_mfma_f32_16x16x32_bf16 v[64:67], v[0:3], v[32:35], 0
	v_mfma_f32_16x16x32_bf16 v[68:71], v[8:11], v[32:35], 0
	v_mfma_f32_16x16x32_bf16 v[72:75], v[0:3], v[40:43], 0
	v_mfma_f32_16x16x32_bf16 v[76:79], v[8:11], v[40:43], 0
	v_mfma_f32_16x16x32_bf16 v[80:83], v[0:3], v[48:51], 0
	v_mfma_f32_16x16x32_bf16 v[84:87], v[8:11], v[48:51], 0
	v_mfma_f32_16x16x32_bf16 v[88:91], v[0:3], v[56:59], 0
	v_mfma_f32_16x16x32_bf16 v[92:95], v[8:11], v[56:59], 0
	v_mfma_f32_16x16x32_bf16 v[64:67], v[4:7], v[36:39], v[64:67]
	v_mfma_f32_16x16x32_bf16 v[68:71], v[12:15], v[36:39], v[68:71]
	v_mfma_f32_16x16x32_bf16 v[72:75], v[4:7], v[44:47], v[72:75]
	v_mfma_f32_16x16x32_bf16 v[76:79], v[12:15], v[44:47], v[76:79]
	v_mfma_f32_16x16x32_bf16 v[80:83], v[4:7], v[52:55], v[80:83]
	v_mfma_f32_16x16x32_bf16 v[84:87], v[12:15], v[52:55], v[84:87]
	v_mfma_f32_16x16x32_bf16 v[88:91], v[4:7], v[60:63], v[88:91]
	v_mfma_f32_16x16x32_bf16 v[92:95], v[12:15], v[60:63], v[92:95]
	v_mfma_f32_16x16x32_bf16 v[96:99], v[16:19], v[32:35], 0
	v_mfma_f32_16x16x32_bf16 v[32:35], v[24:27], v[32:35], 0
	v_mfma_f32_16x16x32_bf16 v[96:99], v[20:23], v[36:39], v[96:99]
	v_mfma_f32_16x16x32_bf16 v[32:35], v[28:31], v[36:39], v[32:35]
	v_mfma_f32_16x16x32_bf16 v[36:39], v[16:19], v[40:43], 0
	v_mfma_f32_16x16x32_bf16 v[40:43], v[24:27], v[40:43], 0
	v_mfma_f32_16x16x32_bf16 v[36:39], v[20:23], v[44:47], v[36:39]
	v_mfma_f32_16x16x32_bf16 v[40:43], v[28:31], v[44:47], v[40:43]
	v_mfma_f32_16x16x32_bf16 v[44:47], v[16:19], v[48:51], 0
	v_mfma_f32_16x16x32_bf16 v[48:51], v[24:27], v[48:51], 0
	v_mfma_f32_16x16x32_bf16 v[44:47], v[20:23], v[52:55], v[44:47]
	v_mfma_f32_16x16x32_bf16 v[48:51], v[28:31], v[52:55], v[48:51]
	v_mfma_f32_16x16x32_bf16 v[52:55], v[16:19], v[56:59], 0
	v_mfma_f32_16x16x32_bf16 v[56:59], v[24:27], v[56:59], 0
	v_mfma_f32_16x16x32_bf16 v[52:55], v[20:23], v[60:63], v[52:55]
	v_mfma_f32_16x16x32_bf16 v[56:59], v[28:31], v[60:63], v[56:59]
	s_barrier
	v_add_u32_e32 v128, s40, v181
	s_add_i32 s39, s33, s3
	ds_read_b128 v[60:63], v191 offset:16384
	ds_read_b128 v[100:103], v191 offset:17408
	ds_read_b128 v[104:107], v191 offset:18432
	ds_read_b128 v[108:111], v191 offset:19456
	ds_read_b128 v[112:115], v191 offset:20480
	ds_read_b128 v[116:119], v191 offset:21504
	ds_read_b128 v[120:123], v191 offset:22528
	ds_read_b128 v[124:127], v191 offset:23552
	s_mov_b32 m0, s39
	s_add_i32 s42, s43, 0x50100
	global_load_lds_dwordx4 v128, s[14:15]
	v_add_u32_e32 v128, s40, v183
	s_add_i32 s40, s39, 0x2000
	s_mov_b32 m0, s40
	s_add_i32 s41, s34, s3
	global_load_lds_dwordx4 v128, s[14:15]
	v_add_u32_e32 v128, s42, v181
	s_mov_b32 m0, s41
	s_nop 0
	global_load_lds_dwordx4 v128, s[14:15]
	v_add_u32_e32 v128, s42, v183
	s_add_i32 s42, s41, 0x2000
	s_mov_b32 m0, s42
	s_nop 0
	global_load_lds_dwordx4 v128, s[14:15]
	v_add_u32_e32 v128, s45, v180
	s_mov_b32 m0, s23
	s_nop 0
	global_load_lds_dwordx4 v128, s[12:13]
	v_add_u32_e32 v128, s45, v182
	s_mov_b32 m0, s24
	s_nop 0
	global_load_lds_dwordx4 v128, s[12:13]
	s_waitcnt vmcnt(8)
	s_waitcnt lgkmcnt(0)
	s_barrier
	s_waitcnt lgkmcnt(0)
	v_mfma_f32_16x16x32_bf16 v[128:131], v[0:3], v[60:63], 0
	v_mfma_f32_16x16x32_bf16 v[136:139], v[0:3], v[104:107], 0
	v_mfma_f32_16x16x32_bf16 v[144:147], v[0:3], v[112:115], 0
	v_mfma_f32_16x16x32_bf16 v[0:3], v[0:3], v[120:123], 0
	v_mfma_f32_16x16x32_bf16 v[128:131], v[4:7], v[100:103], v[128:131]
	v_mfma_f32_16x16x32_bf16 v[136:139], v[4:7], v[108:111], v[136:139]
	v_mfma_f32_16x16x32_bf16 v[144:147], v[4:7], v[116:119], v[144:147]
	v_mfma_f32_16x16x32_bf16 v[0:3], v[4:7], v[124:127], v[0:3]
	v_mfma_f32_16x16x32_bf16 v[4:7], v[8:11], v[120:123], 0
	v_mfma_f32_16x16x32_bf16 v[132:135], v[8:11], v[60:63], 0
	v_mfma_f32_16x16x32_bf16 v[140:143], v[8:11], v[104:107], 0
	v_mfma_f32_16x16x32_bf16 v[148:151], v[8:11], v[112:115], 0
	v_mfma_f32_16x16x32_bf16 v[4:7], v[12:15], v[124:127], v[4:7]
	v_mfma_f32_16x16x32_bf16 v[132:135], v[12:15], v[100:103], v[132:135]
	v_mfma_f32_16x16x32_bf16 v[140:143], v[12:15], v[108:111], v[140:143]
	v_mfma_f32_16x16x32_bf16 v[148:151], v[12:15], v[116:119], v[148:151]
	v_mfma_f32_16x16x32_bf16 v[8:11], v[16:19], v[60:63], 0
	v_mfma_f32_16x16x32_bf16 v[12:15], v[24:27], v[60:63], 0
	v_mfma_f32_16x16x32_bf16 v[8:11], v[20:23], v[100:103], v[8:11]
	v_mfma_f32_16x16x32_bf16 v[12:15], v[28:31], v[100:103], v[12:15]
	v_mfma_f32_16x16x32_bf16 v[60:63], v[16:19], v[104:107], 0
	v_mfma_f32_16x16x32_bf16 v[100:103], v[24:27], v[104:107], 0
	v_mfma_f32_16x16x32_bf16 v[104:107], v[16:19], v[112:115], 0
	v_mfma_f32_16x16x32_bf16 v[16:19], v[16:19], v[120:123], 0
	v_mfma_f32_16x16x32_bf16 v[60:63], v[20:23], v[108:111], v[60:63]
	v_mfma_f32_16x16x32_bf16 v[100:103], v[28:31], v[108:111], v[100:103]
	v_mfma_f32_16x16x32_bf16 v[104:107], v[20:23], v[116:119], v[104:107]
	v_mfma_f32_16x16x32_bf16 v[108:111], v[24:27], v[112:115], 0
	v_mfma_f32_16x16x32_bf16 v[16:19], v[20:23], v[124:127], v[16:19]
	v_mfma_f32_16x16x32_bf16 v[20:23], v[24:27], v[120:123], 0
	v_mfma_f32_16x16x32_bf16 v[108:111], v[28:31], v[116:119], v[108:111]
	v_mfma_f32_16x16x32_bf16 v[20:23], v[28:31], v[124:127], v[20:23]
	s_barrier
;     ...
;         if constexpr (Epi::MIDHOOK) {
;             for (int t = 0; t < 4; t += 2) PG8_ITER(t);
	s_add_i32 s45, 0, 0x18000
	s_add_i32 s47, 0, 0x1c000
	v_add_u32_e32 v167, s45, v185
	v_add_u32_e32 v169, s47, v185
	ds_read_b128 v[24:27], v167
	ds_read_b128 v[28:31], v167 offset:1024
	ds_read_b128 v[112:115], v167 offset:2048
	ds_read_b128 v[116:119], v167 offset:3072
	ds_read_b128 v[120:123], v169
	ds_read_b128 v[124:127], v169 offset:1024
	ds_read_b128 v[152:155], v169 offset:2048
	ds_read_b128 v[156:159], v169 offset:3072
	s_add_i32 s46, s44, 0x150900
	v_add_u32_e32 v160, s46, v180
	s_mov_b32 m0, s25
	ds_read_b128 v[170:173], v191 offset:32768
	ds_read_b128 v[174:177], v191 offset:33792
	ds_read_b128 v[198:201], v191 offset:34816
	ds_read_b128 v[202:205], v191 offset:35840
	ds_read_b128 v[206:209], v191 offset:36864
	ds_read_b128 v[210:213], v191 offset:37888
	ds_read_b128 v[214:217], v191 offset:38912
	ds_read_b128 v[218:221], v191 offset:39936
	s_nop 0
	global_load_lds_dwordx4 v160, s[12:13]
	v_add_u32_e32 v160, s46, v182
	s_mov_b32 m0, s26
	s_nop 0
	global_load_lds_dwordx4 v160, s[12:13]
	s_waitcnt vmcnt(8)
	s_waitcnt lgkmcnt(0)
	s_barrier
	s_waitcnt lgkmcnt(0)
	v_mfma_f32_16x16x32_bf16 v[64:67], v[24:27], v[170:173], v[64:67]
	v_mfma_f32_16x16x32_bf16 v[68:71], v[112:115], v[170:173], v[68:71]
	v_mfma_f32_16x16x32_bf16 v[72:75], v[24:27], v[198:201], v[72:75]
	v_mfma_f32_16x16x32_bf16 v[76:79], v[112:115], v[198:201], v[76:79]
	v_mfma_f32_16x16x32_bf16 v[80:83], v[24:27], v[206:209], v[80:83]
	v_mfma_f32_16x16x32_bf16 v[84:87], v[112:115], v[206:209], v[84:87]
	v_mfma_f32_16x16x32_bf16 v[88:91], v[24:27], v[214:217], v[88:91]
	v_mfma_f32_16x16x32_bf16 v[92:95], v[112:115], v[214:217], v[92:95]
	v_mfma_f32_16x16x32_bf16 v[64:67], v[28:31], v[174:177], v[64:67]
	v_mfma_f32_16x16x32_bf16 v[68:71], v[116:119], v[174:177], v[68:71]
	v_mfma_f32_16x16x32_bf16 v[72:75], v[28:31], v[202:205], v[72:75]
	v_mfma_f32_16x16x32_bf16 v[76:79], v[116:119], v[202:205], v[76:79]
	v_mfma_f32_16x16x32_bf16 v[80:83], v[28:31], v[210:213], v[80:83]
	v_mfma_f32_16x16x32_bf16 v[84:87], v[116:119], v[210:213], v[84:87]
	v_mfma_f32_16x16x32_bf16 v[88:91], v[28:31], v[218:221], v[88:91]
	v_mfma_f32_16x16x32_bf16 v[92:95], v[116:119], v[218:221], v[92:95]
	v_mfma_f32_16x16x32_bf16 v[96:99], v[120:123], v[170:173], v[96:99]
	v_mfma_f32_16x16x32_bf16 v[32:35], v[152:155], v[170:173], v[32:35]
	v_mfma_f32_16x16x32_bf16 v[40:43], v[152:155], v[198:201], v[40:43]
	v_mfma_f32_16x16x32_bf16 v[44:47], v[120:123], v[206:209], v[44:47]
	v_mfma_f32_16x16x32_bf16 v[48:51], v[152:155], v[206:209], v[48:51]
	v_mfma_f32_16x16x32_bf16 v[52:55], v[120:123], v[214:217], v[52:55]
	v_mfma_f32_16x16x32_bf16 v[56:59], v[152:155], v[214:217], v[56:59]
	v_mfma_f32_16x16x32_bf16 v[96:99], v[124:127], v[174:177], v[96:99]
	v_mfma_f32_16x16x32_bf16 v[32:35], v[156:159], v[174:177], v[32:35]
	v_mfma_f32_16x16x32_bf16 v[36:39], v[120:123], v[198:201], v[36:39]
	v_mfma_f32_16x16x32_bf16 v[40:43], v[156:159], v[202:205], v[40:43]
	v_mfma_f32_16x16x32_bf16 v[44:47], v[124:127], v[210:213], v[44:47]
	v_mfma_f32_16x16x32_bf16 v[48:51], v[156:159], v[210:213], v[48:51]
	v_mfma_f32_16x16x32_bf16 v[52:55], v[124:127], v[218:221], v[52:55]
	v_mfma_f32_16x16x32_bf16 v[56:59], v[156:159], v[218:221], v[56:59]
	v_mfma_f32_16x16x32_bf16 v[36:39], v[124:127], v[202:205], v[36:39]
	s_barrier
	s_or_b32 s46, s43, 0x180
	v_add_u32_e32 v160, s46, v181
	s_add_i32 s45, s45, s3
	ds_read_b128 v[170:173], v191 offset:49152
	ds_read_b128 v[174:177], v191 offset:50176
	ds_read_b128 v[198:201], v191 offset:51200
	ds_read_b128 v[202:205], v191 offset:52224
	ds_read_b128 v[206:209], v191 offset:53248
	ds_read_b128 v[210:213], v191 offset:54272
	ds_read_b128 v[214:217], v191 offset:55296
	ds_read_b128 v[218:221], v191 offset:56320
	s_mov_b32 m0, s45
	s_add_i32 s48, s43, 0x50180
	global_load_lds_dwordx4 v160, s[14:15]
	v_add_u32_e32 v160, s46, v183
	s_add_i32 s46, s45, 0x2000
	s_mov_b32 m0, s46
	s_add_i32 s47, s47, s3
	global_load_lds_dwordx4 v160, s[14:15]
	v_add_u32_e32 v160, s48, v181
	s_mov_b32 m0, s47
	s_nop 0
	global_load_lds_dwordx4 v160, s[14:15]
	v_add_u32_e32 v160, s48, v183
	s_add_i32 s48, s47, 0x2000
	s_mov_b32 m0, s48
	s_nop 0
	global_load_lds_dwordx4 v160, s[14:15]
	v_add_u32_e32 v160, s51, v180
	s_mov_b32 m0, s28
	s_nop 0
	global_load_lds_dwordx4 v160, s[12:13]
	v_add_u32_e32 v160, s51, v182
	s_mov_b32 m0, s29
	s_nop 0
	global_load_lds_dwordx4 v160, s[12:13]
	s_waitcnt vmcnt(8)
	s_waitcnt lgkmcnt(0)
	s_barrier
	s_waitcnt lgkmcnt(0)
	v_mfma_f32_16x16x32_bf16 v[128:131], v[24:27], v[170:173], v[128:131]
	v_mfma_f32_16x16x32_bf16 v[136:139], v[24:27], v[198:201], v[136:139]
	v_mfma_f32_16x16x32_bf16 v[0:3], v[24:27], v[214:217], v[0:3]
	v_mfma_f32_16x16x32_bf16 v[4:7], v[112:115], v[214:217], v[4:7]
	v_mfma_f32_16x16x32_bf16 v[128:131], v[28:31], v[174:177], v[128:131]
	v_mfma_f32_16x16x32_bf16 v[132:135], v[112:115], v[170:173], v[132:135]
	v_mfma_f32_16x16x32_bf16 v[136:139], v[28:31], v[202:205], v[136:139]
	v_mfma_f32_16x16x32_bf16 v[140:143], v[112:115], v[198:201], v[140:143]
	v_mfma_f32_16x16x32_bf16 v[144:147], v[24:27], v[206:209], v[144:147]
	v_mfma_f32_16x16x32_bf16 v[148:151], v[112:115], v[206:209], v[148:151]
	v_mfma_f32_16x16x32_bf16 v[0:3], v[28:31], v[218:221], v[0:3]
	v_mfma_f32_16x16x32_bf16 v[4:7], v[116:119], v[218:221], v[4:7]
	v_mfma_f32_16x16x32_bf16 v[132:135], v[116:119], v[174:177], v[132:135]
	v_mfma_f32_16x16x32_bf16 v[140:143], v[116:119], v[202:205], v[140:143]
	v_mfma_f32_16x16x32_bf16 v[144:147], v[28:31], v[210:213], v[144:147]
	v_mfma_f32_16x16x32_bf16 v[148:151], v[116:119], v[210:213], v[148:151]
	v_mfma_f32_16x16x32_bf16 v[8:11], v[120:123], v[170:173], v[8:11]
	v_mfma_f32_16x16x32_bf16 v[12:15], v[152:155], v[170:173], v[12:15]
	v_mfma_f32_16x16x32_bf16 v[24:27], v[120:123], v[198:201], v[60:63]
	v_mfma_f32_16x16x32_bf16 v[28:31], v[152:155], v[198:201], v[100:103]
	v_mfma_f32_16x16x32_bf16 v[60:63], v[120:123], v[206:209], v[104:107]
	v_mfma_f32_16x16x32_bf16 v[100:103], v[152:155], v[206:209], v[108:111]
	v_mfma_f32_16x16x32_bf16 v[16:19], v[120:123], v[214:217], v[16:19]
	v_mfma_f32_16x16x32_bf16 v[20:23], v[152:155], v[214:217], v[20:23]
	v_mfma_f32_16x16x32_bf16 v[8:11], v[124:127], v[174:177], v[8:11]
	v_mfma_f32_16x16x32_bf16 v[12:15], v[156:159], v[174:177], v[12:15]
	v_mfma_f32_16x16x32_bf16 v[24:27], v[124:127], v[202:205], v[24:27]
	v_mfma_f32_16x16x32_bf16 v[28:31], v[156:159], v[202:205], v[28:31]
	v_mfma_f32_16x16x32_bf16 v[60:63], v[124:127], v[210:213], v[60:63]
	v_mfma_f32_16x16x32_bf16 v[100:103], v[156:159], v[210:213], v[100:103]
	v_mfma_f32_16x16x32_bf16 v[16:19], v[124:127], v[218:221], v[16:19]
	v_mfma_f32_16x16x32_bf16 v[20:23], v[156:159], v[218:221], v[20:23]
	s_barrier
;     ...
;         if constexpr (Epi::MIDHOOK) {
;             for (int t = 0; t < 4; t += 2) PG8_ITER(t);
	ds_read_b128 v[104:107], v195
	ds_read_b128 v[108:111], v195 offset:1024
	ds_read_b128 v[112:115], v195 offset:2048
	ds_read_b128 v[116:119], v195 offset:3072
	ds_read_b128 v[120:123], v196
	ds_read_b128 v[124:127], v196 offset:1024
	ds_read_b128 v[152:155], v196 offset:2048
	ds_read_b128 v[156:159], v196 offset:3072
	s_or_b32 s51, s44, 0x80
	s_or_b32 s52, s43, 0x200
	s_add_i32 s53, s44, 0x150980
	v_add_u32_e32 v160, s53, v180
	s_mov_b32 m0, s0
	ds_read_b128 v[170:173], v191
	ds_read_b128 v[174:177], v191 offset:1024
	ds_read_b128 v[198:201], v191 offset:2048
	ds_read_b128 v[202:205], v191 offset:3072
	ds_read_b128 v[206:209], v191 offset:4096
	ds_read_b128 v[210:213], v191 offset:5120
	ds_read_b128 v[214:217], v191 offset:6144
	ds_read_b128 v[218:221], v191 offset:7168
	s_nop 0
	global_load_lds_dwordx4 v160, s[12:13]
	v_add_u32_e32 v160, s53, v182
	s_mov_b32 m0, s1
	s_nop 0
	global_load_lds_dwordx4 v160, s[12:13]
	s_waitcnt vmcnt(8)
	s_waitcnt lgkmcnt(0)
	s_barrier
	s_waitcnt lgkmcnt(0)
	v_mfma_f32_16x16x32_bf16 v[64:67], v[104:107], v[170:173], v[64:67]
	v_mfma_f32_16x16x32_bf16 v[68:71], v[112:115], v[170:173], v[68:71]
	v_mfma_f32_16x16x32_bf16 v[72:75], v[104:107], v[198:201], v[72:75]
	v_mfma_f32_16x16x32_bf16 v[76:79], v[112:115], v[198:201], v[76:79]
	v_mfma_f32_16x16x32_bf16 v[80:83], v[104:107], v[206:209], v[80:83]
	v_mfma_f32_16x16x32_bf16 v[84:87], v[112:115], v[206:209], v[84:87]
	v_mfma_f32_16x16x32_bf16 v[88:91], v[104:107], v[214:217], v[88:91]
	v_mfma_f32_16x16x32_bf16 v[92:95], v[112:115], v[214:217], v[92:95]
	v_mfma_f32_16x16x32_bf16 v[64:67], v[108:111], v[174:177], v[64:67]
	v_mfma_f32_16x16x32_bf16 v[68:71], v[116:119], v[174:177], v[68:71]
	v_mfma_f32_16x16x32_bf16 v[72:75], v[108:111], v[202:205], v[72:75]
	v_mfma_f32_16x16x32_bf16 v[76:79], v[116:119], v[202:205], v[76:79]
	v_mfma_f32_16x16x32_bf16 v[80:83], v[108:111], v[210:213], v[80:83]
	v_mfma_f32_16x16x32_bf16 v[84:87], v[116:119], v[210:213], v[84:87]
	v_mfma_f32_16x16x32_bf16 v[88:91], v[108:111], v[218:221], v[88:91]
	v_mfma_f32_16x16x32_bf16 v[92:95], v[116:119], v[218:221], v[92:95]
	v_mfma_f32_16x16x32_bf16 v[48:51], v[152:155], v[206:209], v[48:51]
	v_mfma_f32_16x16x32_bf16 v[96:99], v[120:123], v[170:173], v[96:99]
	v_mfma_f32_16x16x32_bf16 v[32:35], v[152:155], v[170:173], v[32:35]
	v_mfma_f32_16x16x32_bf16 v[40:43], v[152:155], v[198:201], v[40:43]
	v_mfma_f32_16x16x32_bf16 v[44:47], v[120:123], v[206:209], v[44:47]
	v_mfma_f32_16x16x32_bf16 v[170:173], v[156:159], v[210:213], v[48:51]
	v_mfma_f32_16x16x32_bf16 v[48:51], v[120:123], v[214:217], v[52:55]
	v_mfma_f32_16x16x32_bf16 v[96:99], v[124:127], v[174:177], v[96:99]
	v_mfma_f32_16x16x32_bf16 v[32:35], v[156:159], v[174:177], v[32:35]
	v_mfma_f32_16x16x32_bf16 v[36:39], v[120:123], v[198:201], v[36:39]
	v_mfma_f32_16x16x32_bf16 v[40:43], v[156:159], v[202:205], v[40:43]
	v_mfma_f32_16x16x32_bf16 v[44:47], v[124:127], v[210:213], v[44:47]
	v_mfma_f32_16x16x32_bf16 v[174:177], v[124:127], v[218:221], v[48:51]
	v_mfma_f32_16x16x32_bf16 v[48:51], v[152:155], v[214:217], v[56:59]
	v_mfma_f32_16x16x32_bf16 v[36:39], v[124:127], v[202:205], v[36:39]
	v_mfma_f32_16x16x32_bf16 v[198:201], v[156:159], v[218:221], v[48:51]
	s_barrier
	v_add_u32_e32 v160, s52, v181
	s_mov_b32 m0, s39
	s_nop 1
	ds_read_b128 v[48:51], v191 offset:16384
	ds_read_b128 v[52:55], v191 offset:17408
	ds_read_b128 v[56:59], v191 offset:18432
	ds_read_b128 v[202:205], v191 offset:19456
	ds_read_b128 v[206:209], v191 offset:20480
	ds_read_b128 v[210:213], v191 offset:21504
	ds_read_b128 v[214:217], v191 offset:22528
	ds_read_b128 v[218:221], v191 offset:23552
	s_nop 0
	global_load_lds_dwordx4 v160, s[14:15]
	v_add_u32_e32 v160, s52, v183
	s_mov_b32 m0, s40
	s_add_i32 s52, s43, 0x50200
	global_load_lds_dwordx4 v160, s[14:15]
	v_add_u32_e32 v160, s52, v181
	s_mov_b32 m0, s41
	s_nop 0
	global_load_lds_dwordx4 v160, s[14:15]
	v_add_u32_e32 v160, s52, v183
	s_mov_b32 m0, s42
	s_nop 0
	global_load_lds_dwordx4 v160, s[14:15]
	v_add_u32_e32 v160, s44, v180
	s_mov_b32 m0, s23
	s_nop 0
	global_load_lds_dwordx4 v160, s[12:13]
	v_add_u32_e32 v160, s44, v182
	s_mov_b32 m0, s24
	s_nop 0
	global_load_lds_dwordx4 v160, s[12:13]
	s_waitcnt vmcnt(8)
	s_waitcnt lgkmcnt(0)
	s_barrier
	s_waitcnt lgkmcnt(0)
	v_mfma_f32_16x16x32_bf16 v[0:3], v[104:107], v[214:217], v[0:3]
	v_mfma_f32_16x16x32_bf16 v[128:131], v[104:107], v[48:51], v[128:131]
	v_mfma_f32_16x16x32_bf16 v[136:139], v[104:107], v[56:59], v[136:139]
	v_mfma_f32_16x16x32_bf16 v[222:225], v[108:111], v[218:221], v[0:3]
	v_mfma_f32_16x16x32_bf16 v[0:3], v[112:115], v[214:217], v[4:7]
	v_mfma_f32_16x16x32_bf16 v[128:131], v[108:111], v[52:55], v[128:131]
	v_mfma_f32_16x16x32_bf16 v[132:135], v[112:115], v[48:51], v[132:135]
	v_mfma_f32_16x16x32_bf16 v[136:139], v[108:111], v[202:205], v[136:139]
	v_mfma_f32_16x16x32_bf16 v[140:143], v[112:115], v[56:59], v[140:143]
	v_mfma_f32_16x16x32_bf16 v[144:147], v[104:107], v[206:209], v[144:147]
	v_mfma_f32_16x16x32_bf16 v[148:151], v[112:115], v[206:209], v[148:151]
	v_mfma_f32_16x16x32_bf16 v[4:7], v[116:119], v[218:221], v[0:3]
	v_mfma_f32_16x16x32_bf16 v[132:135], v[116:119], v[52:55], v[132:135]
	v_mfma_f32_16x16x32_bf16 v[140:143], v[116:119], v[202:205], v[140:143]
	v_mfma_f32_16x16x32_bf16 v[144:147], v[108:111], v[210:213], v[144:147]
	v_mfma_f32_16x16x32_bf16 v[148:151], v[116:119], v[210:213], v[148:151]
	v_mfma_f32_16x16x32_bf16 v[0:3], v[120:123], v[48:51], v[8:11]
	v_mfma_f32_16x16x32_bf16 v[226:229], v[124:127], v[52:55], v[0:3]
	v_mfma_f32_16x16x32_bf16 v[0:3], v[152:155], v[48:51], v[12:15]
	v_mfma_f32_16x16x32_bf16 v[230:233], v[156:159], v[52:55], v[0:3]
	v_mfma_f32_16x16x32_bf16 v[0:3], v[120:123], v[56:59], v[24:27]
	v_mfma_f32_16x16x32_bf16 v[234:237], v[124:127], v[202:205], v[0:3]
	v_mfma_f32_16x16x32_bf16 v[0:3], v[152:155], v[56:59], v[28:31]
	v_mfma_f32_16x16x32_bf16 v[202:205], v[156:159], v[202:205], v[0:3]
	v_mfma_f32_16x16x32_bf16 v[0:3], v[120:123], v[206:209], v[60:63]
	v_mfma_f32_16x16x32_bf16 v[238:241], v[124:127], v[210:213], v[0:3]
	v_mfma_f32_16x16x32_bf16 v[0:3], v[152:155], v[206:209], v[100:103]
	v_mfma_f32_16x16x32_bf16 v[206:209], v[156:159], v[210:213], v[0:3]
	v_mfma_f32_16x16x32_bf16 v[0:3], v[120:123], v[214:217], v[16:19]
	v_mfma_f32_16x16x32_bf16 v[16:19], v[124:127], v[218:221], v[0:3]
	v_mfma_f32_16x16x32_bf16 v[0:3], v[152:155], v[214:217], v[20:23]
	v_mfma_f32_16x16x32_bf16 v[152:155], v[156:159], v[218:221], v[0:3]
	s_barrier
;     ...
;         if constexpr (Epi::MIDHOOK) {
;             for (int t = 0; t < 4; t += 2) PG8_ITER(t);
	ds_read_b128 v[20:23], v167
	ds_read_b128 v[120:123], v167 offset:1024
	ds_read_b128 v[156:159], v167 offset:2048
	ds_read_b128 v[210:213], v167 offset:3072
	ds_read_b128 v[214:217], v169
	ds_read_b128 v[218:221], v169 offset:1024
	ds_read_b128 v[242:245], v169 offset:2048
	ds_read_b128 v[246:249], v169 offset:3072
	s_add_i32 s52, s44, 0x150000
	v_add_u32_e32 v0, s52, v180
	s_mov_b32 m0, s25
	ds_read_b128 v[28:31], v191 offset:32768
	ds_read_b128 v[48:51], v191 offset:33792
	ds_read_b128 v[60:63], v191 offset:34816
	ds_read_b128 v[104:107], v191 offset:35840
	ds_read_b128 v[108:111], v191 offset:36864
	ds_read_b128 v[112:115], v191 offset:37888
	ds_read_b128 v[116:119], v191 offset:38912
	ds_read_b128 v[124:127], v191 offset:39936
	s_nop 0
	global_load_lds_dwordx4 v0, s[12:13]
	v_add_u32_e32 v0, s52, v182
	s_mov_b32 m0, s26
	s_nop 0
	global_load_lds_dwordx4 v0, s[12:13]
	s_waitcnt vmcnt(8)
	s_waitcnt lgkmcnt(0)
	s_barrier
	s_waitcnt lgkmcnt(0)
	v_mfma_f32_16x16x32_bf16 v[8:11], v[156:159], v[28:31], v[68:71]
	v_mfma_f32_16x16x32_bf16 v[12:15], v[210:213], v[48:51], v[8:11]
	v_mfma_f32_16x16x32_bf16 v[8:11], v[20:23], v[60:63], v[72:75]
	v_mfma_f32_16x16x32_bf16 v[24:27], v[120:123], v[104:107], v[8:11]
	v_mfma_f32_16x16x32_bf16 v[8:11], v[156:159], v[60:63], v[76:79]
	v_mfma_f32_16x16x32_bf16 v[52:55], v[210:213], v[104:107], v[8:11]
	v_mfma_f32_16x16x32_bf16 v[8:11], v[20:23], v[108:111], v[80:83]
	v_mfma_f32_16x16x32_bf16 v[56:59], v[120:123], v[112:115], v[8:11]
	v_mfma_f32_16x16x32_bf16 v[8:11], v[156:159], v[108:111], v[84:87]
	v_mfma_f32_16x16x32_bf16 v[76:79], v[210:213], v[112:115], v[8:11]
	v_mfma_f32_16x16x32_bf16 v[8:11], v[20:23], v[116:119], v[88:91]
	v_mfma_f32_16x16x32_bf16 v[0:3], v[20:23], v[28:31], v[64:67]
	v_mfma_f32_16x16x32_bf16 v[80:83], v[120:123], v[124:127], v[8:11]
	v_mfma_f32_16x16x32_bf16 v[8:11], v[156:159], v[116:119], v[92:95]
	v_mfma_f32_16x16x32_bf16 v[0:3], v[120:123], v[48:51], v[0:3]
	v_mfma_f32_16x16x32_bf16 v[100:103], v[210:213], v[124:127], v[8:11]
	v_mfma_f32_16x16x32_bf16 v[8:11], v[214:217], v[28:31], v[96:99]
	v_mfma_f32_16x16x32_bf16 v[28:31], v[242:245], v[28:31], v[32:35]
	v_mfma_f32_16x16x32_bf16 v[32:35], v[214:217], v[60:63], v[36:39]
	v_mfma_f32_16x16x32_bf16 v[8:11], v[218:221], v[48:51], v[8:11]
	v_mfma_f32_16x16x32_bf16 v[28:31], v[246:249], v[48:51], v[28:31]
	v_mfma_f32_16x16x32_bf16 v[48:51], v[218:221], v[104:107], v[32:35]
	v_mfma_f32_16x16x32_bf16 v[32:35], v[242:245], v[60:63], v[40:43]
	v_mfma_f32_16x16x32_bf16 v[60:63], v[246:249], v[104:107], v[32:35]
	v_mfma_f32_16x16x32_bf16 v[32:35], v[214:217], v[108:111], v[44:47]
	v_mfma_f32_16x16x32_bf16 v[72:75], v[218:221], v[112:115], v[32:35]
	v_mfma_f32_16x16x32_bf16 v[32:35], v[242:245], v[108:111], v[170:173]
	v_mfma_f32_16x16x32_bf16 v[84:87], v[246:249], v[112:115], v[32:35]
	v_mfma_f32_16x16x32_bf16 v[32:35], v[214:217], v[116:119], v[174:177]
	v_mfma_f32_16x16x32_bf16 v[96:99], v[218:221], v[124:127], v[32:35]
	v_mfma_f32_16x16x32_bf16 v[32:35], v[242:245], v[116:119], v[198:201]
	v_mfma_f32_16x16x32_bf16 v[116:119], v[246:249], v[124:127], v[32:35]
	s_barrier
	s_or_b32 s52, s43, 0x280
	s_nop 3
	v_add_u32_e32 v32, s52, v181
	s_mov_b32 m0, s45
	ds_read_b128 v[40:43], v191 offset:49152
	ds_read_b128 v[44:47], v191 offset:50176
	ds_read_b128 v[92:95], v191 offset:51200
	ds_read_b128 v[170:173], v191 offset:52224
	ds_read_b128 v[174:177], v191 offset:53248
	ds_read_b128 v[198:201], v191 offset:54272
	ds_read_b128 v[250:253], v191 offset:55296
	ds_read_b128 v[160:163], v191 offset:56320
	s_nop 0
	global_load_lds_dwordx4 v32, s[14:15]
	v_add_u32_e32 v32, s52, v183
	s_mov_b32 m0, s46
	s_add_i32 s52, s43, 0x50280
	global_load_lds_dwordx4 v32, s[14:15]
	v_add_u32_e32 v32, s52, v181
	s_mov_b32 m0, s47
	s_nop 0
	global_load_lds_dwordx4 v32, s[14:15]
	v_add_u32_e32 v32, s52, v183
	s_mov_b32 m0, s48
	s_nop 0
	global_load_lds_dwordx4 v32, s[14:15]
	v_add_u32_e32 v32, s51, v180
	s_mov_b32 m0, s28
	s_nop 0
	global_load_lds_dwordx4 v32, s[12:13]
	v_add_u32_e32 v32, s51, v182
	s_mov_b32 m0, s29
	s_nop 0
	global_load_lds_dwordx4 v32, s[12:13]
	s_waitcnt vmcnt(8)
	s_waitcnt lgkmcnt(0)
	s_barrier
	s_waitcnt lgkmcnt(0)
	v_mfma_f32_16x16x32_bf16 v[32:35], v[20:23], v[40:43], v[128:131]
	v_mfma_f32_16x16x32_bf16 v[112:115], v[120:123], v[44:47], v[32:35]
	v_mfma_f32_16x16x32_bf16 v[32:35], v[156:159], v[40:43], v[132:135]
	v_mfma_f32_16x16x32_bf16 v[124:127], v[210:213], v[44:47], v[32:35]
	v_mfma_f32_16x16x32_bf16 v[32:35], v[20:23], v[92:95], v[136:139]
	v_mfma_f32_16x16x32_bf16 v[104:107], v[120:123], v[170:173], v[32:35]
	v_mfma_f32_16x16x32_bf16 v[32:35], v[156:159], v[92:95], v[140:143]
	v_mfma_f32_16x16x32_bf16 v[108:111], v[210:213], v[170:173], v[32:35]
	v_mfma_f32_16x16x32_bf16 v[32:35], v[20:23], v[174:177], v[144:147]
	v_mfma_f32_16x16x32_bf16 v[68:71], v[120:123], v[198:201], v[32:35]
	v_mfma_f32_16x16x32_bf16 v[32:35], v[156:159], v[174:177], v[148:151]
	v_mfma_f32_16x16x32_bf16 v[20:23], v[20:23], v[250:253], v[222:225]
	v_mfma_f32_16x16x32_bf16 v[64:67], v[210:213], v[198:201], v[32:35]
	v_mfma_f32_16x16x32_bf16 v[32:35], v[120:123], v[160:163], v[20:23]
	v_mfma_f32_16x16x32_bf16 v[4:7], v[156:159], v[250:253], v[4:7]
	v_mfma_f32_16x16x32_bf16 v[36:39], v[210:213], v[160:163], v[4:7]
	v_mfma_f32_16x16x32_bf16 v[4:7], v[214:217], v[40:43], v[226:229]
	v_mfma_f32_16x16x32_bf16 v[120:123], v[218:221], v[44:47], v[4:7]
	v_mfma_f32_16x16x32_bf16 v[4:7], v[242:245], v[40:43], v[230:233]
	v_mfma_f32_16x16x32_bf16 v[128:131], v[246:249], v[44:47], v[4:7]
	v_mfma_f32_16x16x32_bf16 v[4:7], v[214:217], v[92:95], v[234:237]
	v_mfma_f32_16x16x32_bf16 v[88:91], v[218:221], v[170:173], v[4:7]
	v_mfma_f32_16x16x32_bf16 v[4:7], v[242:245], v[92:95], v[202:205]
	v_mfma_f32_16x16x32_bf16 v[92:95], v[246:249], v[170:173], v[4:7]
	v_mfma_f32_16x16x32_bf16 v[4:7], v[214:217], v[174:177], v[238:241]
	v_mfma_f32_16x16x32_bf16 v[40:43], v[218:221], v[198:201], v[4:7]
	v_mfma_f32_16x16x32_bf16 v[4:7], v[242:245], v[174:177], v[206:209]
	v_mfma_f32_16x16x32_bf16 v[44:47], v[246:249], v[198:201], v[4:7]
	v_mfma_f32_16x16x32_bf16 v[4:7], v[214:217], v[250:253], v[16:19]
	v_mfma_f32_16x16x32_bf16 v[20:23], v[218:221], v[160:163], v[4:7]
	v_mfma_f32_16x16x32_bf16 v[4:7], v[242:245], v[250:253], v[152:155]
	v_mfma_f32_16x16x32_bf16 v[16:19], v[246:249], v[160:163], v[4:7]
	s_barrier
; __device__ __forceinline__ float lo16(unsigned w) { return __uint_as_float(w << 16); }
; __device__ __forceinline__ float hi16(unsigned w) { return __uint_as_float(w & 0xffff0000u); }
;     __device__ __forceinline__ void mid(f32x4 (&acc)[2][2][4][2], const pg8::Unit& u, int wr, int wc, int fr, int fq) const {
;         const int row0 = u.pm * 256 + wr * 64 + fr, col0 = u.pn * 256 + wc * 32 + 8 * fq;
; #pragma unroll
;         for (int ai = 0; ai < 2; ++ai)
; #pragma unroll
;             for (int m = 0; m < 4; ++m) { const int row = row0 + ai * 128 + m * 16;
; #pragma unroll
;                 for (int bj = 0; bj < 2; ++bj) { const int col = col0 + bj * 128;
;                     const u32x4 aw = *(const u32x4*)((const char*)gA + (unsigned)(row * DM + col) * 2u), bw = *(const u32x4*)((const char*)gB + (unsigned)(row * NMAIN + col) * 2u);
;                     f32x4 r0, r1;
;                     r0[0] = lo16(bw.x) * __builtin_amdgcn_rcpf(fmaxf(lo16(aw.x), 1e-20f)); r0[1] = hi16(bw.x) * __builtin_amdgcn_rcpf(fmaxf(hi16(aw.x), 1e-20f));
;                     r0[2] = lo16(bw.y) * __builtin_amdgcn_rcpf(fmaxf(lo16(aw.y), 1e-20f)); r0[3] = hi16(bw.y) * __builtin_amdgcn_rcpf(fmaxf(hi16(aw.y), 1e-20f));
;                     r1[0] = lo16(bw.z) * __builtin_amdgcn_rcpf(fmaxf(lo16(aw.z), 1e-20f)); r1[1] = hi16(bw.z) * __builtin_amdgcn_rcpf(fmaxf(hi16(aw.z), 1e-20f));
;                     r1[2] = lo16(bw.w) * __builtin_amdgcn_rcpf(fmaxf(lo16(aw.w), 1e-20f)); r1[3] = hi16(bw.w) * __builtin_amdgcn_rcpf(fmaxf(hi16(aw.w), 1e-20f));
;                     acc[ai][bj][m][0] *= r0; acc[ai][bj][m][1] *= r1;
;                     asm volatile("" ::: "memory"); } }
	v_lshl_add_u32 v168, s50, 8, v184
	v_lshl_or_b32 v166, s49, 8, v192
	v_lshlrev_b32_e32 v132, 11, v168
	v_mul_lo_u32 v175, v168, s2
	v_lshlrev_b32_e32 v177, 1, v166
	v_or_b32_e32 v171, 0x80, v166
	v_add_u32_e32 v4, v132, v177
	v_add_lshl_u32 v133, v175, v166, 1
	v_lshlrev_b32_e32 v173, 1, v171
	global_load_dwordx4 v[4:7], v4, s[8:9]
	v_add_u32_e32 v132, v173, v132
	global_load_dwordx4 v[148:151], v133, s[18:19]
	global_load_dwordx4 v[144:147], v132, s[8:9]
	v_add_lshl_u32 v132, v175, v171, 1
	global_load_dwordx4 v[140:143], v132, s[18:19]
	v_or_b32_e32 v170, 16, v168
	v_lshlrev_b32_e32 v172, 11, v170
	v_add_u32_e32 v174, 0x15000, v175
	v_add_u32_e32 v132, v172, v177
	v_add_lshl_u32 v133, v174, v166, 1
	global_load_dwordx4 v[136:139], v132, s[8:9]
	s_nop 0
	global_load_dwordx4 v[132:135], v133, s[18:19]
	v_add_u32_e32 v178, 0x90, v168
	s_and_b64 s[50:51], s[6:7], exec
	s_cselect_b32 s50, s37, s44
	s_cselect_b32 s49, s38, s43
	s_bitset1_b32 s50, 11
	s_add_i32 s44, s44, 0x150080
	s_addk_i32 s43, 0x300
	s_mov_b32 s51, 2
	s_waitcnt vmcnt(0)
	v_lshlrev_b32_e32 v154, 16, v4
	v_and_b32_e32 v155, 0xffff0000, v4
	v_lshlrev_b32_e32 v156, 16, v5
	v_and_b32_e32 v157, 0xffff0000, v5
	v_lshlrev_b32_e32 v152, 16, v148
	v_and_b32_e32 v153, 0xffff0000, v148
	v_lshlrev_b32_e32 v4, 16, v149
	v_and_b32_e32 v5, 0xffff0000, v149
	v_lshlrev_b32_e32 v158, 16, v6
	v_and_b32_e32 v159, 0xffff0000, v6
	v_lshlrev_b32_e32 v148, 16, v150
	v_and_b32_e32 v149, 0xffff0000, v150
	v_lshlrev_b32_e32 v150, 16, v7
	v_and_b32_e32 v160, 0xffff0000, v7
	v_max_f32_e32 v154, v154, v154
	v_max_f32_e32 v155, v155, v155
	v_max_f32_e32 v156, v156, v156
	v_max_f32_e32 v157, v157, v157
	v_lshlrev_b32_e32 v6, 16, v151
	v_and_b32_e32 v7, 0xffff0000, v151
	v_max_f32_e32 v158, v158, v158
	v_max_f32_e32 v159, v159, v159
	v_max_f32_e32 v161, v150, v150
	v_max_f32_e32 v160, v160, v160
	v_lshlrev_b32_e32 v162, 16, v144
	v_and_b32_e32 v144, 0xffff0000, v144
	v_lshlrev_b32_e32 v150, 16, v140
	v_and_b32_e32 v151, 0xffff0000, v140
	v_lshlrev_b32_e32 v140, 16, v145
	v_and_b32_e32 v145, 0xffff0000, v145
	v_max_f32_e32 v154, 0x1e3ce508, v154
	v_max_f32_e32 v155, 0x1e3ce508, v155
	v_max_f32_e32 v156, 0x1e3ce508, v156
	v_max_f32_e32 v157, 0x1e3ce508, v157
	v_max_f32_e32 v158, 0x1e3ce508, v158
	v_max_f32_e32 v159, 0x1e3ce508, v159
	v_max_f32_e32 v161, 0x1e3ce508, v161
	v_max_f32_e32 v160, 0x1e3ce508, v160
	v_max_f32_e32 v162, v162, v162
	v_max_f32_e32 v163, v144, v144
	v_max_f32_e32 v176, v145, v145
	v_rcp_f32_e32 v144, v154
	v_rcp_f32_e32 v145, v155
	v_rcp_f32_e32 v154, v156
	v_rcp_f32_e32 v155, v157
	v_rcp_f32_e32 v156, v158
	v_rcp_f32_e32 v157, v159
	v_rcp_f32_e32 v158, v161
	v_rcp_f32_e32 v159, v160
	v_max_f32_e32 v160, 0x1e3ce508, v162
	v_max_f32_e32 v161, 0x1e3ce508, v163
	v_rcp_f32_e32 v160, v160
	v_rcp_f32_e32 v161, v161
	v_max_f32_e32 v140, v140, v140
	v_pk_mul_f32 v[144:145], v[144:145], v[152:153]
	v_pk_mul_f32 v[4:5], v[154:155], v[4:5]
	v_max_f32_e32 v140, 0x1e3ce508, v140
	v_pk_mul_f32 v[148:149], v[156:157], v[148:149]
	v_pk_mul_f32 v[152:153], v[158:159], v[6:7]
	v_pk_mul_f32 v[6:7], v[2:3], v[4:5]
	v_pk_mul_f32 v[4:5], v[0:1], v[144:145]
	v_add_u32_e32 v144, v172, v173
	v_rcp_f32_e32 v162, v140
	v_pk_mul_f32 v[2:3], v[14:15], v[152:153]
	v_pk_mul_f32 v[0:1], v[12:13], v[148:149]
	v_pk_mul_f32 v[12:13], v[160:161], v[150:151]
	v_lshlrev_b32_e32 v14, 16, v141
	v_and_b32_e32 v15, 0xffff0000, v141
	v_lshlrev_b32_e32 v140, 16, v146
	v_and_b32_e32 v141, 0xffff0000, v146
	global_load_dwordx4 v[148:151], v144, s[8:9]
	v_lshlrev_b32_e32 v144, 16, v142
	v_and_b32_e32 v145, 0xffff0000, v142
	v_lshlrev_b32_e32 v142, 16, v147
	v_max_f32_e32 v140, v140, v140
	v_max_f32_e32 v141, v141, v141
	v_max_f32_e32 v142, v142, v142
	v_max_f32_e32 v140, 0x1e3ce508, v140
	v_max_f32_e32 v141, 0x1e3ce508, v141
	v_add_lshl_u32 v146, v174, v171, 1
	v_max_f32_e32 v142, 0x1e3ce508, v142
	v_rcp_f32_e32 v140, v140
	v_rcp_f32_e32 v141, v141
	global_load_dwordx4 v[154:157], v146, s[18:19]
	v_rcp_f32_e32 v146, v142
	v_and_b32_e32 v142, 0xffff0000, v147
	v_max_f32_e32 v142, v142, v142
	v_max_f32_e32 v163, 0x1e3ce508, v176
	v_max_f32_e32 v142, 0x1e3ce508, v142
	v_rcp_f32_e32 v163, v163
	v_rcp_f32_e32 v147, v142
	v_pk_mul_f32 v[140:141], v[140:141], v[144:145]
	v_pk_mul_f32 v[12:13], v[8:9], v[12:13]
	v_pk_mul_f32 v[8:9], v[28:29], v[140:141]
	v_lshlrev_b32_e32 v28, 16, v136
	v_and_b32_e32 v29, 0xffff0000, v136
	v_lshlrev_b32_e32 v142, 16, v143
	v_and_b32_e32 v143, 0xffff0000, v143
	v_max_f32_e32 v28, v28, v28
	v_max_f32_e32 v29, v29, v29
	v_pk_mul_f32 v[14:15], v[162:163], v[14:15]
	v_pk_mul_f32 v[142:143], v[146:147], v[142:143]
	v_max_f32_e32 v28, 0x1e3ce508, v28
	v_max_f32_e32 v29, 0x1e3ce508, v29
	v_pk_mul_f32 v[14:15], v[10:11], v[14:15]
	v_pk_mul_f32 v[10:11], v[30:31], v[142:143]
	v_rcp_f32_e32 v28, v28
	v_rcp_f32_e32 v29, v29
	v_lshlrev_b32_e32 v30, 16, v132
	v_and_b32_e32 v31, 0xffff0000, v132
	v_lshlrev_b32_e32 v132, 16, v137
	v_max_f32_e32 v132, v132, v132
	v_max_f32_e32 v132, 0x1e3ce508, v132
	v_or_b32_e32 v172, 32, v168
	v_rcp_f32_e32 v136, v132
	v_and_b32_e32 v132, 0xffff0000, v137
	v_lshlrev_b32_e32 v152, 11, v172
	v_max_f32_e32 v132, v132, v132
	v_pk_mul_f32 v[28:29], v[28:29], v[30:31]
	v_lshlrev_b32_e32 v30, 16, v133
	v_and_b32_e32 v31, 0xffff0000, v133
	v_add_u32_e32 v133, v152, v177
	v_max_f32_e32 v132, 0x1e3ce508, v132
	global_load_dwordx4 v[140:143], v133, s[8:9]
	v_rcp_f32_e32 v137, v132
	v_add_u32_e32 v158, 0x2a000, v175
	v_lshlrev_b32_e32 v132, 16, v138
	v_and_b32_e32 v133, 0xffff0000, v138
	v_pk_mul_f32 v[30:31], v[136:137], v[30:31]
	v_add_lshl_u32 v136, v158, v166, 1
	global_load_dwordx4 v[144:147], v136, s[18:19]
	v_max_f32_e32 v132, v132, v132
	v_max_f32_e32 v133, v133, v133
	v_max_f32_e32 v132, 0x1e3ce508, v132
	v_max_f32_e32 v133, 0x1e3ce508, v133
	v_rcp_f32_e32 v132, v132
	v_rcp_f32_e32 v133, v133
	v_lshlrev_b32_e32 v136, 16, v134
	v_and_b32_e32 v137, 0xffff0000, v134
	v_lshlrev_b32_e32 v134, 16, v139
	v_max_f32_e32 v134, v134, v134
	v_max_f32_e32 v134, 0x1e3ce508, v134
	v_rcp_f32_e32 v138, v134
	v_and_b32_e32 v134, 0xffff0000, v139
	v_max_f32_e32 v134, v134, v134
	v_pk_mul_f32 v[132:133], v[132:133], v[136:137]
	v_max_f32_e32 v134, 0x1e3ce508, v134
	v_pk_mul_f32 v[28:29], v[24:25], v[28:29]
	v_pk_mul_f32 v[24:25], v[52:53], v[132:133]
	s_waitcnt vmcnt(3)
; __device__ __forceinline__ float lo16(unsigned w) { return __uint_as_float(w << 16); }
; __device__ __forceinline__ float hi16(unsigned w) { return __uint_as_float(w & 0xffff0000u); }
;     __device__ __forceinline__ void mid(f32x4 (&acc)[2][2][4][2], const pg8::Unit& u, int wr, int wc, int fr, int fq) const {
;         const int row0 = u.pm * 256 + wr * 64 + fr, col0 = u.pn * 256 + wc * 32 + 8 * fq;
; #pragma unroll
;         for (int ai = 0; ai < 2; ++ai)
; #pragma unroll
;             for (int m = 0; m < 4; ++m) { const int row = row0 + ai * 128 + m * 16;
; #pragma unroll
;                 for (int bj = 0; bj < 2; ++bj) { const int col = col0 + bj * 128;
;                     const u32x4 aw = *(const u32x4*)((const char*)gA + (unsigned)(row * DM + col) * 2u), bw = *(const u32x4*)((const char*)gB + (unsigned)(row * NMAIN + col) * 2u);
;                     f32x4 r0, r1;
;                     r0[0] = lo16(bw.x) * __builtin_amdgcn_rcpf(fmaxf(lo16(aw.x), 1e-20f)); r0[1] = hi16(bw.x) * __builtin_amdgcn_rcpf(fmaxf(hi16(aw.x), 1e-20f));
;                     r0[2] = lo16(bw.y) * __builtin_amdgcn_rcpf(fmaxf(lo16(aw.y), 1e-20f)); r0[3] = hi16(bw.y) * __builtin_amdgcn_rcpf(fmaxf(hi16(aw.y), 1e-20f));
;                     r1[0] = lo16(bw.z) * __builtin_amdgcn_rcpf(fmaxf(lo16(aw.z), 1e-20f)); r1[1] = hi16(bw.z) * __builtin_amdgcn_rcpf(fmaxf(hi16(aw.z), 1e-20f));
;                     r1[2] = lo16(bw.w) * __builtin_amdgcn_rcpf(fmaxf(lo16(aw.w), 1e-20f)); r1[3] = hi16(bw.w) * __builtin_amdgcn_rcpf(fmaxf(hi16(aw.w), 1e-20f));
;                     acc[ai][bj][m][0] *= r0; acc[ai][bj][m][1] *= r1;
;                     asm volatile("" ::: "memory"); } }
	v_lshlrev_b32_e32 v52, 16, v148
	v_and_b32_e32 v53, 0xffff0000, v148
	v_rcp_f32_e32 v139, v134
	v_max_f32_e32 v52, v52, v52
	v_max_f32_e32 v53, v53, v53
	v_lshlrev_b32_e32 v132, 16, v149
	v_and_b32_e32 v133, 0xffff0000, v149
	v_max_f32_e32 v52, 0x1e3ce508, v52
	v_max_f32_e32 v53, 0x1e3ce508, v53
	v_max_f32_e32 v132, v132, v132
	v_max_f32_e32 v133, v133, v133
	v_rcp_f32_e32 v52, v52
	v_rcp_f32_e32 v53, v53
	v_max_f32_e32 v132, 0x1e3ce508, v132
	v_max_f32_e32 v133, 0x1e3ce508, v133
	v_lshlrev_b32_e32 v134, 16, v135
	v_and_b32_e32 v135, 0xffff0000, v135
	v_rcp_f32_e32 v132, v132
	v_rcp_f32_e32 v133, v133
	v_pk_mul_f32 v[134:135], v[138:139], v[134:135]
	v_pk_mul_f32 v[30:31], v[26:27], v[30:31]
	v_pk_mul_f32 v[26:27], v[54:55], v[134:135]
	s_waitcnt vmcnt(2)
	v_lshlrev_b32_e32 v54, 16, v154
	v_and_b32_e32 v55, 0xffff0000, v154
	v_pk_mul_f32 v[52:53], v[52:53], v[54:55]
	v_lshlrev_b32_e32 v54, 16, v155
	v_and_b32_e32 v55, 0xffff0000, v155
	v_pk_mul_f32 v[54:55], v[132:133], v[54:55]
	v_lshlrev_b32_e32 v132, 16, v150
	v_and_b32_e32 v133, 0xffff0000, v150
	v_max_f32_e32 v132, v132, v132
	v_max_f32_e32 v133, v133, v133
	v_max_f32_e32 v132, 0x1e3ce508, v132
	v_add_u32_e32 v134, v152, v173
	v_max_f32_e32 v133, 0x1e3ce508, v133
	v_rcp_f32_e32 v132, v132
	global_load_dwordx4 v[152:155], v134, s[8:9]
	v_rcp_f32_e32 v133, v133
	v_add_lshl_u32 v137, v158, v171, 1
	v_lshlrev_b32_e32 v134, 16, v156
	v_and_b32_e32 v135, 0xffff0000, v156
	v_lshlrev_b32_e32 v136, 16, v151
	global_load_dwordx4 v[158:161], v137, s[18:19]
	v_and_b32_e32 v137, 0xffff0000, v151
	v_max_f32_e32 v136, v136, v136
	v_max_f32_e32 v137, v137, v137
	v_pk_mul_f32 v[132:133], v[132:133], v[134:135]
	v_max_f32_e32 v136, 0x1e3ce508, v136
	v_max_f32_e32 v137, 0x1e3ce508, v137
	v_pk_mul_f32 v[52:53], v[48:49], v[52:53]
	v_pk_mul_f32 v[48:49], v[60:61], v[132:133]
	v_rcp_f32_e32 v136, v136
	v_rcp_f32_e32 v137, v137
	s_waitcnt vmcnt(3)
	v_lshlrev_b32_e32 v60, 16, v140
	v_and_b32_e32 v61, 0xffff0000, v140
	v_max_f32_e32 v60, v60, v60
	v_max_f32_e32 v61, v61, v61
	v_lshlrev_b32_e32 v132, 16, v141
	v_and_b32_e32 v133, 0xffff0000, v141
	v_max_f32_e32 v60, 0x1e3ce508, v60
	v_max_f32_e32 v61, 0x1e3ce508, v61
	v_max_f32_e32 v132, v132, v132
	v_max_f32_e32 v133, v133, v133
	v_rcp_f32_e32 v60, v60
	v_rcp_f32_e32 v61, v61
	v_max_f32_e32 v132, 0x1e3ce508, v132
	v_max_f32_e32 v133, 0x1e3ce508, v133
	v_lshlrev_b32_e32 v134, 16, v157
	v_and_b32_e32 v135, 0xffff0000, v157
	v_rcp_f32_e32 v132, v132
	v_rcp_f32_e32 v133, v133
	v_pk_mul_f32 v[134:135], v[136:137], v[134:135]
	v_pk_mul_f32 v[54:55], v[50:51], v[54:55]
	v_pk_mul_f32 v[50:51], v[62:63], v[134:135]
	s_waitcnt vmcnt(2)
	v_lshlrev_b32_e32 v62, 16, v144
	v_and_b32_e32 v63, 0xffff0000, v144
	v_pk_mul_f32 v[60:61], v[60:61], v[62:63]
	v_lshlrev_b32_e32 v62, 16, v145
	v_and_b32_e32 v63, 0xffff0000, v145
	v_pk_mul_f32 v[62:63], v[132:133], v[62:63]
	v_lshlrev_b32_e32 v132, 16, v142
	v_or_b32_e32 v174, 48, v168
	v_max_f32_e32 v132, v132, v132
	v_lshlrev_b32_e32 v148, 11, v174
	v_max_f32_e32 v136, 0x1e3ce508, v132
	v_add_u32_e32 v132, v148, v177
	global_load_dwordx4 v[132:135], v132, s[8:9]
	v_add_u32_e32 v150, 0x3f000, v175
	v_add_lshl_u32 v138, v150, v166, 1
	global_load_dwordx4 v[138:141], v138, s[18:19]
	v_and_b32_e32 v137, 0xffff0000, v142
	v_max_f32_e32 v137, v137, v137
	v_max_f32_e32 v137, 0x1e3ce508, v137
	v_rcp_f32_e32 v136, v136
	v_rcp_f32_e32 v137, v137
	v_lshlrev_b32_e32 v144, 16, v146
	v_and_b32_e32 v145, 0xffff0000, v146
	v_lshlrev_b32_e32 v142, 16, v143
	v_and_b32_e32 v143, 0xffff0000, v143
	v_max_f32_e32 v142, v142, v142
	v_max_f32_e32 v143, v143, v143
	v_pk_mul_f32 v[136:137], v[136:137], v[144:145]
	v_max_f32_e32 v142, 0x1e3ce508, v142
	v_max_f32_e32 v143, 0x1e3ce508, v143
	v_pk_mul_f32 v[60:61], v[56:57], v[60:61]
	v_pk_mul_f32 v[56:57], v[76:77], v[136:137]
	v_rcp_f32_e32 v142, v142
	v_rcp_f32_e32 v143, v143
	v_lshlrev_b32_e32 v144, 16, v147
	v_and_b32_e32 v145, 0xffff0000, v147
	v_pk_mul_f32 v[62:63], v[58:59], v[62:63]
	v_pk_mul_f32 v[142:143], v[142:143], v[144:145]
	v_add_lshl_u32 v145, v150, v171, 1
	v_pk_mul_f32 v[58:59], v[78:79], v[142:143]
	s_waitcnt vmcnt(3)
	v_lshlrev_b32_e32 v76, 16, v152
	v_and_b32_e32 v77, 0xffff0000, v152
	v_max_f32_e32 v76, v76, v76
	v_max_f32_e32 v77, v77, v77
	v_lshlrev_b32_e32 v136, 16, v153
	v_and_b32_e32 v137, 0xffff0000, v153
	v_max_f32_e32 v76, 0x1e3ce508, v76
	v_max_f32_e32 v77, 0x1e3ce508, v77
	v_max_f32_e32 v136, v136, v136
	v_max_f32_e32 v137, v137, v137
	v_rcp_f32_e32 v76, v76
	v_rcp_f32_e32 v77, v77
	v_max_f32_e32 v136, 0x1e3ce508, v136
	v_max_f32_e32 v137, 0x1e3ce508, v137
	v_rcp_f32_e32 v136, v136
	v_rcp_f32_e32 v137, v137
	s_waitcnt vmcnt(2)
	v_lshlrev_b32_e32 v78, 16, v158
	v_and_b32_e32 v79, 0xffff0000, v158
	v_pk_mul_f32 v[76:77], v[76:77], v[78:79]
	v_lshlrev_b32_e32 v78, 16, v159
	v_and_b32_e32 v79, 0xffff0000, v159
	v_pk_mul_f32 v[78:79], v[136:137], v[78:79]
	v_lshlrev_b32_e32 v136, 16, v154
	v_and_b32_e32 v137, 0xffff0000, v154
	v_add_u32_e32 v142, v148, v173
	v_max_f32_e32 v136, v136, v136
	global_load_dwordx4 v[146:149], v142, s[8:9]
	v_max_f32_e32 v137, v137, v137
	v_max_f32_e32 v136, 0x1e3ce508, v136
	v_max_f32_e32 v137, 0x1e3ce508, v137
	v_rcp_f32_e32 v136, v136
	v_rcp_f32_e32 v137, v137
	v_lshlrev_b32_e32 v142, 16, v160
	v_and_b32_e32 v143, 0xffff0000, v160
	v_lshlrev_b32_e32 v144, 16, v155
	global_load_dwordx4 v[156:159], v145, s[18:19]
	v_and_b32_e32 v145, 0xffff0000, v155
	v_max_f32_e32 v144, v144, v144
	v_max_f32_e32 v145, v145, v145
	v_pk_mul_f32 v[136:137], v[136:137], v[142:143]
	v_max_f32_e32 v144, 0x1e3ce508, v144
	v_max_f32_e32 v145, 0x1e3ce508, v145
	v_pk_mul_f32 v[76:77], v[72:73], v[76:77]
	v_pk_mul_f32 v[72:73], v[84:85], v[136:137]
	v_rcp_f32_e32 v144, v144
	v_rcp_f32_e32 v145, v145
	v_lshlrev_b32_e32 v142, 16, v161
	v_and_b32_e32 v143, 0xffff0000, v161
	v_pk_mul_f32 v[78:79], v[74:75], v[78:79]
	v_pk_mul_f32 v[142:143], v[144:145], v[142:143]
	v_add_u32_e32 v176, 0x80, v168
	s_waitcnt vmcnt(3)
; __device__ __forceinline__ float lo16(unsigned w) { return __uint_as_float(w << 16); }
; __device__ __forceinline__ float hi16(unsigned w) { return __uint_as_float(w & 0xffff0000u); }
;     __device__ __forceinline__ void mid(f32x4 (&acc)[2][2][4][2], const pg8::Unit& u, int wr, int wc, int fr, int fq) const {
;         const int row0 = u.pm * 256 + wr * 64 + fr, col0 = u.pn * 256 + wc * 32 + 8 * fq;
; #pragma unroll
;         for (int ai = 0; ai < 2; ++ai)
; #pragma unroll
;             for (int m = 0; m < 4; ++m) { const int row = row0 + ai * 128 + m * 16;
; #pragma unroll
;                 for (int bj = 0; bj < 2; ++bj) { const int col = col0 + bj * 128;
;                     const u32x4 aw = *(const u32x4*)((const char*)gA + (unsigned)(row * DM + col) * 2u), bw = *(const u32x4*)((const char*)gB + (unsigned)(row * NMAIN + col) * 2u);
;                     f32x4 r0, r1;
;                     r0[0] = lo16(bw.x) * __builtin_amdgcn_rcpf(fmaxf(lo16(aw.x), 1e-20f)); r0[1] = hi16(bw.x) * __builtin_amdgcn_rcpf(fmaxf(hi16(aw.x), 1e-20f));
;                     r0[2] = lo16(bw.y) * __builtin_amdgcn_rcpf(fmaxf(lo16(aw.y), 1e-20f)); r0[3] = hi16(bw.y) * __builtin_amdgcn_rcpf(fmaxf(hi16(aw.y), 1e-20f));
;                     r1[0] = lo16(bw.z) * __builtin_amdgcn_rcpf(fmaxf(lo16(aw.z), 1e-20f)); r1[1] = hi16(bw.z) * __builtin_amdgcn_rcpf(fmaxf(hi16(aw.z), 1e-20f));
;                     r1[2] = lo16(bw.w) * __builtin_amdgcn_rcpf(fmaxf(lo16(aw.w), 1e-20f)); r1[3] = hi16(bw.w) * __builtin_amdgcn_rcpf(fmaxf(hi16(aw.w), 1e-20f));
;                     acc[ai][bj][m][0] *= r0; acc[ai][bj][m][1] *= r1;
;                     asm volatile("" ::: "memory"); } }
;     }
	v_lshlrev_b32_e32 v84, 16, v132
	v_and_b32_e32 v85, 0xffff0000, v132
	v_max_f32_e32 v84, v84, v84
	v_max_f32_e32 v85, v85, v85
	v_lshlrev_b32_e32 v132, 16, v133
	v_and_b32_e32 v133, 0xffff0000, v133
	v_max_f32_e32 v84, 0x1e3ce508, v84
	v_max_f32_e32 v85, 0x1e3ce508, v85
	v_max_f32_e32 v132, v132, v132
	v_max_f32_e32 v133, v133, v133
	v_rcp_f32_e32 v84, v84
	v_rcp_f32_e32 v85, v85
	v_max_f32_e32 v132, 0x1e3ce508, v132
	v_max_f32_e32 v133, 0x1e3ce508, v133
	v_rcp_f32_e32 v132, v132
	v_rcp_f32_e32 v133, v133
	v_pk_mul_f32 v[74:75], v[86:87], v[142:143]
	s_waitcnt vmcnt(2)
	v_lshlrev_b32_e32 v86, 16, v138
	v_and_b32_e32 v87, 0xffff0000, v138
	v_pk_mul_f32 v[84:85], v[84:85], v[86:87]
	v_lshlrev_b32_e32 v86, 16, v139
	v_and_b32_e32 v87, 0xffff0000, v139
	v_lshlrev_b32_e32 v152, 11, v176
	v_pk_mul_f32 v[86:87], v[132:133], v[86:87]
	v_add_u32_e32 v133, v152, v177
	global_load_dwordx4 v[136:139], v133, s[8:9]
	v_add_u32_e32 v154, 0xa8000, v175
	v_lshlrev_b32_e32 v132, 16, v134
	v_and_b32_e32 v133, 0xffff0000, v134
	v_add_lshl_u32 v134, v154, v166, 1
	global_load_dwordx4 v[142:145], v134, s[18:19]
	v_lshlrev_b32_e32 v134, 16, v135
	v_and_b32_e32 v135, 0xffff0000, v135
	v_max_f32_e32 v134, v134, v134
	v_max_f32_e32 v135, v135, v135
	v_max_f32_e32 v134, 0x1e3ce508, v134
	v_max_f32_e32 v135, 0x1e3ce508, v135
	v_max_f32_e32 v132, v132, v132
	v_max_f32_e32 v133, v133, v133
	v_rcp_f32_e32 v134, v134
	v_rcp_f32_e32 v135, v135
	v_max_f32_e32 v132, 0x1e3ce508, v132
	v_max_f32_e32 v133, 0x1e3ce508, v133
	v_rcp_f32_e32 v132, v132
	v_rcp_f32_e32 v133, v133
	v_lshlrev_b32_e32 v150, 16, v140
	v_and_b32_e32 v151, 0xffff0000, v140
	v_lshlrev_b32_e32 v140, 16, v141
	v_and_b32_e32 v141, 0xffff0000, v141
	v_pk_mul_f32 v[134:135], v[134:135], v[140:141]
	v_pk_mul_f32 v[86:87], v[82:83], v[86:87]
	v_pk_mul_f32 v[82:83], v[102:103], v[134:135]
	v_add_u32_e32 v134, v152, v173
	v_pk_mul_f32 v[132:133], v[132:133], v[150:151]
	global_load_dwordx4 v[150:153], v134, s[8:9]
	v_pk_mul_f32 v[84:85], v[80:81], v[84:85]
	v_pk_mul_f32 v[80:81], v[100:101], v[132:133]
	s_waitcnt vmcnt(4)
	v_lshlrev_b32_e32 v100, 16, v146
	v_and_b32_e32 v101, 0xffff0000, v146
	v_max_f32_e32 v100, v100, v100
	v_max_f32_e32 v101, v101, v101
	v_lshlrev_b32_e32 v132, 16, v147
	v_and_b32_e32 v133, 0xffff0000, v147
	v_max_f32_e32 v100, 0x1e3ce508, v100
	v_max_f32_e32 v101, 0x1e3ce508, v101
	v_max_f32_e32 v132, v132, v132
	v_max_f32_e32 v133, v133, v133
	v_rcp_f32_e32 v100, v100
	v_rcp_f32_e32 v101, v101
	v_max_f32_e32 v132, 0x1e3ce508, v132
	v_max_f32_e32 v133, 0x1e3ce508, v133
	v_rcp_f32_e32 v132, v132
	v_rcp_f32_e32 v133, v133
	s_waitcnt vmcnt(3)
	v_lshlrev_b32_e32 v102, 16, v156
	v_and_b32_e32 v103, 0xffff0000, v156
	v_pk_mul_f32 v[100:101], v[100:101], v[102:103]
	v_lshlrev_b32_e32 v102, 16, v157
	v_and_b32_e32 v103, 0xffff0000, v157
	v_pk_mul_f32 v[102:103], v[132:133], v[102:103]
	v_lshlrev_b32_e32 v132, 16, v148
	v_and_b32_e32 v133, 0xffff0000, v148
	v_max_f32_e32 v132, v132, v132
	v_max_f32_e32 v133, v133, v133
	v_max_f32_e32 v132, 0x1e3ce508, v132
	v_max_f32_e32 v133, 0x1e3ce508, v133
	v_rcp_f32_e32 v132, v132
	v_rcp_f32_e32 v133, v133
	v_add_lshl_u32 v141, v154, v171, 1
	v_lshlrev_b32_e32 v134, 16, v158
	v_and_b32_e32 v135, 0xffff0000, v158
	v_lshlrev_b32_e32 v140, 16, v149
	global_load_dwordx4 v[154:157], v141, s[18:19]
	v_and_b32_e32 v141, 0xffff0000, v149
	v_max_f32_e32 v140, v140, v140
	v_max_f32_e32 v141, v141, v141
	v_pk_mul_f32 v[132:133], v[132:133], v[134:135]
	v_max_f32_e32 v140, 0x1e3ce508, v140
	v_max_f32_e32 v141, 0x1e3ce508, v141
	v_pk_mul_f32 v[100:101], v[96:97], v[100:101]
	v_pk_mul_f32 v[96:97], v[116:117], v[132:133]
	v_rcp_f32_e32 v140, v140
	v_rcp_f32_e32 v141, v141
	v_lshlrev_b32_e32 v134, 16, v159
	v_and_b32_e32 v135, 0xffff0000, v159
	s_waitcnt vmcnt(3)
	v_lshlrev_b32_e32 v116, 16, v136
	v_and_b32_e32 v117, 0xffff0000, v136
	v_max_f32_e32 v116, v116, v116
	v_max_f32_e32 v117, v117, v117
	v_lshlrev_b32_e32 v132, 16, v137
	v_and_b32_e32 v133, 0xffff0000, v137
	v_max_f32_e32 v116, 0x1e3ce508, v116
	v_max_f32_e32 v117, 0x1e3ce508, v117
	v_max_f32_e32 v132, v132, v132
	v_max_f32_e32 v133, v133, v133
	v_rcp_f32_e32 v116, v116
	v_rcp_f32_e32 v117, v117
	v_max_f32_e32 v132, 0x1e3ce508, v132
	v_max_f32_e32 v133, 0x1e3ce508, v133
	v_rcp_f32_e32 v132, v132
	v_rcp_f32_e32 v133, v133
	v_pk_mul_f32 v[134:135], v[140:141], v[134:135]
	v_pk_mul_f32 v[102:103], v[98:99], v[102:103]
	v_pk_mul_f32 v[98:99], v[118:119], v[134:135]
	s_waitcnt vmcnt(2)
	v_lshlrev_b32_e32 v118, 16, v142
	v_and_b32_e32 v119, 0xffff0000, v142
	v_pk_mul_f32 v[116:117], v[116:117], v[118:119]
	v_lshlrev_b32_e32 v118, 16, v143
	v_and_b32_e32 v119, 0xffff0000, v143
	v_pk_mul_f32 v[118:119], v[132:133], v[118:119]
	v_lshlrev_b32_e32 v132, 16, v138
	v_max_f32_e32 v132, v132, v132
	v_lshlrev_b32_e32 v148, 11, v178
	v_max_f32_e32 v136, 0x1e3ce508, v132
	v_add_u32_e32 v132, v148, v177
	global_load_dwordx4 v[132:135], v132, s[8:9]
	v_add_u32_e32 v158, 0xbd000, v175
	v_and_b32_e32 v137, 0xffff0000, v138
	v_add_lshl_u32 v138, v158, v166, 1
	global_load_dwordx4 v[140:143], v138, s[18:19]
	v_lshlrev_b32_e32 v138, 16, v139
	v_and_b32_e32 v139, 0xffff0000, v139
	v_max_f32_e32 v138, v138, v138
	v_max_f32_e32 v139, v139, v139
	v_max_f32_e32 v137, v137, v137
	v_max_f32_e32 v138, 0x1e3ce508, v138
	v_max_f32_e32 v139, 0x1e3ce508, v139
	v_max_f32_e32 v137, 0x1e3ce508, v137
	v_rcp_f32_e32 v138, v138
	v_rcp_f32_e32 v139, v139
	v_rcp_f32_e32 v136, v136
	v_rcp_f32_e32 v137, v137
	v_lshlrev_b32_e32 v146, 16, v144
	v_and_b32_e32 v147, 0xffff0000, v144
	v_lshlrev_b32_e32 v144, 16, v145
	v_and_b32_e32 v145, 0xffff0000, v145
	v_pk_mul_f32 v[138:139], v[138:139], v[144:145]
	v_pk_mul_f32 v[136:137], v[136:137], v[146:147]
	v_pk_mul_f32 v[118:119], v[114:115], v[118:119]
	v_pk_mul_f32 v[114:115], v[126:127], v[138:139]
	v_add_u32_e32 v138, v148, v173
	v_pk_mul_f32 v[116:117], v[112:113], v[116:117]
	v_pk_mul_f32 v[112:113], v[124:125], v[136:137]
	s_waitcnt vmcnt(3)
; __device__ __forceinline__ float lo16(unsigned w) { return __uint_as_float(w << 16); }
; __device__ __forceinline__ float hi16(unsigned w) { return __uint_as_float(w & 0xffff0000u); }
;     __device__ __forceinline__ void mid(f32x4 (&acc)[2][2][4][2], const pg8::Unit& u, int wr, int wc, int fr, int fq) const {
;         const int row0 = u.pm * 256 + wr * 64 + fr, col0 = u.pn * 256 + wc * 32 + 8 * fq;
; #pragma unroll
;         for (int ai = 0; ai < 2; ++ai)
; #pragma unroll
;             for (int m = 0; m < 4; ++m) { const int row = row0 + ai * 128 + m * 16;
; #pragma unroll
;                 for (int bj = 0; bj < 2; ++bj) { const int col = col0 + bj * 128;
;                     const u32x4 aw = *(const u32x4*)((const char*)gA + (unsigned)(row * DM + col) * 2u), bw = *(const u32x4*)((const char*)gB + (unsigned)(row * NMAIN + col) * 2u);
;                     f32x4 r0, r1;
;                     r0[0] = lo16(bw.x) * __builtin_amdgcn_rcpf(fmaxf(lo16(aw.x), 1e-20f)); r0[1] = hi16(bw.x) * __builtin_amdgcn_rcpf(fmaxf(hi16(aw.x), 1e-20f));
;                     r0[2] = lo16(bw.y) * __builtin_amdgcn_rcpf(fmaxf(lo16(aw.y), 1e-20f)); r0[3] = hi16(bw.y) * __builtin_amdgcn_rcpf(fmaxf(hi16(aw.y), 1e-20f));
;                     r1[0] = lo16(bw.z) * __builtin_amdgcn_rcpf(fmaxf(lo16(aw.z), 1e-20f)); r1[1] = hi16(bw.z) * __builtin_amdgcn_rcpf(fmaxf(hi16(aw.z), 1e-20f));
;                     r1[2] = lo16(bw.w) * __builtin_amdgcn_rcpf(fmaxf(lo16(aw.w), 1e-20f)); r1[3] = hi16(bw.w) * __builtin_amdgcn_rcpf(fmaxf(hi16(aw.w), 1e-20f));
;                     acc[ai][bj][m][0] *= r0; acc[ai][bj][m][1] *= r1;
;                     asm volatile("" ::: "memory"); } }
;     }
	v_lshlrev_b32_e32 v124, 16, v150
	v_and_b32_e32 v125, 0xffff0000, v150
	v_lshlrev_b32_e32 v136, 16, v151
	v_and_b32_e32 v137, 0xffff0000, v151
	global_load_dwordx4 v[148:151], v138, s[8:9]
	v_add_lshl_u32 v145, v158, v171, 1
	global_load_dwordx4 v[158:161], v145, s[18:19]
	v_max_f32_e32 v124, v124, v124
	v_max_f32_e32 v125, v125, v125
	v_max_f32_e32 v124, 0x1e3ce508, v124
	v_max_f32_e32 v125, 0x1e3ce508, v125
	v_max_f32_e32 v136, v136, v136
	v_max_f32_e32 v137, v137, v137
	v_rcp_f32_e32 v124, v124
	v_rcp_f32_e32 v125, v125
	v_max_f32_e32 v136, 0x1e3ce508, v136
	v_max_f32_e32 v137, 0x1e3ce508, v137
	v_rcp_f32_e32 v136, v136
	v_rcp_f32_e32 v137, v137
	s_waitcnt vmcnt(4)
	v_lshlrev_b32_e32 v126, 16, v154
	v_and_b32_e32 v127, 0xffff0000, v154
	v_pk_mul_f32 v[124:125], v[124:125], v[126:127]
	v_lshlrev_b32_e32 v126, 16, v155
	v_and_b32_e32 v127, 0xffff0000, v155
	v_pk_mul_f32 v[126:127], v[136:137], v[126:127]
	v_lshlrev_b32_e32 v136, 16, v152
	v_and_b32_e32 v137, 0xffff0000, v152
	v_max_f32_e32 v136, v136, v136
	v_max_f32_e32 v137, v137, v137
	v_max_f32_e32 v136, 0x1e3ce508, v136
	v_max_f32_e32 v137, 0x1e3ce508, v137
	v_rcp_f32_e32 v136, v136
	v_rcp_f32_e32 v137, v137
	v_lshlrev_b32_e32 v138, 16, v156
	v_and_b32_e32 v139, 0xffff0000, v156
	v_lshlrev_b32_e32 v144, 16, v153
	v_and_b32_e32 v145, 0xffff0000, v153
	v_max_f32_e32 v144, v144, v144
	v_max_f32_e32 v145, v145, v145
	v_pk_mul_f32 v[136:137], v[136:137], v[138:139]
	v_max_f32_e32 v144, 0x1e3ce508, v144
	v_max_f32_e32 v145, 0x1e3ce508, v145
	v_pk_mul_f32 v[124:125], v[120:121], v[124:125]
	v_pk_mul_f32 v[120:121], v[128:129], v[136:137]
	v_rcp_f32_e32 v144, v144
	v_rcp_f32_e32 v145, v145
	v_lshlrev_b32_e32 v138, 16, v157
	v_and_b32_e32 v139, 0xffff0000, v157
	v_pk_mul_f32 v[126:127], v[122:123], v[126:127]
	v_pk_mul_f32 v[138:139], v[144:145], v[138:139]
	v_add_u32_e32 v152, 0xa0, v168
	s_waitcnt vmcnt(3)
	v_lshlrev_b32_e32 v128, 16, v132
	v_and_b32_e32 v129, 0xffff0000, v132
	v_max_f32_e32 v128, v128, v128
	v_max_f32_e32 v129, v129, v129
	v_lshlrev_b32_e32 v132, 16, v133
	v_and_b32_e32 v133, 0xffff0000, v133
	v_max_f32_e32 v128, 0x1e3ce508, v128
	v_max_f32_e32 v129, 0x1e3ce508, v129
	v_max_f32_e32 v132, v132, v132
	v_max_f32_e32 v133, v133, v133
	v_rcp_f32_e32 v128, v128
	v_rcp_f32_e32 v129, v129
	v_max_f32_e32 v132, 0x1e3ce508, v132
	v_max_f32_e32 v133, 0x1e3ce508, v133
	v_rcp_f32_e32 v132, v132
	v_rcp_f32_e32 v133, v133
	v_pk_mul_f32 v[122:123], v[130:131], v[138:139]
	s_waitcnt vmcnt(2)
	v_lshlrev_b32_e32 v130, 16, v140
	v_and_b32_e32 v131, 0xffff0000, v140
	v_pk_mul_f32 v[128:129], v[128:129], v[130:131]
	v_lshlrev_b32_e32 v130, 16, v141
	v_and_b32_e32 v131, 0xffff0000, v141
	v_lshlrev_b32_e32 v153, 11, v152
	v_pk_mul_f32 v[130:131], v[132:133], v[130:131]
	v_add_u32_e32 v133, v153, v177
	v_lshlrev_b32_e32 v132, 16, v134
	global_load_dwordx4 v[136:139], v133, s[8:9]
	v_and_b32_e32 v133, 0xffff0000, v134
	v_max_f32_e32 v132, v132, v132
	v_max_f32_e32 v133, v133, v133
	v_max_f32_e32 v132, 0x1e3ce508, v132
	v_max_f32_e32 v133, 0x1e3ce508, v133
	v_rcp_f32_e32 v132, v132
	v_rcp_f32_e32 v133, v133
	v_add_u32_e32 v156, 0xd2000, v175
	v_add_lshl_u32 v134, v156, v166, 1
	global_load_dwordx4 v[144:147], v134, s[18:19]
	v_lshlrev_b32_e32 v140, 16, v142
	v_and_b32_e32 v141, 0xffff0000, v142
	v_lshlrev_b32_e32 v134, 16, v135
	v_and_b32_e32 v135, 0xffff0000, v135
	v_max_f32_e32 v134, v134, v134
	v_max_f32_e32 v135, v135, v135
	v_pk_mul_f32 v[132:133], v[132:133], v[140:141]
	v_max_f32_e32 v134, 0x1e3ce508, v134
	v_max_f32_e32 v135, 0x1e3ce508, v135
	v_pk_mul_f32 v[128:129], v[104:105], v[128:129]
	v_pk_mul_f32 v[104:105], v[108:109], v[132:133]
	s_waitcnt vmcnt(3)
	v_lshlrev_b32_e32 v108, 16, v148
	v_and_b32_e32 v109, 0xffff0000, v148
	v_rcp_f32_e32 v134, v134
	v_rcp_f32_e32 v135, v135
	v_max_f32_e32 v108, v108, v108
	v_max_f32_e32 v109, v109, v109
	v_lshlrev_b32_e32 v132, 16, v149
	v_and_b32_e32 v133, 0xffff0000, v149
	v_max_f32_e32 v108, 0x1e3ce508, v108
	v_max_f32_e32 v109, 0x1e3ce508, v109
	v_max_f32_e32 v132, v132, v132
	v_max_f32_e32 v133, v133, v133
	v_rcp_f32_e32 v108, v108
	v_rcp_f32_e32 v109, v109
	v_max_f32_e32 v132, 0x1e3ce508, v132
	v_max_f32_e32 v133, 0x1e3ce508, v133
	v_lshlrev_b32_e32 v140, 16, v143
	v_and_b32_e32 v141, 0xffff0000, v143
	v_rcp_f32_e32 v132, v132
	v_rcp_f32_e32 v133, v133
	v_pk_mul_f32 v[134:135], v[134:135], v[140:141]
	v_pk_mul_f32 v[130:131], v[106:107], v[130:131]
	v_pk_mul_f32 v[106:107], v[110:111], v[134:135]
	s_waitcnt vmcnt(2)
	v_lshlrev_b32_e32 v110, 16, v158
	v_and_b32_e32 v111, 0xffff0000, v158
	v_pk_mul_f32 v[108:109], v[108:109], v[110:111]
	v_lshlrev_b32_e32 v110, 16, v159
	v_and_b32_e32 v111, 0xffff0000, v159
	v_pk_mul_f32 v[110:111], v[132:133], v[110:111]
	v_lshlrev_b32_e32 v132, 16, v150
	v_max_f32_e32 v132, v132, v132
	v_max_f32_e32 v132, 0x1e3ce508, v132
	v_rcp_f32_e32 v148, v132
	v_add_u32_e32 v132, v153, v173
	global_load_dwordx4 v[132:135], v132, s[8:9]
	v_and_b32_e32 v140, 0xffff0000, v150
	v_max_f32_e32 v140, v140, v140
	v_max_f32_e32 v140, 0x1e3ce508, v140
	v_rcp_f32_e32 v149, v140
	v_add_lshl_u32 v140, v156, v171, 1
	global_load_dwordx4 v[140:143], v140, s[18:19]
	v_lshlrev_b32_e32 v154, 16, v160
	v_and_b32_e32 v155, 0xffff0000, v160
	v_lshlrev_b32_e32 v150, 16, v151
	v_and_b32_e32 v151, 0xffff0000, v151
	v_max_f32_e32 v150, v150, v150
	v_max_f32_e32 v151, v151, v151
	v_pk_mul_f32 v[148:149], v[148:149], v[154:155]
	v_max_f32_e32 v150, 0x1e3ce508, v150
	v_max_f32_e32 v151, 0x1e3ce508, v151
	v_pk_mul_f32 v[108:109], v[88:89], v[108:109]
	v_pk_mul_f32 v[88:89], v[92:93], v[148:149]
	v_rcp_f32_e32 v150, v150
	v_rcp_f32_e32 v151, v151
	v_lshlrev_b32_e32 v154, 16, v161
	v_and_b32_e32 v155, 0xffff0000, v161
	v_pk_mul_f32 v[110:111], v[90:91], v[110:111]
	s_waitcnt vmcnt(3)
; __device__ __forceinline__ float lo16(unsigned w) { return __uint_as_float(w << 16); }
; __device__ __forceinline__ float hi16(unsigned w) { return __uint_as_float(w & 0xffff0000u); }
;     __device__ __forceinline__ void mid(f32x4 (&acc)[2][2][4][2], const pg8::Unit& u, int wr, int wc, int fr, int fq) const {
;         const int row0 = u.pm * 256 + wr * 64 + fr, col0 = u.pn * 256 + wc * 32 + 8 * fq;
; #pragma unroll
;         for (int ai = 0; ai < 2; ++ai)
; #pragma unroll
;             for (int m = 0; m < 4; ++m) { const int row = row0 + ai * 128 + m * 16;
; #pragma unroll
;                 for (int bj = 0; bj < 2; ++bj) { const int col = col0 + bj * 128;
;                     const u32x4 aw = *(const u32x4*)((const char*)gA + (unsigned)(row * DM + col) * 2u), bw = *(const u32x4*)((const char*)gB + (unsigned)(row * NMAIN + col) * 2u);
;                     f32x4 r0, r1;
;                     r0[0] = lo16(bw.x) * __builtin_amdgcn_rcpf(fmaxf(lo16(aw.x), 1e-20f)); r0[1] = hi16(bw.x) * __builtin_amdgcn_rcpf(fmaxf(hi16(aw.x), 1e-20f));
;                     r0[2] = lo16(bw.y) * __builtin_amdgcn_rcpf(fmaxf(lo16(aw.y), 1e-20f)); r0[3] = hi16(bw.y) * __builtin_amdgcn_rcpf(fmaxf(hi16(aw.y), 1e-20f));
;                     r1[0] = lo16(bw.z) * __builtin_amdgcn_rcpf(fmaxf(lo16(aw.z), 1e-20f)); r1[1] = hi16(bw.z) * __builtin_amdgcn_rcpf(fmaxf(hi16(aw.z), 1e-20f));
;                     r1[2] = lo16(bw.w) * __builtin_amdgcn_rcpf(fmaxf(lo16(aw.w), 1e-20f)); r1[3] = hi16(bw.w) * __builtin_amdgcn_rcpf(fmaxf(hi16(aw.w), 1e-20f));
;                     acc[ai][bj][m][0] *= r0; acc[ai][bj][m][1] *= r1;
;                     asm volatile("" ::: "memory"); } }
;     }
	v_lshlrev_b32_e32 v92, 16, v136
	v_and_b32_e32 v93, 0xffff0000, v136
	v_max_f32_e32 v92, v92, v92
	v_max_f32_e32 v93, v93, v93
	v_lshlrev_b32_e32 v136, 16, v137
	v_and_b32_e32 v137, 0xffff0000, v137
	v_max_f32_e32 v92, 0x1e3ce508, v92
	v_max_f32_e32 v93, 0x1e3ce508, v93
	v_max_f32_e32 v136, v136, v136
	v_max_f32_e32 v137, v137, v137
	v_rcp_f32_e32 v92, v92
	v_rcp_f32_e32 v93, v93
	v_max_f32_e32 v136, 0x1e3ce508, v136
	v_max_f32_e32 v137, 0x1e3ce508, v137
	v_rcp_f32_e32 v136, v136
	v_rcp_f32_e32 v137, v137
	v_pk_mul_f32 v[150:151], v[150:151], v[154:155]
	s_waitcnt vmcnt(2)
	v_lshlrev_b32_e32 v158, 16, v146
	v_pk_mul_f32 v[90:91], v[94:95], v[150:151]
	v_lshlrev_b32_e32 v94, 16, v144
	v_and_b32_e32 v95, 0xffff0000, v144
	v_pk_mul_f32 v[92:93], v[92:93], v[94:95]
	v_lshlrev_b32_e32 v94, 16, v145
	v_and_b32_e32 v95, 0xffff0000, v145
	v_pk_mul_f32 v[94:95], v[136:137], v[94:95]
	v_lshlrev_b32_e32 v136, 16, v138
	v_max_f32_e32 v136, v136, v136
	v_max_f32_e32 v137, 0x1e3ce508, v136
	v_add_u32_e32 v136, 0xb0, v168
	v_lshlrev_b32_e32 v153, 11, v136
	v_add_u32_e32 v144, v153, v177
	global_load_dwordx4 v[148:151], v144, s[8:9]
	v_rcp_f32_e32 v144, v137
	v_and_b32_e32 v137, 0xffff0000, v138
	v_max_f32_e32 v137, v137, v137
	v_max_f32_e32 v137, 0x1e3ce508, v137
	v_rcp_f32_e32 v145, v137
	v_add_u32_e32 v137, 0xe7000, v175
	v_add_lshl_u32 v138, v137, v166, 1
	global_load_dwordx4 v[154:157], v138, s[18:19]
	v_pk_mul_f32 v[68:69], v[68:69], v[92:93]
	v_lshlrev_b32_e32 v138, 16, v139
	v_and_b32_e32 v139, 0xffff0000, v139
	v_max_f32_e32 v138, v138, v138
	v_max_f32_e32 v139, v139, v139
	v_max_f32_e32 v138, 0x1e3ce508, v138
	v_max_f32_e32 v139, 0x1e3ce508, v139
	v_rcp_f32_e32 v138, v138
	v_rcp_f32_e32 v139, v139
	v_pk_mul_f32 v[70:71], v[70:71], v[94:95]
	v_and_b32_e32 v159, 0xffff0000, v146
	v_pk_mul_f32 v[144:145], v[144:145], v[158:159]
	v_lshlrev_b32_e32 v146, 16, v147
	v_and_b32_e32 v147, 0xffff0000, v147
	v_pk_mul_f32 v[138:139], v[138:139], v[146:147]
	s_waitcnt vmcnt(3)
	v_lshlrev_b32_e32 v92, 16, v132
	v_and_b32_e32 v93, 0xffff0000, v132
	v_max_f32_e32 v92, v92, v92
	v_max_f32_e32 v93, v93, v93
	v_max_f32_e32 v92, 0x1e3ce508, v92
	v_max_f32_e32 v93, 0x1e3ce508, v93
	v_rcp_f32_e32 v92, v92
	v_rcp_f32_e32 v93, v93
	s_waitcnt vmcnt(2)
	v_lshlrev_b32_e32 v94, 16, v140
	v_and_b32_e32 v95, 0xffff0000, v140
	v_add_u32_e32 v132, v153, v173
	v_pk_mul_f32 v[92:93], v[92:93], v[94:95]
	v_lshlrev_b32_e32 v94, 16, v133
	v_and_b32_e32 v95, 0xffff0000, v133
	v_max_f32_e32 v94, v94, v94
	v_max_f32_e32 v95, v95, v95
	v_pk_mul_f32 v[64:65], v[64:65], v[144:145]
	v_max_f32_e32 v94, 0x1e3ce508, v94
	v_max_f32_e32 v95, 0x1e3ce508, v95
	global_load_dwordx4 v[144:147], v132, s[8:9]
	v_rcp_f32_e32 v94, v94
	v_rcp_f32_e32 v95, v95
	v_lshlrev_b32_e32 v132, 16, v141
	v_and_b32_e32 v133, 0xffff0000, v141
	v_pk_mul_f32 v[66:67], v[66:67], v[138:139]
	v_pk_mul_f32 v[94:95], v[94:95], v[132:133]
	v_add_lshl_u32 v133, v137, v171, 1
	global_load_dwordx4 v[138:141], v133, s[18:19]
	v_lshlrev_b32_e32 v132, 16, v134
	v_and_b32_e32 v133, 0xffff0000, v134
	v_max_f32_e32 v132, v132, v132
	v_max_f32_e32 v133, v133, v133
	v_max_f32_e32 v132, 0x1e3ce508, v132
	v_max_f32_e32 v133, 0x1e3ce508, v133
	v_rcp_f32_e32 v132, v132
	v_rcp_f32_e32 v133, v133
	v_lshlrev_b32_e32 v158, 16, v142
	v_and_b32_e32 v159, 0xffff0000, v142
	v_pk_mul_f32 v[92:93], v[40:41], v[92:93]
	v_pk_mul_f32 v[132:133], v[132:133], v[158:159]
	v_lshlrev_b32_e32 v134, 16, v135
	v_pk_mul_f32 v[44:45], v[44:45], v[132:133]
	v_and_b32_e32 v135, 0xffff0000, v135
	v_pk_mul_f32 v[94:95], v[42:43], v[94:95]
	v_max_f32_e32 v134, v134, v134
	v_max_f32_e32 v135, v135, v135
	v_max_f32_e32 v134, 0x1e3ce508, v134
	v_max_f32_e32 v135, 0x1e3ce508, v135
	v_rcp_f32_e32 v134, v134
	v_rcp_f32_e32 v135, v135
	v_lshlrev_b32_e32 v142, 16, v143
	v_and_b32_e32 v143, 0xffff0000, v143
	v_pk_mul_f32 v[134:135], v[134:135], v[142:143]
	s_waitcnt vmcnt(3)
	v_lshlrev_b32_e32 v40, 16, v148
	v_and_b32_e32 v41, 0xffff0000, v148
	v_max_f32_e32 v40, v40, v40
	v_max_f32_e32 v41, v41, v41
	v_lshlrev_b32_e32 v132, 16, v149
	v_and_b32_e32 v133, 0xffff0000, v149
	v_max_f32_e32 v40, 0x1e3ce508, v40
	v_max_f32_e32 v41, 0x1e3ce508, v41
	v_max_f32_e32 v132, v132, v132
	v_max_f32_e32 v133, v133, v133
	v_rcp_f32_e32 v40, v40
	v_rcp_f32_e32 v41, v41
	v_max_f32_e32 v132, 0x1e3ce508, v132
	v_max_f32_e32 v133, 0x1e3ce508, v133
	v_rcp_f32_e32 v132, v132
	v_rcp_f32_e32 v133, v133
	s_waitcnt vmcnt(2)
	v_lshlrev_b32_e32 v42, 16, v154
	v_and_b32_e32 v43, 0xffff0000, v154
	v_pk_mul_f32 v[40:41], v[40:41], v[42:43]
	v_lshlrev_b32_e32 v42, 16, v155
	v_and_b32_e32 v43, 0xffff0000, v155
	v_pk_mul_f32 v[42:43], v[132:133], v[42:43]
	v_lshlrev_b32_e32 v132, 16, v150
	v_and_b32_e32 v133, 0xffff0000, v150
	v_max_f32_e32 v132, v132, v132
	v_max_f32_e32 v133, v133, v133
	v_max_f32_e32 v132, 0x1e3ce508, v132
	v_max_f32_e32 v133, 0x1e3ce508, v133
	v_rcp_f32_e32 v132, v132
	v_rcp_f32_e32 v133, v133
	v_lshlrev_b32_e32 v137, 16, v151
	v_max_f32_e32 v137, v137, v137
	v_max_f32_e32 v137, 0x1e3ce508, v137
	v_pk_mul_f32 v[46:47], v[46:47], v[134:135]
	v_lshlrev_b32_e32 v134, 16, v156
	v_and_b32_e32 v135, 0xffff0000, v156
	v_rcp_f32_e32 v142, v137
	v_and_b32_e32 v137, 0xffff0000, v151
	v_max_f32_e32 v137, v137, v137
	v_pk_mul_f32 v[132:133], v[132:133], v[134:135]
	v_max_f32_e32 v137, 0x1e3ce508, v137
	v_pk_mul_f32 v[40:41], v[32:33], v[40:41]
	v_pk_mul_f32 v[32:33], v[36:37], v[132:133]
	v_rcp_f32_e32 v143, v137
	s_waitcnt vmcnt(1)
; __device__ __forceinline__ float lo16(unsigned w) { return __uint_as_float(w << 16); }
; __device__ __forceinline__ float hi16(unsigned w) { return __uint_as_float(w & 0xffff0000u); }
;     __device__ __forceinline__ void mid(f32x4 (&acc)[2][2][4][2], const pg8::Unit& u, int wr, int wc, int fr, int fq) const {
;     ...
;                     const u32x4 aw = *(const u32x4*)((const char*)gA + (unsigned)(row * DM + col) * 2u), bw = *(const u32x4*)((const char*)gB + (unsigned)(row * NMAIN + col) * 2u);
;                     f32x4 r0, r1;
;                     r0[0] = lo16(bw.x) * __builtin_amdgcn_rcpf(fmaxf(lo16(aw.x), 1e-20f)); r0[1] = hi16(bw.x) * __builtin_amdgcn_rcpf(fmaxf(hi16(aw.x), 1e-20f));
;                     r0[2] = lo16(bw.y) * __builtin_amdgcn_rcpf(fmaxf(lo16(aw.y), 1e-20f)); r0[3] = hi16(bw.y) * __builtin_amdgcn_rcpf(fmaxf(hi16(aw.y), 1e-20f));
;                     r1[0] = lo16(bw.z) * __builtin_amdgcn_rcpf(fmaxf(lo16(aw.z), 1e-20f)); r1[1] = hi16(bw.z) * __builtin_amdgcn_rcpf(fmaxf(hi16(aw.z), 1e-20f));
;                     r1[2] = lo16(bw.w) * __builtin_amdgcn_rcpf(fmaxf(lo16(aw.w), 1e-20f)); r1[3] = hi16(bw.w) * __builtin_amdgcn_rcpf(fmaxf(hi16(aw.w), 1e-20f));
;                     acc[ai][bj][m][0] *= r0; acc[ai][bj][m][1] *= r1;
	v_lshlrev_b32_e32 v36, 16, v144
	v_and_b32_e32 v37, 0xffff0000, v144
	v_max_f32_e32 v36, v36, v36
	v_max_f32_e32 v37, v37, v37
	v_lshlrev_b32_e32 v132, 16, v145
	v_and_b32_e32 v133, 0xffff0000, v145
	v_max_f32_e32 v36, 0x1e3ce508, v36
	v_max_f32_e32 v37, 0x1e3ce508, v37
	v_max_f32_e32 v132, v132, v132
	v_max_f32_e32 v133, v133, v133
	v_rcp_f32_e32 v36, v36
	v_rcp_f32_e32 v37, v37
	v_max_f32_e32 v132, 0x1e3ce508, v132
	v_max_f32_e32 v133, 0x1e3ce508, v133
	v_lshlrev_b32_e32 v134, 16, v157
	v_and_b32_e32 v135, 0xffff0000, v157
	v_rcp_f32_e32 v132, v132
	v_rcp_f32_e32 v133, v133
	v_pk_mul_f32 v[134:135], v[142:143], v[134:135]
	v_pk_mul_f32 v[42:43], v[34:35], v[42:43]
	v_pk_mul_f32 v[34:35], v[38:39], v[134:135]
	s_waitcnt vmcnt(0)
	v_lshlrev_b32_e32 v38, 16, v138
	v_and_b32_e32 v39, 0xffff0000, v138
	v_lshlrev_b32_e32 v137, 16, v147
	v_pk_mul_f32 v[36:37], v[36:37], v[38:39]
	v_lshlrev_b32_e32 v38, 16, v139
	v_and_b32_e32 v39, 0xffff0000, v139
	v_max_f32_e32 v137, v137, v137
	v_pk_mul_f32 v[38:39], v[132:133], v[38:39]
	v_lshlrev_b32_e32 v132, 16, v146
	v_and_b32_e32 v133, 0xffff0000, v146
	v_max_f32_e32 v137, 0x1e3ce508, v137
	v_max_f32_e32 v132, v132, v132
	v_max_f32_e32 v133, v133, v133
	v_rcp_f32_e32 v138, v137
	v_and_b32_e32 v137, 0xffff0000, v147
	v_max_f32_e32 v132, 0x1e3ce508, v132
	v_max_f32_e32 v133, 0x1e3ce508, v133
	v_max_f32_e32 v137, v137, v137
	v_rcp_f32_e32 v132, v132
	v_rcp_f32_e32 v133, v133
	v_max_f32_e32 v137, 0x1e3ce508, v137
	v_rcp_f32_e32 v139, v137
	v_lshlrev_b32_e32 v134, 16, v140
	v_and_b32_e32 v135, 0xffff0000, v140
	v_pk_mul_f32 v[132:133], v[132:133], v[134:135]
	v_lshlrev_b32_e32 v134, 16, v141
	v_and_b32_e32 v135, 0xffff0000, v141
	v_pk_mul_f32 v[134:135], v[138:139], v[134:135]
	v_pk_mul_f32 v[22:23], v[22:23], v[38:39]
	v_pk_mul_f32 v[20:21], v[20:21], v[36:37]
	v_pk_mul_f32 v[18:19], v[18:19], v[134:135]
	v_pk_mul_f32 v[16:17], v[16:17], v[132:133]
.LBB0_599:
	ds_read_b128 v[36:39], v195
	ds_read_b128 v[132:135], v195 offset:1024
	ds_read_b128 v[138:141], v195 offset:2048
	ds_read_b128 v[142:145], v195 offset:3072
	ds_read_b128 v[146:149], v196
	ds_read_b128 v[154:157], v196 offset:1024
	ds_read_b128 v[158:161], v196 offset:2048
	ds_read_b128 v[198:201], v196 offset:3072
	s_add_i32 s52, s44, 0xffeb0080
	s_cmp_eq_u32 s51, 16
	s_cselect_b32 s54, s50, s52
	s_cselect_b32 s53, s49, s43
	s_or_b32 s52, s54, 0x80
	v_add_u32_e32 v137, s44, v194
	s_mov_b32 m0, s0
	ds_read_b128 v[202:205], v191
	ds_read_b128 v[206:209], v191 offset:1024
	ds_read_b128 v[210:213], v191 offset:2048
	ds_read_b128 v[214:217], v191 offset:3072
	ds_read_b128 v[218:221], v191 offset:4096
	ds_read_b128 v[222:225], v191 offset:5120
	ds_read_b128 v[226:229], v191 offset:6144
	ds_read_b128 v[230:233], v191 offset:7168
	s_nop 0
	global_load_lds_dwordx4 v137, s[12:13]
	v_add_u32_e32 v137, s44, v193
	s_mov_b32 m0, s1
	s_nop 0
	global_load_lds_dwordx4 v137, s[12:13]
	s_waitcnt vmcnt(8)
	s_waitcnt lgkmcnt(0)
	s_barrier
	s_waitcnt lgkmcnt(0)
	v_mfma_f32_16x16x32_bf16 v[4:7], v[36:39], v[202:205], v[4:7]
	v_mfma_f32_16x16x32_bf16 v[0:3], v[138:141], v[202:205], v[0:3]
	v_mfma_f32_16x16x32_bf16 v[28:31], v[36:39], v[210:213], v[28:31]
	v_mfma_f32_16x16x32_bf16 v[24:27], v[138:141], v[210:213], v[24:27]
	v_mfma_f32_16x16x32_bf16 v[60:63], v[36:39], v[218:221], v[60:63]
	v_mfma_f32_16x16x32_bf16 v[56:59], v[138:141], v[218:221], v[56:59]
	v_mfma_f32_16x16x32_bf16 v[84:87], v[36:39], v[226:229], v[84:87]
	v_mfma_f32_16x16x32_bf16 v[80:83], v[138:141], v[226:229], v[80:83]
	v_mfma_f32_16x16x32_bf16 v[4:7], v[132:135], v[206:209], v[4:7]
	v_mfma_f32_16x16x32_bf16 v[0:3], v[142:145], v[206:209], v[0:3]
	v_mfma_f32_16x16x32_bf16 v[28:31], v[132:135], v[214:217], v[28:31]
	v_mfma_f32_16x16x32_bf16 v[24:27], v[142:145], v[214:217], v[24:27]
	v_mfma_f32_16x16x32_bf16 v[60:63], v[132:135], v[222:225], v[60:63]
	v_mfma_f32_16x16x32_bf16 v[56:59], v[142:145], v[222:225], v[56:59]
	v_mfma_f32_16x16x32_bf16 v[84:87], v[132:135], v[230:233], v[84:87]
	v_mfma_f32_16x16x32_bf16 v[80:83], v[142:145], v[230:233], v[80:83]
	v_mfma_f32_16x16x32_bf16 v[12:15], v[146:149], v[202:205], v[12:15]
	v_mfma_f32_16x16x32_bf16 v[8:11], v[158:161], v[202:205], v[8:11]
	v_mfma_f32_16x16x32_bf16 v[52:55], v[146:149], v[210:213], v[52:55]
	v_mfma_f32_16x16x32_bf16 v[48:51], v[158:161], v[210:213], v[48:51]
	v_mfma_f32_16x16x32_bf16 v[76:79], v[146:149], v[218:221], v[76:79]
	v_mfma_f32_16x16x32_bf16 v[72:75], v[158:161], v[218:221], v[72:75]
	v_mfma_f32_16x16x32_bf16 v[100:103], v[146:149], v[226:229], v[100:103]
	v_mfma_f32_16x16x32_bf16 v[96:99], v[158:161], v[226:229], v[96:99]
	v_mfma_f32_16x16x32_bf16 v[12:15], v[154:157], v[206:209], v[12:15]
	v_mfma_f32_16x16x32_bf16 v[8:11], v[198:201], v[206:209], v[8:11]
	v_mfma_f32_16x16x32_bf16 v[52:55], v[154:157], v[214:217], v[52:55]
	v_mfma_f32_16x16x32_bf16 v[48:51], v[198:201], v[214:217], v[48:51]
	v_mfma_f32_16x16x32_bf16 v[76:79], v[154:157], v[222:225], v[76:79]
	v_mfma_f32_16x16x32_bf16 v[72:75], v[198:201], v[222:225], v[72:75]
	v_mfma_f32_16x16x32_bf16 v[100:103], v[154:157], v[230:233], v[100:103]
	v_mfma_f32_16x16x32_bf16 v[96:99], v[198:201], v[230:233], v[96:99]
	s_barrier
	v_add_u32_e32 v137, s53, v181
	s_mov_b32 m0, s39
	ds_read_b128 v[202:205], v191 offset:16384
	ds_read_b128 v[206:209], v191 offset:17408
	ds_read_b128 v[210:213], v191 offset:18432
	ds_read_b128 v[214:217], v191 offset:19456
	ds_read_b128 v[218:221], v191 offset:20480
	ds_read_b128 v[222:225], v191 offset:21504
	ds_read_b128 v[226:229], v191 offset:22528
	ds_read_b128 v[230:233], v191 offset:23552
	s_add_i32 s55, s53, 0x50000
	global_load_lds_dwordx4 v137, s[14:15]
	v_add_u32_e32 v137, s53, v183
	s_mov_b32 m0, s40
	s_nop 0
	global_load_lds_dwordx4 v137, s[14:15]
	v_add_u32_e32 v137, s55, v181
	s_mov_b32 m0, s41
	s_nop 0
	global_load_lds_dwordx4 v137, s[14:15]
	v_add_u32_e32 v137, s55, v183
	s_mov_b32 m0, s42
	s_nop 0
	global_load_lds_dwordx4 v137, s[14:15]
	v_add_u32_e32 v137, s54, v180
	s_mov_b32 m0, s23
	s_nop 0
	global_load_lds_dwordx4 v137, s[12:13]
	v_add_u32_e32 v137, s54, v182
	s_mov_b32 m0, s24
	s_nop 0
	global_load_lds_dwordx4 v137, s[12:13]
	s_waitcnt vmcnt(8)
	s_waitcnt lgkmcnt(0)
	s_barrier
	s_waitcnt lgkmcnt(0)
	v_mfma_f32_16x16x32_bf16 v[116:119], v[36:39], v[202:205], v[116:119]
	v_mfma_f32_16x16x32_bf16 v[112:115], v[138:141], v[202:205], v[112:115]
	v_mfma_f32_16x16x32_bf16 v[128:131], v[36:39], v[210:213], v[128:131]
	v_mfma_f32_16x16x32_bf16 v[104:107], v[138:141], v[210:213], v[104:107]
	v_mfma_f32_16x16x32_bf16 v[68:71], v[36:39], v[218:221], v[68:71]
	v_mfma_f32_16x16x32_bf16 v[64:67], v[138:141], v[218:221], v[64:67]
	v_mfma_f32_16x16x32_bf16 v[32:35], v[138:141], v[226:229], v[32:35]
	v_mfma_f32_16x16x32_bf16 v[116:119], v[132:135], v[206:209], v[116:119]
	v_mfma_f32_16x16x32_bf16 v[112:115], v[142:145], v[206:209], v[112:115]
	v_mfma_f32_16x16x32_bf16 v[128:131], v[132:135], v[214:217], v[128:131]
	v_mfma_f32_16x16x32_bf16 v[104:107], v[142:145], v[214:217], v[104:107]
	v_mfma_f32_16x16x32_bf16 v[68:71], v[132:135], v[222:225], v[68:71]
	v_mfma_f32_16x16x32_bf16 v[64:67], v[142:145], v[222:225], v[64:67]
	v_mfma_f32_16x16x32_bf16 v[36:39], v[36:39], v[226:229], v[40:43]
	v_mfma_f32_16x16x32_bf16 v[32:35], v[142:145], v[230:233], v[32:35]
	v_mfma_f32_16x16x32_bf16 v[36:39], v[132:135], v[230:233], v[36:39]
	v_mfma_f32_16x16x32_bf16 v[40:43], v[146:149], v[202:205], v[124:127]
	v_mfma_f32_16x16x32_bf16 v[124:127], v[154:157], v[206:209], v[40:43]
	v_mfma_f32_16x16x32_bf16 v[40:43], v[158:161], v[202:205], v[120:123]
	v_mfma_f32_16x16x32_bf16 v[120:123], v[198:201], v[206:209], v[40:43]
	v_mfma_f32_16x16x32_bf16 v[40:43], v[146:149], v[210:213], v[108:111]
	v_mfma_f32_16x16x32_bf16 v[108:111], v[154:157], v[214:217], v[40:43]
	v_mfma_f32_16x16x32_bf16 v[40:43], v[158:161], v[210:213], v[88:91]
	v_mfma_f32_16x16x32_bf16 v[88:91], v[198:201], v[214:217], v[40:43]
	v_mfma_f32_16x16x32_bf16 v[40:43], v[146:149], v[218:221], v[92:95]
	v_mfma_f32_16x16x32_bf16 v[92:95], v[154:157], v[222:225], v[40:43]
	v_mfma_f32_16x16x32_bf16 v[40:43], v[158:161], v[218:221], v[44:47]
	v_mfma_f32_16x16x32_bf16 v[20:23], v[146:149], v[226:229], v[20:23]
	v_mfma_f32_16x16x32_bf16 v[16:19], v[158:161], v[226:229], v[16:19]
	v_mfma_f32_16x16x32_bf16 v[44:47], v[198:201], v[222:225], v[40:43]
	v_mfma_f32_16x16x32_bf16 v[20:23], v[154:157], v[230:233], v[20:23]
	v_mfma_f32_16x16x32_bf16 v[16:19], v[198:201], v[230:233], v[16:19]
	s_barrier
	s_nop 0
	ds_read_b128 v[40:43], v167
	ds_read_b128 v[132:135], v167 offset:1024
	ds_read_b128 v[138:141], v167 offset:2048
	ds_read_b128 v[142:145], v167 offset:3072
	ds_read_b128 v[146:149], v169
	ds_read_b128 v[154:157], v169 offset:1024
	ds_read_b128 v[158:161], v169 offset:2048
	ds_read_b128 v[198:201], v169 offset:3072
	s_add_i32 s54, s54, 0x150000
	v_add_u32_e32 v137, s54, v180
	s_mov_b32 m0, s25
	ds_read_b128 v[202:205], v191 offset:32768
	ds_read_b128 v[206:209], v191 offset:33792
	ds_read_b128 v[210:213], v191 offset:34816
	ds_read_b128 v[214:217], v191 offset:35840
	ds_read_b128 v[218:221], v191 offset:36864
	ds_read_b128 v[222:225], v191 offset:37888
	ds_read_b128 v[226:229], v191 offset:38912
	ds_read_b128 v[230:233], v191 offset:39936
	s_nop 0
	global_load_lds_dwordx4 v137, s[12:13]
	v_add_u32_e32 v137, s54, v182
	s_mov_b32 m0, s26
	s_nop 0
	global_load_lds_dwordx4 v137, s[12:13]
	s_waitcnt vmcnt(8)
	s_waitcnt lgkmcnt(0)
	s_barrier
; #define PG8_BAR __builtin_amdgcn_s_barrier()
;     ...
;         if constexpr (ALIGN_EPI) { if (wr == 0) PG8_BAR; }
	s_waitcnt lgkmcnt(0)
	v_mfma_f32_16x16x32_bf16 v[4:7], v[40:43], v[202:205], v[4:7]
	v_mfma_f32_16x16x32_bf16 v[0:3], v[138:141], v[202:205], v[0:3]
	v_mfma_f32_16x16x32_bf16 v[28:31], v[40:43], v[210:213], v[28:31]
	v_mfma_f32_16x16x32_bf16 v[24:27], v[138:141], v[210:213], v[24:27]
	v_mfma_f32_16x16x32_bf16 v[60:63], v[40:43], v[218:221], v[60:63]
	v_mfma_f32_16x16x32_bf16 v[56:59], v[138:141], v[218:221], v[56:59]
	v_mfma_f32_16x16x32_bf16 v[84:87], v[40:43], v[226:229], v[84:87]
	v_mfma_f32_16x16x32_bf16 v[80:83], v[138:141], v[226:229], v[80:83]
	v_mfma_f32_16x16x32_bf16 v[4:7], v[132:135], v[206:209], v[4:7]
	v_mfma_f32_16x16x32_bf16 v[0:3], v[142:145], v[206:209], v[0:3]
	v_mfma_f32_16x16x32_bf16 v[28:31], v[132:135], v[214:217], v[28:31]
	v_mfma_f32_16x16x32_bf16 v[24:27], v[142:145], v[214:217], v[24:27]
	v_mfma_f32_16x16x32_bf16 v[60:63], v[132:135], v[222:225], v[60:63]
	v_mfma_f32_16x16x32_bf16 v[56:59], v[142:145], v[222:225], v[56:59]
	v_mfma_f32_16x16x32_bf16 v[84:87], v[132:135], v[230:233], v[84:87]
	v_mfma_f32_16x16x32_bf16 v[80:83], v[142:145], v[230:233], v[80:83]
	v_mfma_f32_16x16x32_bf16 v[12:15], v[146:149], v[202:205], v[12:15]
	v_mfma_f32_16x16x32_bf16 v[8:11], v[158:161], v[202:205], v[8:11]
	v_mfma_f32_16x16x32_bf16 v[52:55], v[146:149], v[210:213], v[52:55]
	v_mfma_f32_16x16x32_bf16 v[48:51], v[158:161], v[210:213], v[48:51]
	v_mfma_f32_16x16x32_bf16 v[76:79], v[146:149], v[218:221], v[76:79]
	v_mfma_f32_16x16x32_bf16 v[72:75], v[158:161], v[218:221], v[72:75]
	v_mfma_f32_16x16x32_bf16 v[100:103], v[146:149], v[226:229], v[100:103]
	v_mfma_f32_16x16x32_bf16 v[96:99], v[158:161], v[226:229], v[96:99]
	v_mfma_f32_16x16x32_bf16 v[12:15], v[154:157], v[206:209], v[12:15]
	v_mfma_f32_16x16x32_bf16 v[8:11], v[198:201], v[206:209], v[8:11]
	v_mfma_f32_16x16x32_bf16 v[52:55], v[154:157], v[214:217], v[52:55]
	v_mfma_f32_16x16x32_bf16 v[48:51], v[198:201], v[214:217], v[48:51]
	v_mfma_f32_16x16x32_bf16 v[76:79], v[154:157], v[222:225], v[76:79]
	v_mfma_f32_16x16x32_bf16 v[72:75], v[198:201], v[222:225], v[72:75]
	v_mfma_f32_16x16x32_bf16 v[100:103], v[154:157], v[230:233], v[100:103]
	v_mfma_f32_16x16x32_bf16 v[96:99], v[198:201], v[230:233], v[96:99]
	s_barrier
	s_or_b32 s54, s53, 0x80
	v_add_u32_e32 v137, s54, v181
	s_mov_b32 m0, s45
	ds_read_b128 v[202:205], v191 offset:49152
	ds_read_b128 v[206:209], v191 offset:50176
	ds_read_b128 v[210:213], v191 offset:51200
	ds_read_b128 v[214:217], v191 offset:52224
	ds_read_b128 v[218:221], v191 offset:53248
	ds_read_b128 v[222:225], v191 offset:54272
	ds_read_b128 v[226:229], v191 offset:55296
	ds_read_b128 v[230:233], v191 offset:56320
	s_add_i32 s53, s53, 0x50080
	global_load_lds_dwordx4 v137, s[14:15]
	v_add_u32_e32 v137, s54, v183
	s_mov_b32 m0, s46
	s_nop 0
	global_load_lds_dwordx4 v137, s[14:15]
	v_add_u32_e32 v137, s53, v181
	s_mov_b32 m0, s47
	s_nop 0
	global_load_lds_dwordx4 v137, s[14:15]
	v_add_u32_e32 v137, s53, v183
	s_mov_b32 m0, s48
	s_nop 0
	global_load_lds_dwordx4 v137, s[14:15]
	v_add_u32_e32 v137, s52, v180
	s_mov_b32 m0, s28
	s_nop 0
	global_load_lds_dwordx4 v137, s[12:13]
	v_add_u32_e32 v137, s52, v182
	s_mov_b32 m0, s29
	s_nop 0
	global_load_lds_dwordx4 v137, s[12:13]
	s_waitcnt vmcnt(8)
	s_waitcnt lgkmcnt(0)
	s_barrier
	s_waitcnt lgkmcnt(0)
	v_mfma_f32_16x16x32_bf16 v[116:119], v[40:43], v[202:205], v[116:119]
	v_mfma_f32_16x16x32_bf16 v[112:115], v[138:141], v[202:205], v[112:115]
	v_mfma_f32_16x16x32_bf16 v[128:131], v[40:43], v[210:213], v[128:131]
	v_mfma_f32_16x16x32_bf16 v[104:107], v[138:141], v[210:213], v[104:107]
	v_mfma_f32_16x16x32_bf16 v[68:71], v[40:43], v[218:221], v[68:71]
	v_mfma_f32_16x16x32_bf16 v[64:67], v[138:141], v[218:221], v[64:67]
	v_mfma_f32_16x16x32_bf16 v[36:39], v[40:43], v[226:229], v[36:39]
	v_mfma_f32_16x16x32_bf16 v[32:35], v[138:141], v[226:229], v[32:35]
	v_mfma_f32_16x16x32_bf16 v[116:119], v[132:135], v[206:209], v[116:119]
	v_mfma_f32_16x16x32_bf16 v[112:115], v[142:145], v[206:209], v[112:115]
	v_mfma_f32_16x16x32_bf16 v[128:131], v[132:135], v[214:217], v[128:131]
	v_mfma_f32_16x16x32_bf16 v[104:107], v[142:145], v[214:217], v[104:107]
	v_mfma_f32_16x16x32_bf16 v[68:71], v[132:135], v[222:225], v[68:71]
	v_mfma_f32_16x16x32_bf16 v[64:67], v[142:145], v[222:225], v[64:67]
	v_mfma_f32_16x16x32_bf16 v[40:43], v[132:135], v[230:233], v[36:39]
	v_mfma_f32_16x16x32_bf16 v[32:35], v[142:145], v[230:233], v[32:35]
	v_mfma_f32_16x16x32_bf16 v[36:39], v[146:149], v[202:205], v[124:127]
	v_mfma_f32_16x16x32_bf16 v[124:127], v[154:157], v[206:209], v[36:39]
	v_mfma_f32_16x16x32_bf16 v[36:39], v[158:161], v[202:205], v[120:123]
	v_mfma_f32_16x16x32_bf16 v[120:123], v[198:201], v[206:209], v[36:39]
	v_mfma_f32_16x16x32_bf16 v[36:39], v[146:149], v[210:213], v[108:111]
	v_mfma_f32_16x16x32_bf16 v[108:111], v[154:157], v[214:217], v[36:39]
	v_mfma_f32_16x16x32_bf16 v[36:39], v[158:161], v[210:213], v[88:91]
	v_mfma_f32_16x16x32_bf16 v[88:91], v[198:201], v[214:217], v[36:39]
	v_mfma_f32_16x16x32_bf16 v[36:39], v[146:149], v[218:221], v[92:95]
	v_mfma_f32_16x16x32_bf16 v[92:95], v[154:157], v[222:225], v[36:39]
	v_mfma_f32_16x16x32_bf16 v[36:39], v[158:161], v[218:221], v[44:47]
	v_mfma_f32_16x16x32_bf16 v[20:23], v[146:149], v[226:229], v[20:23]
	v_mfma_f32_16x16x32_bf16 v[16:19], v[158:161], v[226:229], v[16:19]
	v_mfma_f32_16x16x32_bf16 v[44:47], v[198:201], v[222:225], v[36:39]
	v_mfma_f32_16x16x32_bf16 v[20:23], v[154:157], v[230:233], v[20:23]
	v_mfma_f32_16x16x32_bf16 v[16:19], v[198:201], v[230:233], v[16:19]
	s_barrier
	s_add_i32 s51, s51, 2
	s_addk_i32 s44, 0x100
	s_addk_i32 s43, 0x100
	s_cmp_gt_u32 s51, 17
	s_cbranch_scc0 .LBB0_599
	s_and_b64 vcc, exec, s[20:21]
	s_cbranch_vccz .LBB0_602
	s_barrier

.LBB0_674:
	v_add_u32_e32 v154, s36, v136
	v_add_u32_e32 v170, s37, v136
	ds_read_b128 v[142:145], v154
	ds_read_b128 v[146:149], v154 offset:1024
	ds_read_b128 v[150:153], v154 offset:2048
	ds_read_b128 v[154:157], v154 offset:3072
	ds_read_b128 v[158:161], v170
	ds_read_b128 v[162:165], v170 offset:1024
	ds_read_b128 v[166:169], v170 offset:2048
	ds_read_b128 v[170:173], v170 offset:3072
	s_add_i32 s45, s28, s44
	s_add_i32 s46, s27, s44
	s_cmp_eq_u32 s43, 12
	s_cselect_b32 s47, s41, s45
	s_cselect_b32 s46, s42, s46
	s_or_b32 s45, s47, 0x80
	v_add_u32_e32 v185, s44, v141
	v_add_u32_e32 v185, 0x3ff80, v185
	ds_read_b128 v[174:177], v139
	ds_read_b128 v[178:181], v139 offset:1024
	ds_read_b128 v[192:195], v139 offset:2048
	ds_read_b128 v[196:199], v139 offset:3072
	ds_read_b128 v[200:203], v139 offset:4096
	ds_read_b128 v[204:207], v139 offset:5120
	ds_read_b128 v[208:211], v139 offset:6144
	ds_read_b128 v[212:215], v139 offset:7168
	s_add_i32 m0, s26, 0xc000
	s_nop 0
	global_load_lds_dwordx4 v185, s[10:11]
	v_add_u32_e32 v185, s44, v140
	v_add_u32_e32 v185, 0x3ff80, v185
	s_add_i32 m0, s26, 0xe000
	s_nop 0
	global_load_lds_dwordx4 v185, s[10:11]
	s_waitcnt vmcnt(8)
	s_waitcnt lgkmcnt(0)
	s_barrier
	s_waitcnt lgkmcnt(0)
	v_mfma_f32_16x16x32_bf16 v[124:127], v[142:145], v[174:177], v[124:127]
	v_mfma_f32_16x16x32_bf16 v[120:123], v[150:153], v[174:177], v[120:123]
	v_mfma_f32_16x16x32_bf16 v[108:111], v[142:145], v[192:195], v[108:111]
	v_mfma_f32_16x16x32_bf16 v[104:107], v[150:153], v[192:195], v[104:107]
	v_mfma_f32_16x16x32_bf16 v[92:95], v[142:145], v[200:203], v[92:95]
	v_mfma_f32_16x16x32_bf16 v[88:91], v[150:153], v[200:203], v[88:91]
	v_mfma_f32_16x16x32_bf16 v[76:79], v[142:145], v[208:211], v[76:79]
	v_mfma_f32_16x16x32_bf16 v[72:75], v[150:153], v[208:211], v[72:75]
	v_mfma_f32_16x16x32_bf16 v[124:127], v[146:149], v[178:181], v[124:127]
	v_mfma_f32_16x16x32_bf16 v[120:123], v[154:157], v[178:181], v[120:123]
	v_mfma_f32_16x16x32_bf16 v[108:111], v[146:149], v[196:199], v[108:111]
	v_mfma_f32_16x16x32_bf16 v[104:107], v[154:157], v[196:199], v[104:107]
	v_mfma_f32_16x16x32_bf16 v[92:95], v[146:149], v[204:207], v[92:95]
	v_mfma_f32_16x16x32_bf16 v[88:91], v[154:157], v[204:207], v[88:91]
	v_mfma_f32_16x16x32_bf16 v[76:79], v[146:149], v[212:215], v[76:79]
	v_mfma_f32_16x16x32_bf16 v[72:75], v[154:157], v[212:215], v[72:75]
	v_mfma_f32_16x16x32_bf16 v[116:119], v[158:161], v[174:177], v[116:119]
	v_mfma_f32_16x16x32_bf16 v[112:115], v[166:169], v[174:177], v[112:115]
	v_mfma_f32_16x16x32_bf16 v[100:103], v[158:161], v[192:195], v[100:103]
	v_mfma_f32_16x16x32_bf16 v[96:99], v[166:169], v[192:195], v[96:99]
	v_mfma_f32_16x16x32_bf16 v[84:87], v[158:161], v[200:203], v[84:87]
	v_mfma_f32_16x16x32_bf16 v[80:83], v[166:169], v[200:203], v[80:83]
	v_mfma_f32_16x16x32_bf16 v[68:71], v[158:161], v[208:211], v[68:71]
	v_mfma_f32_16x16x32_bf16 v[64:67], v[166:169], v[208:211], v[64:67]
	v_mfma_f32_16x16x32_bf16 v[116:119], v[162:165], v[178:181], v[116:119]
	v_mfma_f32_16x16x32_bf16 v[112:115], v[170:173], v[178:181], v[112:115]
	v_mfma_f32_16x16x32_bf16 v[100:103], v[162:165], v[196:199], v[100:103]
	v_mfma_f32_16x16x32_bf16 v[96:99], v[170:173], v[196:199], v[96:99]
	v_mfma_f32_16x16x32_bf16 v[84:87], v[162:165], v[204:207], v[84:87]
	v_mfma_f32_16x16x32_bf16 v[80:83], v[170:173], v[204:207], v[80:83]
	v_mfma_f32_16x16x32_bf16 v[68:71], v[162:165], v[212:215], v[68:71]
	v_mfma_f32_16x16x32_bf16 v[64:67], v[170:173], v[212:215], v[64:67]
	s_barrier
	v_add_u32_e32 v185, s46, v133
	s_add_i32 s48, s36, s25
	ds_read_b128 v[174:177], v139 offset:16384
	ds_read_b128 v[178:181], v139 offset:17408
	ds_read_b128 v[192:195], v139 offset:18432
	ds_read_b128 v[196:199], v139 offset:19456
	ds_read_b128 v[200:203], v139 offset:20480
	ds_read_b128 v[204:207], v139 offset:21504
	ds_read_b128 v[208:211], v139 offset:22528
	ds_read_b128 v[212:215], v139 offset:23552
	s_mov_b32 m0, s48
	s_add_i32 s49, s37, s25
	global_load_lds_dwordx4 v185, s[0:1]
	v_add_u32_e32 v185, s46, v135
	s_add_i32 m0, s48, 0x2000
	s_add_i32 s48, s46, 0x40000
	global_load_lds_dwordx4 v185, s[0:1]
	v_add_u32_e32 v185, s48, v133
	s_mov_b32 m0, s49
	s_nop 0
	global_load_lds_dwordx4 v185, s[0:1]
	v_add_u32_e32 v185, s48, v135
	s_add_i32 m0, s49, 0x2000
	s_nop 0
	global_load_lds_dwordx4 v185, s[0:1]
	v_add_u32_e32 v185, s47, v132
	s_mov_b32 m0, s26
	s_nop 0
	global_load_lds_dwordx4 v185, s[10:11]
	v_add_u32_e32 v185, s47, v134
	s_mov_b32 m0, s29
	s_nop 0
	global_load_lds_dwordx4 v185, s[10:11]
	s_waitcnt vmcnt(8)
	s_waitcnt lgkmcnt(0)
	s_barrier
	s_waitcnt lgkmcnt(0)
	v_mfma_f32_16x16x32_bf16 v[60:63], v[142:145], v[174:177], v[60:63]
	v_mfma_f32_16x16x32_bf16 v[56:59], v[150:153], v[174:177], v[56:59]
	v_mfma_f32_16x16x32_bf16 v[44:47], v[142:145], v[192:195], v[44:47]
	v_mfma_f32_16x16x32_bf16 v[40:43], v[150:153], v[192:195], v[40:43]
	v_mfma_f32_16x16x32_bf16 v[28:31], v[142:145], v[200:203], v[28:31]
	v_mfma_f32_16x16x32_bf16 v[24:27], v[150:153], v[200:203], v[24:27]
	v_mfma_f32_16x16x32_bf16 v[12:15], v[142:145], v[208:211], v[12:15]
	v_mfma_f32_16x16x32_bf16 v[8:11], v[150:153], v[208:211], v[8:11]
	v_mfma_f32_16x16x32_bf16 v[60:63], v[146:149], v[178:181], v[60:63]
	v_mfma_f32_16x16x32_bf16 v[56:59], v[154:157], v[178:181], v[56:59]
	v_mfma_f32_16x16x32_bf16 v[44:47], v[146:149], v[196:199], v[44:47]
	v_mfma_f32_16x16x32_bf16 v[40:43], v[154:157], v[196:199], v[40:43]
	v_mfma_f32_16x16x32_bf16 v[28:31], v[146:149], v[204:207], v[28:31]
	v_mfma_f32_16x16x32_bf16 v[24:27], v[154:157], v[204:207], v[24:27]
	v_mfma_f32_16x16x32_bf16 v[12:15], v[146:149], v[212:215], v[12:15]
	v_mfma_f32_16x16x32_bf16 v[8:11], v[154:157], v[212:215], v[8:11]
	v_mfma_f32_16x16x32_bf16 v[52:55], v[158:161], v[174:177], v[52:55]
	v_mfma_f32_16x16x32_bf16 v[48:51], v[166:169], v[174:177], v[48:51]
	v_mfma_f32_16x16x32_bf16 v[36:39], v[158:161], v[192:195], v[36:39]
	v_mfma_f32_16x16x32_bf16 v[32:35], v[166:169], v[192:195], v[32:35]
	v_mfma_f32_16x16x32_bf16 v[20:23], v[158:161], v[200:203], v[20:23]
	v_mfma_f32_16x16x32_bf16 v[16:19], v[166:169], v[200:203], v[16:19]
	v_mfma_f32_16x16x32_bf16 v[4:7], v[158:161], v[208:211], v[4:7]
	v_mfma_f32_16x16x32_bf16 v[0:3], v[166:169], v[208:211], v[0:3]
	v_mfma_f32_16x16x32_bf16 v[52:55], v[162:165], v[178:181], v[52:55]
	v_mfma_f32_16x16x32_bf16 v[48:51], v[170:173], v[178:181], v[48:51]
	v_mfma_f32_16x16x32_bf16 v[36:39], v[162:165], v[196:199], v[36:39]
	v_mfma_f32_16x16x32_bf16 v[32:35], v[170:173], v[196:199], v[32:35]
	v_mfma_f32_16x16x32_bf16 v[20:23], v[162:165], v[204:207], v[20:23]
	v_mfma_f32_16x16x32_bf16 v[16:19], v[170:173], v[204:207], v[16:19]
	v_mfma_f32_16x16x32_bf16 v[4:7], v[162:165], v[212:215], v[4:7]
	v_mfma_f32_16x16x32_bf16 v[0:3], v[170:173], v[212:215], v[0:3]
	s_barrier
	s_add_i32 s48, 0, 0x18000
	s_add_i32 s49, 0, 0x1c000
	v_add_u32_e32 v154, s48, v136
	v_add_u32_e32 v170, s49, v136
	ds_read_b128 v[142:145], v154
	ds_read_b128 v[146:149], v154 offset:1024
	ds_read_b128 v[150:153], v154 offset:2048
	ds_read_b128 v[154:157], v154 offset:3072
	ds_read_b128 v[158:161], v170
	ds_read_b128 v[162:165], v170 offset:1024
	ds_read_b128 v[166:169], v170 offset:2048
	ds_read_b128 v[170:173], v170 offset:3072
	s_add_i32 s47, s47, 0x40000
	v_add_u32_e32 v185, s47, v132
	s_mov_b32 m0, s30
	ds_read_b128 v[174:177], v139 offset:32768
	ds_read_b128 v[178:181], v139 offset:33792
	ds_read_b128 v[192:195], v139 offset:34816
	ds_read_b128 v[196:199], v139 offset:35840
	ds_read_b128 v[200:203], v139 offset:36864
	ds_read_b128 v[204:207], v139 offset:37888
	ds_read_b128 v[208:211], v139 offset:38912
	ds_read_b128 v[212:215], v139 offset:39936
	s_nop 0
	global_load_lds_dwordx4 v185, s[10:11]
	v_add_u32_e32 v185, s47, v134
	s_mov_b32 m0, s31
	s_nop 0
	global_load_lds_dwordx4 v185, s[10:11]
	s_waitcnt vmcnt(8)
	s_waitcnt lgkmcnt(0)
	s_barrier
	s_waitcnt lgkmcnt(0)
	v_mfma_f32_16x16x32_bf16 v[124:127], v[142:145], v[174:177], v[124:127]
	v_mfma_f32_16x16x32_bf16 v[120:123], v[150:153], v[174:177], v[120:123]
	v_mfma_f32_16x16x32_bf16 v[108:111], v[142:145], v[192:195], v[108:111]
	v_mfma_f32_16x16x32_bf16 v[104:107], v[150:153], v[192:195], v[104:107]
	v_mfma_f32_16x16x32_bf16 v[92:95], v[142:145], v[200:203], v[92:95]
	v_mfma_f32_16x16x32_bf16 v[88:91], v[150:153], v[200:203], v[88:91]
	v_mfma_f32_16x16x32_bf16 v[76:79], v[142:145], v[208:211], v[76:79]
	v_mfma_f32_16x16x32_bf16 v[72:75], v[150:153], v[208:211], v[72:75]
	v_mfma_f32_16x16x32_bf16 v[124:127], v[146:149], v[178:181], v[124:127]
	v_mfma_f32_16x16x32_bf16 v[120:123], v[154:157], v[178:181], v[120:123]
	v_mfma_f32_16x16x32_bf16 v[108:111], v[146:149], v[196:199], v[108:111]
	v_mfma_f32_16x16x32_bf16 v[104:107], v[154:157], v[196:199], v[104:107]
	v_mfma_f32_16x16x32_bf16 v[92:95], v[146:149], v[204:207], v[92:95]
	v_mfma_f32_16x16x32_bf16 v[88:91], v[154:157], v[204:207], v[88:91]
	v_mfma_f32_16x16x32_bf16 v[76:79], v[146:149], v[212:215], v[76:79]
	v_mfma_f32_16x16x32_bf16 v[72:75], v[154:157], v[212:215], v[72:75]
	v_mfma_f32_16x16x32_bf16 v[116:119], v[158:161], v[174:177], v[116:119]
	v_mfma_f32_16x16x32_bf16 v[112:115], v[166:169], v[174:177], v[112:115]
	v_mfma_f32_16x16x32_bf16 v[100:103], v[158:161], v[192:195], v[100:103]
	v_mfma_f32_16x16x32_bf16 v[96:99], v[166:169], v[192:195], v[96:99]
	v_mfma_f32_16x16x32_bf16 v[84:87], v[158:161], v[200:203], v[84:87]
	v_mfma_f32_16x16x32_bf16 v[80:83], v[166:169], v[200:203], v[80:83]
	v_mfma_f32_16x16x32_bf16 v[68:71], v[158:161], v[208:211], v[68:71]
	v_mfma_f32_16x16x32_bf16 v[64:67], v[166:169], v[208:211], v[64:67]
	v_mfma_f32_16x16x32_bf16 v[116:119], v[162:165], v[178:181], v[116:119]
	v_mfma_f32_16x16x32_bf16 v[112:115], v[170:173], v[178:181], v[112:115]
	v_mfma_f32_16x16x32_bf16 v[100:103], v[162:165], v[196:199], v[100:103]
	v_mfma_f32_16x16x32_bf16 v[96:99], v[170:173], v[196:199], v[96:99]
	v_mfma_f32_16x16x32_bf16 v[84:87], v[162:165], v[204:207], v[84:87]
	v_mfma_f32_16x16x32_bf16 v[80:83], v[170:173], v[204:207], v[80:83]
	v_mfma_f32_16x16x32_bf16 v[68:71], v[162:165], v[212:215], v[68:71]
	v_mfma_f32_16x16x32_bf16 v[64:67], v[170:173], v[212:215], v[64:67]
	s_barrier
;     ...
;         if (!has_next) break;
; #pragma unroll
;         for (int a = 0; a < 2; ++a)
; #pragma unroll
;             for (int b = 0; b < 2; ++b)
; #pragma unroll
;                 for (int m = 0; m < 4; ++m)
; #pragma unroll
;                     for (int n = 0; n < 2; ++n) acc[a][b][m][n] = (f32x4){0.f, 0.f, 0.f, 0.f};
;         cur = nxt; cA = nA; cB = nB; ++ui;
	s_or_b32 s47, s46, 0x80
	v_add_u32_e32 v185, s47, v133
	s_add_i32 s48, s48, s25
	ds_read_b128 v[174:177], v139 offset:49152
	ds_read_b128 v[178:181], v139 offset:50176
	ds_read_b128 v[192:195], v139 offset:51200
	ds_read_b128 v[196:199], v139 offset:52224
	ds_read_b128 v[200:203], v139 offset:53248
	ds_read_b128 v[204:207], v139 offset:54272
	ds_read_b128 v[208:211], v139 offset:55296
	ds_read_b128 v[212:215], v139 offset:56320
	s_mov_b32 m0, s48
	s_add_i32 s46, s46, 0x40080
	global_load_lds_dwordx4 v185, s[0:1]
	v_add_u32_e32 v185, s47, v135
	s_add_i32 m0, s48, 0x2000
	s_add_i32 s47, s49, s25
	global_load_lds_dwordx4 v185, s[0:1]
	v_add_u32_e32 v185, s46, v133
	s_mov_b32 m0, s47
	s_nop 0
	global_load_lds_dwordx4 v185, s[0:1]
	v_add_u32_e32 v185, s46, v135
	s_add_i32 m0, s47, 0x2000
	s_nop 0
	global_load_lds_dwordx4 v185, s[0:1]
	v_add_u32_e32 v185, s45, v132
	s_mov_b32 m0, s33
	s_nop 0
	global_load_lds_dwordx4 v185, s[10:11]
	v_add_u32_e32 v185, s45, v134
	s_mov_b32 m0, s34
	s_nop 0
	global_load_lds_dwordx4 v185, s[10:11]
	s_waitcnt vmcnt(8)
	s_waitcnt lgkmcnt(0)
	s_barrier
	s_waitcnt lgkmcnt(0)
	v_mfma_f32_16x16x32_bf16 v[60:63], v[142:145], v[174:177], v[60:63]
	v_mfma_f32_16x16x32_bf16 v[56:59], v[150:153], v[174:177], v[56:59]
	v_mfma_f32_16x16x32_bf16 v[44:47], v[142:145], v[192:195], v[44:47]
	v_mfma_f32_16x16x32_bf16 v[40:43], v[150:153], v[192:195], v[40:43]
	v_mfma_f32_16x16x32_bf16 v[28:31], v[142:145], v[200:203], v[28:31]
	v_mfma_f32_16x16x32_bf16 v[24:27], v[150:153], v[200:203], v[24:27]
	v_mfma_f32_16x16x32_bf16 v[12:15], v[142:145], v[208:211], v[12:15]
	v_mfma_f32_16x16x32_bf16 v[8:11], v[150:153], v[208:211], v[8:11]
	v_mfma_f32_16x16x32_bf16 v[60:63], v[146:149], v[178:181], v[60:63]
	v_mfma_f32_16x16x32_bf16 v[56:59], v[154:157], v[178:181], v[56:59]
	v_mfma_f32_16x16x32_bf16 v[44:47], v[146:149], v[196:199], v[44:47]
	v_mfma_f32_16x16x32_bf16 v[40:43], v[154:157], v[196:199], v[40:43]
	v_mfma_f32_16x16x32_bf16 v[28:31], v[146:149], v[204:207], v[28:31]
	v_mfma_f32_16x16x32_bf16 v[24:27], v[154:157], v[204:207], v[24:27]
	v_mfma_f32_16x16x32_bf16 v[12:15], v[146:149], v[212:215], v[12:15]
	v_mfma_f32_16x16x32_bf16 v[8:11], v[154:157], v[212:215], v[8:11]
	v_mfma_f32_16x16x32_bf16 v[52:55], v[158:161], v[174:177], v[52:55]
	v_mfma_f32_16x16x32_bf16 v[48:51], v[166:169], v[174:177], v[48:51]
	v_mfma_f32_16x16x32_bf16 v[36:39], v[158:161], v[192:195], v[36:39]
	v_mfma_f32_16x16x32_bf16 v[32:35], v[166:169], v[192:195], v[32:35]
	v_mfma_f32_16x16x32_bf16 v[20:23], v[158:161], v[200:203], v[20:23]
	v_mfma_f32_16x16x32_bf16 v[16:19], v[166:169], v[200:203], v[16:19]
	v_mfma_f32_16x16x32_bf16 v[4:7], v[158:161], v[208:211], v[4:7]
	v_mfma_f32_16x16x32_bf16 v[0:3], v[166:169], v[208:211], v[0:3]
	v_mfma_f32_16x16x32_bf16 v[52:55], v[162:165], v[178:181], v[52:55]
	v_mfma_f32_16x16x32_bf16 v[48:51], v[170:173], v[178:181], v[48:51]
	v_mfma_f32_16x16x32_bf16 v[36:39], v[162:165], v[196:199], v[36:39]
	v_mfma_f32_16x16x32_bf16 v[32:35], v[170:173], v[196:199], v[32:35]
	v_mfma_f32_16x16x32_bf16 v[20:23], v[162:165], v[204:207], v[20:23]
	v_mfma_f32_16x16x32_bf16 v[16:19], v[170:173], v[204:207], v[16:19]
	v_mfma_f32_16x16x32_bf16 v[4:7], v[162:165], v[212:215], v[4:7]
	v_mfma_f32_16x16x32_bf16 v[0:3], v[170:173], v[212:215], v[0:3]
	s_barrier
	s_add_i32 s43, s43, 2
	s_addk_i32 s44, 0x100
	s_cmp_gt_u32 s43, 13
	s_cbranch_scc0 .LBB0_674
	s_andn2_b64 vcc, exec, s[8:9]
	s_cbranch_vccnz .LBB0_666
	v_mov_b32_e32 v0, 0
	s_mov_b32 s16, s38
	s_mov_b32 s21, s39
	s_mov_b32 s27, s3
	s_mov_b32 s28, s2
	s_mov_b32 s35, s40
	v_mov_b32_e32 v1, v0
	v_mov_b32_e32 v2, v0
	v_mov_b32_e32 v3, v0
	v_mov_b32_e32 v4, v0
	v_mov_b32_e32 v5, v0
	v_mov_b32_e32 v6, v0
	v_mov_b32_e32 v7, v0
	v_mov_b32_e32 v16, v0
	v_mov_b32_e32 v17, v0
	v_mov_b32_e32 v18, v0
	v_mov_b32_e32 v19, v0
	v_mov_b32_e32 v20, v0
	v_mov_b32_e32 v21, v0
	v_mov_b32_e32 v22, v0
	v_mov_b32_e32 v23, v0
	v_mov_b32_e32 v32, v0
	v_mov_b32_e32 v33, v0
	v_mov_b32_e32 v34, v0
	v_mov_b32_e32 v35, v0
	v_mov_b32_e32 v36, v0
	v_mov_b32_e32 v37, v0
	v_mov_b32_e32 v38, v0
	v_mov_b32_e32 v39, v0
	v_mov_b32_e32 v48, v0
	v_mov_b32_e32 v49, v0
	v_mov_b32_e32 v50, v0
	v_mov_b32_e32 v51, v0
	v_mov_b32_e32 v52, v0
	v_mov_b32_e32 v53, v0
	v_mov_b32_e32 v54, v0
	v_mov_b32_e32 v55, v0
	v_mov_b32_e32 v8, v0
	v_mov_b32_e32 v9, v0
	v_mov_b32_e32 v10, v0
	v_mov_b32_e32 v11, v0
	v_mov_b32_e32 v12, v0
	v_mov_b32_e32 v13, v0
	v_mov_b32_e32 v14, v0
	v_mov_b32_e32 v15, v0
	v_mov_b32_e32 v24, v0
	v_mov_b32_e32 v25, v0
	v_mov_b32_e32 v26, v0
	v_mov_b32_e32 v27, v0
	v_mov_b32_e32 v28, v0
	v_mov_b32_e32 v29, v0
	v_mov_b32_e32 v30, v0
	v_mov_b32_e32 v31, v0
	v_mov_b32_e32 v40, v0
	v_mov_b32_e32 v41, v0
	v_mov_b32_e32 v42, v0
	v_mov_b32_e32 v43, v0
	v_mov_b32_e32 v44, v0
	v_mov_b32_e32 v45, v0
	v_mov_b32_e32 v46, v0
	v_mov_b32_e32 v47, v0
	v_mov_b32_e32 v56, v0
	v_mov_b32_e32 v57, v0
	v_mov_b32_e32 v58, v0
	v_mov_b32_e32 v59, v0
	v_mov_b32_e32 v60, v0
	v_mov_b32_e32 v61, v0
	v_mov_b32_e32 v62, v0
	v_mov_b32_e32 v63, v0
	v_mov_b32_e32 v64, v0
	v_mov_b32_e32 v65, v0
	v_mov_b32_e32 v66, v0
	v_mov_b32_e32 v67, v0
	v_mov_b32_e32 v68, v0
	v_mov_b32_e32 v69, v0
	v_mov_b32_e32 v70, v0
	v_mov_b32_e32 v71, v0
	v_mov_b32_e32 v80, v0
	v_mov_b32_e32 v81, v0
	v_mov_b32_e32 v82, v0
	v_mov_b32_e32 v83, v0
	v_mov_b32_e32 v84, v0
	v_mov_b32_e32 v85, v0
	v_mov_b32_e32 v86, v0
	v_mov_b32_e32 v87, v0
	v_mov_b32_e32 v96, v0
	v_mov_b32_e32 v97, v0
	v_mov_b32_e32 v98, v0
	v_mov_b32_e32 v99, v0
	v_mov_b32_e32 v100, v0
	v_mov_b32_e32 v101, v0
	v_mov_b32_e32 v102, v0
	v_mov_b32_e32 v103, v0
	v_mov_b32_e32 v112, v0
	v_mov_b32_e32 v113, v0
	v_mov_b32_e32 v114, v0
	v_mov_b32_e32 v115, v0
	v_mov_b32_e32 v116, v0
	v_mov_b32_e32 v117, v0
	v_mov_b32_e32 v118, v0
	v_mov_b32_e32 v119, v0
	v_mov_b32_e32 v72, v0
	v_mov_b32_e32 v73, v0
	v_mov_b32_e32 v74, v0
	v_mov_b32_e32 v75, v0
	v_mov_b32_e32 v76, v0
	v_mov_b32_e32 v77, v0
	v_mov_b32_e32 v78, v0
	v_mov_b32_e32 v79, v0
	v_mov_b32_e32 v88, v0
	v_mov_b32_e32 v89, v0
	v_mov_b32_e32 v90, v0
	v_mov_b32_e32 v91, v0
	v_mov_b32_e32 v92, v0
	v_mov_b32_e32 v93, v0
	v_mov_b32_e32 v94, v0
	v_mov_b32_e32 v95, v0
	v_mov_b32_e32 v104, v0
	v_mov_b32_e32 v105, v0
	v_mov_b32_e32 v106, v0
	v_mov_b32_e32 v107, v0
	v_mov_b32_e32 v108, v0
	v_mov_b32_e32 v109, v0
	v_mov_b32_e32 v110, v0
	v_mov_b32_e32 v111, v0
	v_mov_b32_e32 v120, v0
	v_mov_b32_e32 v121, v0
	v_mov_b32_e32 v122, v0
	v_mov_b32_e32 v123, v0
	v_mov_b32_e32 v124, v0
	v_mov_b32_e32 v125, v0
	v_mov_b32_e32 v126, v0
	v_mov_b32_e32 v127, v0
	s_branch .LBB0_666

.LBB0_780:
	ds_read_b128 v[128:131], v207
	ds_read_b128 v[132:135], v207 offset:1024
	ds_read_b128 v[136:139], v207 offset:2048
	ds_read_b128 v[140:143], v207 offset:3072
	ds_read_b128 v[144:147], v208
	ds_read_b128 v[148:151], v208 offset:1024
	ds_read_b128 v[152:155], v208 offset:2048
	ds_read_b128 v[156:159], v208 offset:3072
	s_add_i32 s12, s2, 0xffffe080
	s_cmp_eq_u32 s11, 12
	s_cselect_b32 s14, s0, s12
	s_cselect_b32 s13, s1, s3
	s_or_b32 s12, s14, 0x80
	v_add_u32_e32 v184, s2, v206
	ds_read_b128 v[164:167], v209
	ds_read_b128 v[168:171], v209 offset:1024
	ds_read_b128 v[172:175], v209 offset:2048
	ds_read_b128 v[176:179], v209 offset:3072
	ds_read_b128 v[180:183], v209 offset:4096
	ds_read_b128 v[210:213], v209 offset:5120
	ds_read_b128 v[214:217], v209 offset:6144
	ds_read_b128 v[218:221], v209 offset:7168
	s_add_i32 m0, s27, 0xc000
	s_nop 0
	global_load_lds_dwordx4 v184, s[22:23]
	v_add_u32_e32 v184, s2, v205
	s_add_i32 m0, s27, 0xe000
	s_nop 0
	global_load_lds_dwordx4 v184, s[22:23]
	s_waitcnt vmcnt(8)
	s_waitcnt lgkmcnt(0)
	s_barrier
	s_waitcnt lgkmcnt(0)
	v_mfma_f32_16x16x32_bf16 v[120:123], v[128:131], v[164:167], v[120:123]
	v_mfma_f32_16x16x32_bf16 v[56:59], v[136:139], v[164:167], v[56:59]
	v_mfma_f32_16x16x32_bf16 v[112:115], v[128:131], v[172:175], v[112:115]
	v_mfma_f32_16x16x32_bf16 v[48:51], v[136:139], v[172:175], v[48:51]
	v_mfma_f32_16x16x32_bf16 v[104:107], v[128:131], v[180:183], v[104:107]
	v_mfma_f32_16x16x32_bf16 v[40:43], v[136:139], v[180:183], v[40:43]
	v_mfma_f32_16x16x32_bf16 v[96:99], v[128:131], v[214:217], v[96:99]
	v_mfma_f32_16x16x32_bf16 v[32:35], v[136:139], v[214:217], v[32:35]
	v_mfma_f32_16x16x32_bf16 v[120:123], v[132:135], v[168:171], v[120:123]
	v_mfma_f32_16x16x32_bf16 v[56:59], v[140:143], v[168:171], v[56:59]
	v_mfma_f32_16x16x32_bf16 v[112:115], v[132:135], v[176:179], v[112:115]
	v_mfma_f32_16x16x32_bf16 v[48:51], v[140:143], v[176:179], v[48:51]
	v_mfma_f32_16x16x32_bf16 v[104:107], v[132:135], v[210:213], v[104:107]
	v_mfma_f32_16x16x32_bf16 v[40:43], v[140:143], v[210:213], v[40:43]
	v_mfma_f32_16x16x32_bf16 v[96:99], v[132:135], v[218:221], v[96:99]
	v_mfma_f32_16x16x32_bf16 v[32:35], v[140:143], v[218:221], v[32:35]
	v_mfma_f32_16x16x32_bf16 v[124:127], v[144:147], v[164:167], v[124:127]
	v_mfma_f32_16x16x32_bf16 v[60:63], v[152:155], v[164:167], v[60:63]
	v_mfma_f32_16x16x32_bf16 v[116:119], v[144:147], v[172:175], v[116:119]
	v_mfma_f32_16x16x32_bf16 v[52:55], v[152:155], v[172:175], v[52:55]
	v_mfma_f32_16x16x32_bf16 v[108:111], v[144:147], v[180:183], v[108:111]
	v_mfma_f32_16x16x32_bf16 v[44:47], v[152:155], v[180:183], v[44:47]
	v_mfma_f32_16x16x32_bf16 v[100:103], v[144:147], v[214:217], v[100:103]
	v_mfma_f32_16x16x32_bf16 v[36:39], v[152:155], v[214:217], v[36:39]
	v_mfma_f32_16x16x32_bf16 v[124:127], v[148:151], v[168:171], v[124:127]
	v_mfma_f32_16x16x32_bf16 v[60:63], v[156:159], v[168:171], v[60:63]
	v_mfma_f32_16x16x32_bf16 v[116:119], v[148:151], v[176:179], v[116:119]
	v_mfma_f32_16x16x32_bf16 v[52:55], v[156:159], v[176:179], v[52:55]
	v_mfma_f32_16x16x32_bf16 v[108:111], v[148:151], v[210:213], v[108:111]
	v_mfma_f32_16x16x32_bf16 v[44:47], v[156:159], v[210:213], v[44:47]
	v_mfma_f32_16x16x32_bf16 v[100:103], v[148:151], v[218:221], v[100:103]
	v_mfma_f32_16x16x32_bf16 v[36:39], v[156:159], v[218:221], v[36:39]
	s_barrier
	v_add_u32_e32 v184, s13, v192
	s_add_i32 s15, s71, s26
	ds_read_b128 v[164:167], v209 offset:16384
	ds_read_b128 v[168:171], v209 offset:17408
	ds_read_b128 v[172:175], v209 offset:18432
	ds_read_b128 v[176:179], v209 offset:19456
	ds_read_b128 v[180:183], v209 offset:20480
	ds_read_b128 v[210:213], v209 offset:21504
	ds_read_b128 v[214:217], v209 offset:22528
	ds_read_b128 v[218:221], v209 offset:23552
	s_mov_b32 m0, s15
	s_add_i32 s16, s72, s26
	global_load_lds_dwordx4 v184, s[36:37]
	v_add_u32_e32 v184, s13, v194
	s_add_i32 m0, s15, 0x2000
	s_add_i32 s15, s13, 0x40000
	global_load_lds_dwordx4 v184, s[36:37]
	v_add_u32_e32 v184, s15, v192
	s_mov_b32 m0, s16
	s_nop 0
	global_load_lds_dwordx4 v184, s[36:37]
	v_add_u32_e32 v184, s15, v194
	s_add_i32 m0, s16, 0x2000
	s_nop 0
	global_load_lds_dwordx4 v184, s[36:37]
	v_add_u32_e32 v184, s14, v191
	s_mov_b32 m0, s27
	s_nop 0
	global_load_lds_dwordx4 v184, s[22:23]
	v_add_u32_e32 v184, s14, v193
	s_mov_b32 m0, s33
	s_nop 0
	global_load_lds_dwordx4 v184, s[22:23]
	s_waitcnt vmcnt(8)
	s_waitcnt lgkmcnt(0)
	s_barrier
	s_waitcnt lgkmcnt(0)
	v_mfma_f32_16x16x32_bf16 v[88:91], v[128:131], v[164:167], v[88:91]
	v_mfma_f32_16x16x32_bf16 v[24:27], v[136:139], v[164:167], v[24:27]
	v_mfma_f32_16x16x32_bf16 v[72:75], v[128:131], v[172:175], v[72:75]
	v_mfma_f32_16x16x32_bf16 v[8:11], v[136:139], v[172:175], v[8:11]
	v_mfma_f32_16x16x32_bf16 v[68:71], v[128:131], v[180:183], v[68:71]
	v_mfma_f32_16x16x32_bf16 v[4:7], v[136:139], v[180:183], v[4:7]
	v_mfma_f32_16x16x32_bf16 v[64:67], v[128:131], v[214:217], v[64:67]
	v_mfma_f32_16x16x32_bf16 v[0:3], v[136:139], v[214:217], v[0:3]
	v_mfma_f32_16x16x32_bf16 v[88:91], v[132:135], v[168:171], v[88:91]
	v_mfma_f32_16x16x32_bf16 v[24:27], v[140:143], v[168:171], v[24:27]
	v_mfma_f32_16x16x32_bf16 v[72:75], v[132:135], v[176:179], v[72:75]
	v_mfma_f32_16x16x32_bf16 v[8:11], v[140:143], v[176:179], v[8:11]
	v_mfma_f32_16x16x32_bf16 v[68:71], v[132:135], v[210:213], v[68:71]
	v_mfma_f32_16x16x32_bf16 v[4:7], v[140:143], v[210:213], v[4:7]
	v_mfma_f32_16x16x32_bf16 v[64:67], v[132:135], v[218:221], v[64:67]
	v_mfma_f32_16x16x32_bf16 v[0:3], v[140:143], v[218:221], v[0:3]
	v_mfma_f32_16x16x32_bf16 v[92:95], v[144:147], v[164:167], v[92:95]
	v_mfma_f32_16x16x32_bf16 v[28:31], v[152:155], v[164:167], v[28:31]
	v_mfma_f32_16x16x32_bf16 v[76:79], v[144:147], v[172:175], v[76:79]
	v_mfma_f32_16x16x32_bf16 v[16:19], v[152:155], v[172:175], v[16:19]
	v_mfma_f32_16x16x32_bf16 v[84:87], v[144:147], v[180:183], v[84:87]
	v_mfma_f32_16x16x32_bf16 v[20:23], v[152:155], v[180:183], v[20:23]
	v_mfma_f32_16x16x32_bf16 v[80:83], v[144:147], v[214:217], v[80:83]
	v_mfma_f32_16x16x32_bf16 v[12:15], v[152:155], v[214:217], v[12:15]
	v_mfma_f32_16x16x32_bf16 v[92:95], v[148:151], v[168:171], v[92:95]
	v_mfma_f32_16x16x32_bf16 v[28:31], v[156:159], v[168:171], v[28:31]
	v_mfma_f32_16x16x32_bf16 v[76:79], v[148:151], v[176:179], v[76:79]
	v_mfma_f32_16x16x32_bf16 v[16:19], v[156:159], v[176:179], v[16:19]
	v_mfma_f32_16x16x32_bf16 v[84:87], v[148:151], v[210:213], v[84:87]
	v_mfma_f32_16x16x32_bf16 v[20:23], v[156:159], v[210:213], v[20:23]
	v_mfma_f32_16x16x32_bf16 v[80:83], v[148:151], v[218:221], v[80:83]
	v_mfma_f32_16x16x32_bf16 v[12:15], v[156:159], v[218:221], v[12:15]
	s_barrier
; #define PG8_BAR __builtin_amdgcn_s_barrier()
;     ...
;         if constexpr (ALIGN_EPI) { if (wr == 0) PG8_BAR; }
	s_add_i32 s15, 0, 0x18000
	s_add_i32 s16, 0, 0x1c000
	v_add_u32_e32 v140, s15, v195
	v_add_u32_e32 v156, s16, v195
	ds_read_b128 v[128:131], v140
	ds_read_b128 v[132:135], v140 offset:1024
	ds_read_b128 v[136:139], v140 offset:2048
	ds_read_b128 v[140:143], v140 offset:3072
	ds_read_b128 v[144:147], v156
	ds_read_b128 v[148:151], v156 offset:1024
	ds_read_b128 v[152:155], v156 offset:2048
	ds_read_b128 v[156:159], v156 offset:3072
	s_addk_i32 s14, 0x2000
	v_add_u32_e32 v184, s14, v191
	s_mov_b32 m0, s34
	ds_read_b128 v[164:167], v209 offset:32768
	ds_read_b128 v[168:171], v209 offset:33792
	ds_read_b128 v[172:175], v209 offset:34816
	ds_read_b128 v[176:179], v209 offset:35840
	ds_read_b128 v[180:183], v209 offset:36864
	ds_read_b128 v[210:213], v209 offset:37888
	ds_read_b128 v[214:217], v209 offset:38912
	ds_read_b128 v[218:221], v209 offset:39936
	s_nop 0
	global_load_lds_dwordx4 v184, s[22:23]
	v_add_u32_e32 v184, s14, v193
	s_mov_b32 m0, s35
	s_nop 0
	global_load_lds_dwordx4 v184, s[22:23]
	s_waitcnt vmcnt(8)
	s_waitcnt lgkmcnt(0)
	s_barrier
	s_waitcnt lgkmcnt(0)
	v_mfma_f32_16x16x32_bf16 v[120:123], v[128:131], v[164:167], v[120:123]
	v_mfma_f32_16x16x32_bf16 v[56:59], v[136:139], v[164:167], v[56:59]
	v_mfma_f32_16x16x32_bf16 v[112:115], v[128:131], v[172:175], v[112:115]
	v_mfma_f32_16x16x32_bf16 v[48:51], v[136:139], v[172:175], v[48:51]
	v_mfma_f32_16x16x32_bf16 v[104:107], v[128:131], v[180:183], v[104:107]
	v_mfma_f32_16x16x32_bf16 v[40:43], v[136:139], v[180:183], v[40:43]
	v_mfma_f32_16x16x32_bf16 v[96:99], v[128:131], v[214:217], v[96:99]
	v_mfma_f32_16x16x32_bf16 v[32:35], v[136:139], v[214:217], v[32:35]
	v_mfma_f32_16x16x32_bf16 v[120:123], v[132:135], v[168:171], v[120:123]
	v_mfma_f32_16x16x32_bf16 v[56:59], v[140:143], v[168:171], v[56:59]
	v_mfma_f32_16x16x32_bf16 v[112:115], v[132:135], v[176:179], v[112:115]
	v_mfma_f32_16x16x32_bf16 v[48:51], v[140:143], v[176:179], v[48:51]
	v_mfma_f32_16x16x32_bf16 v[104:107], v[132:135], v[210:213], v[104:107]
	v_mfma_f32_16x16x32_bf16 v[40:43], v[140:143], v[210:213], v[40:43]
	v_mfma_f32_16x16x32_bf16 v[96:99], v[132:135], v[218:221], v[96:99]
	v_mfma_f32_16x16x32_bf16 v[32:35], v[140:143], v[218:221], v[32:35]
	v_mfma_f32_16x16x32_bf16 v[124:127], v[144:147], v[164:167], v[124:127]
	v_mfma_f32_16x16x32_bf16 v[60:63], v[152:155], v[164:167], v[60:63]
	v_mfma_f32_16x16x32_bf16 v[116:119], v[144:147], v[172:175], v[116:119]
	v_mfma_f32_16x16x32_bf16 v[52:55], v[152:155], v[172:175], v[52:55]
	v_mfma_f32_16x16x32_bf16 v[108:111], v[144:147], v[180:183], v[108:111]
	v_mfma_f32_16x16x32_bf16 v[44:47], v[152:155], v[180:183], v[44:47]
	v_mfma_f32_16x16x32_bf16 v[100:103], v[144:147], v[214:217], v[100:103]
	v_mfma_f32_16x16x32_bf16 v[36:39], v[152:155], v[214:217], v[36:39]
	v_mfma_f32_16x16x32_bf16 v[124:127], v[148:151], v[168:171], v[124:127]
	v_mfma_f32_16x16x32_bf16 v[60:63], v[156:159], v[168:171], v[60:63]
	v_mfma_f32_16x16x32_bf16 v[116:119], v[148:151], v[176:179], v[116:119]
	v_mfma_f32_16x16x32_bf16 v[52:55], v[156:159], v[176:179], v[52:55]
	v_mfma_f32_16x16x32_bf16 v[108:111], v[148:151], v[210:213], v[108:111]
	v_mfma_f32_16x16x32_bf16 v[44:47], v[156:159], v[210:213], v[44:47]
	v_mfma_f32_16x16x32_bf16 v[100:103], v[148:151], v[218:221], v[100:103]
	v_mfma_f32_16x16x32_bf16 v[36:39], v[156:159], v[218:221], v[36:39]
	s_barrier
	s_or_b32 s14, s13, 0x80
	v_add_u32_e32 v184, s14, v192
	s_add_i32 s15, s15, s26
	ds_read_b128 v[164:167], v209 offset:49152
	ds_read_b128 v[168:171], v209 offset:50176
	ds_read_b128 v[172:175], v209 offset:51200
	ds_read_b128 v[176:179], v209 offset:52224
	ds_read_b128 v[180:183], v209 offset:53248
	ds_read_b128 v[210:213], v209 offset:54272
	ds_read_b128 v[214:217], v209 offset:55296
	ds_read_b128 v[218:221], v209 offset:56320
	s_mov_b32 m0, s15
	s_add_i32 s13, s13, 0x40080
	global_load_lds_dwordx4 v184, s[36:37]
	v_add_u32_e32 v184, s14, v194
	s_add_i32 m0, s15, 0x2000
	s_add_i32 s14, s16, s26
	global_load_lds_dwordx4 v184, s[36:37]
	v_add_u32_e32 v184, s13, v192
	s_mov_b32 m0, s14
	s_nop 0
	global_load_lds_dwordx4 v184, s[36:37]
	v_add_u32_e32 v184, s13, v194
	s_add_i32 m0, s14, 0x2000
	s_nop 0
	global_load_lds_dwordx4 v184, s[36:37]
	v_add_u32_e32 v184, s12, v191
	s_mov_b32 m0, s61
	s_nop 0
	global_load_lds_dwordx4 v184, s[22:23]
	v_add_u32_e32 v184, s12, v193
	s_mov_b32 m0, s63
	s_nop 0
	global_load_lds_dwordx4 v184, s[22:23]
	s_waitcnt vmcnt(8)
	s_waitcnt lgkmcnt(0)
	s_barrier
	s_waitcnt lgkmcnt(0)
	v_mfma_f32_16x16x32_bf16 v[88:91], v[128:131], v[164:167], v[88:91]
	v_mfma_f32_16x16x32_bf16 v[24:27], v[136:139], v[164:167], v[24:27]
	v_mfma_f32_16x16x32_bf16 v[72:75], v[128:131], v[172:175], v[72:75]
	v_mfma_f32_16x16x32_bf16 v[8:11], v[136:139], v[172:175], v[8:11]
	v_mfma_f32_16x16x32_bf16 v[68:71], v[128:131], v[180:183], v[68:71]
	v_mfma_f32_16x16x32_bf16 v[4:7], v[136:139], v[180:183], v[4:7]
	v_mfma_f32_16x16x32_bf16 v[64:67], v[128:131], v[214:217], v[64:67]
	v_mfma_f32_16x16x32_bf16 v[0:3], v[136:139], v[214:217], v[0:3]
	v_mfma_f32_16x16x32_bf16 v[88:91], v[132:135], v[168:171], v[88:91]
	v_mfma_f32_16x16x32_bf16 v[24:27], v[140:143], v[168:171], v[24:27]
	v_mfma_f32_16x16x32_bf16 v[72:75], v[132:135], v[176:179], v[72:75]
	v_mfma_f32_16x16x32_bf16 v[8:11], v[140:143], v[176:179], v[8:11]
	v_mfma_f32_16x16x32_bf16 v[68:71], v[132:135], v[210:213], v[68:71]
	v_mfma_f32_16x16x32_bf16 v[4:7], v[140:143], v[210:213], v[4:7]
	v_mfma_f32_16x16x32_bf16 v[64:67], v[132:135], v[218:221], v[64:67]
	v_mfma_f32_16x16x32_bf16 v[0:3], v[140:143], v[218:221], v[0:3]
	v_mfma_f32_16x16x32_bf16 v[92:95], v[144:147], v[164:167], v[92:95]
	v_mfma_f32_16x16x32_bf16 v[28:31], v[152:155], v[164:167], v[28:31]
	v_mfma_f32_16x16x32_bf16 v[76:79], v[144:147], v[172:175], v[76:79]
	v_mfma_f32_16x16x32_bf16 v[16:19], v[152:155], v[172:175], v[16:19]
	v_mfma_f32_16x16x32_bf16 v[84:87], v[144:147], v[180:183], v[84:87]
	v_mfma_f32_16x16x32_bf16 v[20:23], v[152:155], v[180:183], v[20:23]
	v_mfma_f32_16x16x32_bf16 v[80:83], v[144:147], v[214:217], v[80:83]
	v_mfma_f32_16x16x32_bf16 v[12:15], v[152:155], v[214:217], v[12:15]
	v_mfma_f32_16x16x32_bf16 v[92:95], v[148:151], v[168:171], v[92:95]
	v_mfma_f32_16x16x32_bf16 v[28:31], v[156:159], v[168:171], v[28:31]
	v_mfma_f32_16x16x32_bf16 v[76:79], v[148:151], v[176:179], v[76:79]
	v_mfma_f32_16x16x32_bf16 v[16:19], v[156:159], v[176:179], v[16:19]
	v_mfma_f32_16x16x32_bf16 v[84:87], v[148:151], v[210:213], v[84:87]
	v_mfma_f32_16x16x32_bf16 v[20:23], v[156:159], v[210:213], v[20:23]
	v_mfma_f32_16x16x32_bf16 v[80:83], v[148:151], v[218:221], v[80:83]
	v_mfma_f32_16x16x32_bf16 v[12:15], v[156:159], v[218:221], v[12:15]
	s_barrier
	s_add_i32 s11, s11, 2
	s_addk_i32 s2, 0x100
	s_addk_i32 s3, 0x100
	s_cmp_gt_u32 s11, 13
	s_cbranch_scc0 .LBB0_780
	s_and_b64 vcc, exec, s[42:43]
	s_cbranch_vccz .LBB0_783
	s_barrier

.LBB0_924:
	v_add_u32_e32 v154, s34, v136
	v_add_u32_e32 v162, s35, v136
	ds_read_b128 v[142:145], v154
	ds_read_b128 v[146:149], v154 offset:1024
	ds_read_b128 v[150:153], v154 offset:2048
	ds_read_b128 v[154:157], v154 offset:3072
	ds_read_b128 v[158:161], v162
	ds_read_b128 v[166:169], v162 offset:1024
	ds_read_b128 v[170:173], v162 offset:2048
	ds_read_b128 v[174:177], v162 offset:3072
	s_add_i32 s43, s46, 0x100
	s_add_i32 s44, s43, s26
	s_add_i32 s45, s39, s46
	s_cmpk_eq_i32 s46, 0x1500
	s_cselect_b32 s47, s40, s44
	s_cselect_b32 s45, s41, s45
	s_or_b32 s44, s47, 0x80
	v_add_u32_e32 v162, s46, v141
	ds_read_b128 v[178:181], v139
	ds_read_b128 v[182:185], v139 offset:1024
	ds_read_b128 v[192:195], v139 offset:2048
	ds_read_b128 v[196:199], v139 offset:3072
	ds_read_b128 v[200:203], v139 offset:4096
	ds_read_b128 v[204:207], v139 offset:5120
	ds_read_b128 v[208:211], v139 offset:6144
	ds_read_b128 v[212:215], v139 offset:7168
	s_add_i32 m0, s24, 0xc000
	s_nop 0
	global_load_lds_dwordx4 v162, s[2:3]
	v_add_u32_e32 v162, s46, v140
	s_add_i32 m0, s24, 0xe000
	s_nop 0
	global_load_lds_dwordx4 v162, s[2:3]
	s_waitcnt vmcnt(8)
	s_waitcnt lgkmcnt(0)
	s_barrier
	s_waitcnt lgkmcnt(0)
	v_mfma_f32_16x16x32_bf16 v[124:127], v[142:145], v[178:181], v[124:127]
	v_mfma_f32_16x16x32_bf16 v[120:123], v[150:153], v[178:181], v[120:123]
	v_mfma_f32_16x16x32_bf16 v[108:111], v[142:145], v[192:195], v[108:111]
	v_mfma_f32_16x16x32_bf16 v[104:107], v[150:153], v[192:195], v[104:107]
	v_mfma_f32_16x16x32_bf16 v[92:95], v[142:145], v[200:203], v[92:95]
	v_mfma_f32_16x16x32_bf16 v[88:91], v[150:153], v[200:203], v[88:91]
	v_mfma_f32_16x16x32_bf16 v[76:79], v[142:145], v[208:211], v[76:79]
	v_mfma_f32_16x16x32_bf16 v[72:75], v[150:153], v[208:211], v[72:75]
	v_mfma_f32_16x16x32_bf16 v[124:127], v[146:149], v[182:185], v[124:127]
	v_mfma_f32_16x16x32_bf16 v[120:123], v[154:157], v[182:185], v[120:123]
	v_mfma_f32_16x16x32_bf16 v[108:111], v[146:149], v[196:199], v[108:111]
	v_mfma_f32_16x16x32_bf16 v[104:107], v[154:157], v[196:199], v[104:107]
	v_mfma_f32_16x16x32_bf16 v[92:95], v[146:149], v[204:207], v[92:95]
	v_mfma_f32_16x16x32_bf16 v[88:91], v[154:157], v[204:207], v[88:91]
	v_mfma_f32_16x16x32_bf16 v[76:79], v[146:149], v[212:215], v[76:79]
	v_mfma_f32_16x16x32_bf16 v[72:75], v[154:157], v[212:215], v[72:75]
	v_mfma_f32_16x16x32_bf16 v[116:119], v[158:161], v[178:181], v[116:119]
	v_mfma_f32_16x16x32_bf16 v[112:115], v[170:173], v[178:181], v[112:115]
	v_mfma_f32_16x16x32_bf16 v[100:103], v[158:161], v[192:195], v[100:103]
	v_mfma_f32_16x16x32_bf16 v[96:99], v[170:173], v[192:195], v[96:99]
	v_mfma_f32_16x16x32_bf16 v[84:87], v[158:161], v[200:203], v[84:87]
	v_mfma_f32_16x16x32_bf16 v[80:83], v[170:173], v[200:203], v[80:83]
	v_mfma_f32_16x16x32_bf16 v[68:71], v[158:161], v[208:211], v[68:71]
	v_mfma_f32_16x16x32_bf16 v[64:67], v[170:173], v[208:211], v[64:67]
	v_mfma_f32_16x16x32_bf16 v[116:119], v[166:169], v[182:185], v[116:119]
	v_mfma_f32_16x16x32_bf16 v[112:115], v[174:177], v[182:185], v[112:115]
	v_mfma_f32_16x16x32_bf16 v[100:103], v[166:169], v[196:199], v[100:103]
	v_mfma_f32_16x16x32_bf16 v[96:99], v[174:177], v[196:199], v[96:99]
	v_mfma_f32_16x16x32_bf16 v[84:87], v[166:169], v[204:207], v[84:87]
	v_mfma_f32_16x16x32_bf16 v[80:83], v[174:177], v[204:207], v[80:83]
	v_mfma_f32_16x16x32_bf16 v[68:71], v[166:169], v[212:215], v[68:71]
	v_mfma_f32_16x16x32_bf16 v[64:67], v[174:177], v[212:215], v[64:67]
	s_barrier
	v_add_u32_e32 v162, s45, v133
	s_add_i32 s46, s34, s23
	ds_read_b128 v[178:181], v139 offset:16384
	ds_read_b128 v[182:185], v139 offset:17408
	ds_read_b128 v[192:195], v139 offset:18432
	ds_read_b128 v[196:199], v139 offset:19456
	ds_read_b128 v[200:203], v139 offset:20480
	ds_read_b128 v[204:207], v139 offset:21504
	ds_read_b128 v[208:211], v139 offset:22528
	ds_read_b128 v[212:215], v139 offset:23552
	s_mov_b32 m0, s46
	s_add_i32 s48, s35, s23
	global_load_lds_dwordx4 v162, s[14:15]
	v_add_u32_e32 v162, s45, v135
	s_add_i32 m0, s46, 0x2000
	s_add_i32 s46, s45, 0xb0000
	global_load_lds_dwordx4 v162, s[14:15]
	v_add_u32_e32 v162, s46, v133
	s_mov_b32 m0, s48
	s_nop 0
	global_load_lds_dwordx4 v162, s[14:15]
	v_add_u32_e32 v162, s46, v135
	s_add_i32 m0, s48, 0x2000
	s_nop 0
	global_load_lds_dwordx4 v162, s[14:15]
	v_add_u32_e32 v162, s47, v132
	s_mov_b32 m0, s24
	s_nop 0
	global_load_lds_dwordx4 v162, s[2:3]
	v_add_u32_e32 v162, s47, v134
	s_mov_b32 m0, s27
	s_nop 0
	global_load_lds_dwordx4 v162, s[2:3]
	s_waitcnt vmcnt(8)
	s_waitcnt lgkmcnt(0)
	s_barrier
	s_waitcnt lgkmcnt(0)
	v_mfma_f32_16x16x32_bf16 v[60:63], v[142:145], v[178:181], v[60:63]
	v_mfma_f32_16x16x32_bf16 v[56:59], v[150:153], v[178:181], v[56:59]
	v_mfma_f32_16x16x32_bf16 v[44:47], v[142:145], v[192:195], v[44:47]
	v_mfma_f32_16x16x32_bf16 v[40:43], v[150:153], v[192:195], v[40:43]
	v_mfma_f32_16x16x32_bf16 v[28:31], v[142:145], v[200:203], v[28:31]
	v_mfma_f32_16x16x32_bf16 v[24:27], v[150:153], v[200:203], v[24:27]
	v_mfma_f32_16x16x32_bf16 v[12:15], v[142:145], v[208:211], v[12:15]
	v_mfma_f32_16x16x32_bf16 v[8:11], v[150:153], v[208:211], v[8:11]
	v_mfma_f32_16x16x32_bf16 v[60:63], v[146:149], v[182:185], v[60:63]
	v_mfma_f32_16x16x32_bf16 v[56:59], v[154:157], v[182:185], v[56:59]
	v_mfma_f32_16x16x32_bf16 v[44:47], v[146:149], v[196:199], v[44:47]
	v_mfma_f32_16x16x32_bf16 v[40:43], v[154:157], v[196:199], v[40:43]
	v_mfma_f32_16x16x32_bf16 v[28:31], v[146:149], v[204:207], v[28:31]
	v_mfma_f32_16x16x32_bf16 v[24:27], v[154:157], v[204:207], v[24:27]
	v_mfma_f32_16x16x32_bf16 v[12:15], v[146:149], v[212:215], v[12:15]
	v_mfma_f32_16x16x32_bf16 v[8:11], v[154:157], v[212:215], v[8:11]
	v_mfma_f32_16x16x32_bf16 v[52:55], v[158:161], v[178:181], v[52:55]
	v_mfma_f32_16x16x32_bf16 v[48:51], v[170:173], v[178:181], v[48:51]
	v_mfma_f32_16x16x32_bf16 v[36:39], v[158:161], v[192:195], v[36:39]
	v_mfma_f32_16x16x32_bf16 v[32:35], v[170:173], v[192:195], v[32:35]
	v_mfma_f32_16x16x32_bf16 v[20:23], v[158:161], v[200:203], v[20:23]
	v_mfma_f32_16x16x32_bf16 v[16:19], v[170:173], v[200:203], v[16:19]
	v_mfma_f32_16x16x32_bf16 v[4:7], v[158:161], v[208:211], v[4:7]
	v_mfma_f32_16x16x32_bf16 v[0:3], v[170:173], v[208:211], v[0:3]
	v_mfma_f32_16x16x32_bf16 v[52:55], v[166:169], v[182:185], v[52:55]
	v_mfma_f32_16x16x32_bf16 v[48:51], v[174:177], v[182:185], v[48:51]
	v_mfma_f32_16x16x32_bf16 v[36:39], v[166:169], v[196:199], v[36:39]
	v_mfma_f32_16x16x32_bf16 v[32:35], v[174:177], v[196:199], v[32:35]
	v_mfma_f32_16x16x32_bf16 v[20:23], v[166:169], v[204:207], v[20:23]
	v_mfma_f32_16x16x32_bf16 v[16:19], v[174:177], v[204:207], v[16:19]
	v_mfma_f32_16x16x32_bf16 v[4:7], v[166:169], v[212:215], v[4:7]
	v_mfma_f32_16x16x32_bf16 v[0:3], v[174:177], v[212:215], v[0:3]
	s_barrier
	s_add_i32 s46, 0, 0x18000
	s_add_i32 s48, 0, 0x1c000
	v_add_u32_e32 v154, s46, v136
	v_add_u32_e32 v162, s48, v136
	ds_read_b128 v[142:145], v154
	ds_read_b128 v[146:149], v154 offset:1024
	ds_read_b128 v[150:153], v154 offset:2048
	ds_read_b128 v[154:157], v154 offset:3072
	ds_read_b128 v[158:161], v162
	ds_read_b128 v[166:169], v162 offset:1024
	ds_read_b128 v[170:173], v162 offset:2048
	ds_read_b128 v[174:177], v162 offset:3072
	s_add_i32 s47, s47, 0xb0000
	v_add_u32_e32 v162, s47, v132
	s_mov_b32 m0, s28
	ds_read_b128 v[178:181], v139 offset:32768
	ds_read_b128 v[182:185], v139 offset:33792
	ds_read_b128 v[192:195], v139 offset:34816
	ds_read_b128 v[196:199], v139 offset:35840
	ds_read_b128 v[200:203], v139 offset:36864
	ds_read_b128 v[204:207], v139 offset:37888
	ds_read_b128 v[208:211], v139 offset:38912
	ds_read_b128 v[212:215], v139 offset:39936
	s_nop 0
	global_load_lds_dwordx4 v162, s[2:3]
	v_add_u32_e32 v162, s47, v134
	s_mov_b32 m0, s29
	s_nop 0
	global_load_lds_dwordx4 v162, s[2:3]
	s_waitcnt vmcnt(8)
	s_waitcnt lgkmcnt(0)
	s_barrier
	s_waitcnt lgkmcnt(0)
	v_mfma_f32_16x16x32_bf16 v[124:127], v[142:145], v[178:181], v[124:127]
	v_mfma_f32_16x16x32_bf16 v[120:123], v[150:153], v[178:181], v[120:123]
	v_mfma_f32_16x16x32_bf16 v[108:111], v[142:145], v[192:195], v[108:111]
	v_mfma_f32_16x16x32_bf16 v[104:107], v[150:153], v[192:195], v[104:107]
	v_mfma_f32_16x16x32_bf16 v[92:95], v[142:145], v[200:203], v[92:95]
	v_mfma_f32_16x16x32_bf16 v[88:91], v[150:153], v[200:203], v[88:91]
	v_mfma_f32_16x16x32_bf16 v[76:79], v[142:145], v[208:211], v[76:79]
	v_mfma_f32_16x16x32_bf16 v[72:75], v[150:153], v[208:211], v[72:75]
	v_mfma_f32_16x16x32_bf16 v[124:127], v[146:149], v[182:185], v[124:127]
	v_mfma_f32_16x16x32_bf16 v[120:123], v[154:157], v[182:185], v[120:123]
	v_mfma_f32_16x16x32_bf16 v[108:111], v[146:149], v[196:199], v[108:111]
	v_mfma_f32_16x16x32_bf16 v[104:107], v[154:157], v[196:199], v[104:107]
	v_mfma_f32_16x16x32_bf16 v[92:95], v[146:149], v[204:207], v[92:95]
	v_mfma_f32_16x16x32_bf16 v[88:91], v[154:157], v[204:207], v[88:91]
	v_mfma_f32_16x16x32_bf16 v[76:79], v[146:149], v[212:215], v[76:79]
	v_mfma_f32_16x16x32_bf16 v[72:75], v[154:157], v[212:215], v[72:75]
	v_mfma_f32_16x16x32_bf16 v[116:119], v[158:161], v[178:181], v[116:119]
	v_mfma_f32_16x16x32_bf16 v[112:115], v[170:173], v[178:181], v[112:115]
	v_mfma_f32_16x16x32_bf16 v[100:103], v[158:161], v[192:195], v[100:103]
	v_mfma_f32_16x16x32_bf16 v[96:99], v[170:173], v[192:195], v[96:99]
	v_mfma_f32_16x16x32_bf16 v[84:87], v[158:161], v[200:203], v[84:87]
	v_mfma_f32_16x16x32_bf16 v[80:83], v[170:173], v[200:203], v[80:83]
	v_mfma_f32_16x16x32_bf16 v[68:71], v[158:161], v[208:211], v[68:71]
	v_mfma_f32_16x16x32_bf16 v[64:67], v[170:173], v[208:211], v[64:67]
	v_mfma_f32_16x16x32_bf16 v[116:119], v[166:169], v[182:185], v[116:119]
	v_mfma_f32_16x16x32_bf16 v[112:115], v[174:177], v[182:185], v[112:115]
	v_mfma_f32_16x16x32_bf16 v[100:103], v[166:169], v[196:199], v[100:103]
	v_mfma_f32_16x16x32_bf16 v[96:99], v[174:177], v[196:199], v[96:99]
	v_mfma_f32_16x16x32_bf16 v[84:87], v[166:169], v[204:207], v[84:87]
	v_mfma_f32_16x16x32_bf16 v[80:83], v[174:177], v[204:207], v[80:83]
	v_mfma_f32_16x16x32_bf16 v[68:71], v[166:169], v[212:215], v[68:71]
	v_mfma_f32_16x16x32_bf16 v[64:67], v[174:177], v[212:215], v[64:67]
	s_barrier
;     ...
;         if (!has_next) break;
; #pragma unroll
;         for (int a = 0; a < 2; ++a)
; #pragma unroll
;             for (int b = 0; b < 2; ++b)
; #pragma unroll
;                 for (int m = 0; m < 4; ++m)
; #pragma unroll
;                     for (int n = 0; n < 2; ++n) acc[a][b][m][n] = (f32x4){0.f, 0.f, 0.f, 0.f};
;         cur = nxt; cA = nA; cB = nB; ++ui;
	s_or_b32 s47, s45, 0x80
	v_add_u32_e32 v162, s47, v133
	s_add_i32 s46, s46, s23
	ds_read_b128 v[178:181], v139 offset:49152
	ds_read_b128 v[182:185], v139 offset:50176
	ds_read_b128 v[192:195], v139 offset:51200
	ds_read_b128 v[196:199], v139 offset:52224
	ds_read_b128 v[200:203], v139 offset:53248
	ds_read_b128 v[204:207], v139 offset:54272
	ds_read_b128 v[208:211], v139 offset:55296
	ds_read_b128 v[212:215], v139 offset:56320
	s_mov_b32 m0, s46
	s_add_i32 s45, s45, 0xb0080
	global_load_lds_dwordx4 v162, s[14:15]
	v_add_u32_e32 v162, s47, v135
	s_add_i32 m0, s46, 0x2000
	s_add_i32 s46, s48, s23
	global_load_lds_dwordx4 v162, s[14:15]
	v_add_u32_e32 v162, s45, v133
	s_mov_b32 m0, s46
	s_nop 0
	global_load_lds_dwordx4 v162, s[14:15]
	v_add_u32_e32 v162, s45, v135
	s_add_i32 m0, s46, 0x2000
	s_nop 0
	global_load_lds_dwordx4 v162, s[14:15]
	v_add_u32_e32 v162, s44, v132
	s_mov_b32 m0, s30
	s_nop 0
	global_load_lds_dwordx4 v162, s[2:3]
	v_add_u32_e32 v162, s44, v134
	s_mov_b32 m0, s31
	s_nop 0
	global_load_lds_dwordx4 v162, s[2:3]
	s_waitcnt vmcnt(8)
	s_waitcnt lgkmcnt(0)
	s_barrier
	s_waitcnt lgkmcnt(0)
	v_mfma_f32_16x16x32_bf16 v[60:63], v[142:145], v[178:181], v[60:63]
	v_mfma_f32_16x16x32_bf16 v[56:59], v[150:153], v[178:181], v[56:59]
	v_mfma_f32_16x16x32_bf16 v[44:47], v[142:145], v[192:195], v[44:47]
	v_mfma_f32_16x16x32_bf16 v[40:43], v[150:153], v[192:195], v[40:43]
	v_mfma_f32_16x16x32_bf16 v[28:31], v[142:145], v[200:203], v[28:31]
	v_mfma_f32_16x16x32_bf16 v[24:27], v[150:153], v[200:203], v[24:27]
	v_mfma_f32_16x16x32_bf16 v[12:15], v[142:145], v[208:211], v[12:15]
	v_mfma_f32_16x16x32_bf16 v[8:11], v[150:153], v[208:211], v[8:11]
	v_mfma_f32_16x16x32_bf16 v[60:63], v[146:149], v[182:185], v[60:63]
	v_mfma_f32_16x16x32_bf16 v[56:59], v[154:157], v[182:185], v[56:59]
	v_mfma_f32_16x16x32_bf16 v[44:47], v[146:149], v[196:199], v[44:47]
	v_mfma_f32_16x16x32_bf16 v[40:43], v[154:157], v[196:199], v[40:43]
	v_mfma_f32_16x16x32_bf16 v[28:31], v[146:149], v[204:207], v[28:31]
	v_mfma_f32_16x16x32_bf16 v[24:27], v[154:157], v[204:207], v[24:27]
	v_mfma_f32_16x16x32_bf16 v[12:15], v[146:149], v[212:215], v[12:15]
	v_mfma_f32_16x16x32_bf16 v[8:11], v[154:157], v[212:215], v[8:11]
	v_mfma_f32_16x16x32_bf16 v[52:55], v[158:161], v[178:181], v[52:55]
	v_mfma_f32_16x16x32_bf16 v[48:51], v[170:173], v[178:181], v[48:51]
	v_mfma_f32_16x16x32_bf16 v[36:39], v[158:161], v[192:195], v[36:39]
	v_mfma_f32_16x16x32_bf16 v[32:35], v[170:173], v[192:195], v[32:35]
	v_mfma_f32_16x16x32_bf16 v[20:23], v[158:161], v[200:203], v[20:23]
	v_mfma_f32_16x16x32_bf16 v[16:19], v[170:173], v[200:203], v[16:19]
	v_mfma_f32_16x16x32_bf16 v[4:7], v[158:161], v[208:211], v[4:7]
	v_mfma_f32_16x16x32_bf16 v[0:3], v[170:173], v[208:211], v[0:3]
	v_mfma_f32_16x16x32_bf16 v[52:55], v[166:169], v[182:185], v[52:55]
	v_mfma_f32_16x16x32_bf16 v[48:51], v[174:177], v[182:185], v[48:51]
	v_mfma_f32_16x16x32_bf16 v[36:39], v[166:169], v[196:199], v[36:39]
	v_mfma_f32_16x16x32_bf16 v[32:35], v[174:177], v[196:199], v[32:35]
	v_mfma_f32_16x16x32_bf16 v[20:23], v[166:169], v[204:207], v[20:23]
	v_mfma_f32_16x16x32_bf16 v[16:19], v[174:177], v[204:207], v[16:19]
	v_mfma_f32_16x16x32_bf16 v[4:7], v[166:169], v[212:215], v[4:7]
	v_mfma_f32_16x16x32_bf16 v[0:3], v[174:177], v[212:215], v[0:3]
	s_barrier
	s_add_i32 s42, s42, 2
	s_cmp_gt_u32 s42, 41
	s_mov_b32 s46, s43
	s_cbranch_scc0 .LBB0_924
	s_andn2_b64 vcc, exec, s[4:5]
	s_cbranch_vccnz .LBB0_916
	v_mov_b32_e32 v0, 0
	s_mov_b32 s12, s36
	s_mov_b32 s19, s37
	s_mov_b32 s25, s17
	s_mov_b32 s26, s16
	s_mov_b32 s33, s38
	v_mov_b32_e32 v1, v0
	v_mov_b32_e32 v2, v0
	v_mov_b32_e32 v3, v0
	v_mov_b32_e32 v4, v0
	v_mov_b32_e32 v5, v0
	v_mov_b32_e32 v6, v0
	v_mov_b32_e32 v7, v0
	v_mov_b32_e32 v16, v0
	v_mov_b32_e32 v17, v0
	v_mov_b32_e32 v18, v0
	v_mov_b32_e32 v19, v0
	v_mov_b32_e32 v20, v0
	v_mov_b32_e32 v21, v0
	v_mov_b32_e32 v22, v0
	v_mov_b32_e32 v23, v0
	v_mov_b32_e32 v32, v0
	v_mov_b32_e32 v33, v0
	v_mov_b32_e32 v34, v0
	v_mov_b32_e32 v35, v0
	v_mov_b32_e32 v36, v0
	v_mov_b32_e32 v37, v0
	v_mov_b32_e32 v38, v0
	v_mov_b32_e32 v39, v0
	v_mov_b32_e32 v48, v0
	v_mov_b32_e32 v49, v0
	v_mov_b32_e32 v50, v0
	v_mov_b32_e32 v51, v0
	v_mov_b32_e32 v52, v0
	v_mov_b32_e32 v53, v0
	v_mov_b32_e32 v54, v0
	v_mov_b32_e32 v55, v0
	v_mov_b32_e32 v8, v0
	v_mov_b32_e32 v9, v0
	v_mov_b32_e32 v10, v0
	v_mov_b32_e32 v11, v0
	v_mov_b32_e32 v12, v0
	v_mov_b32_e32 v13, v0
	v_mov_b32_e32 v14, v0
	v_mov_b32_e32 v15, v0
	v_mov_b32_e32 v24, v0
	v_mov_b32_e32 v25, v0
	v_mov_b32_e32 v26, v0
	v_mov_b32_e32 v27, v0
	v_mov_b32_e32 v28, v0
	v_mov_b32_e32 v29, v0
	v_mov_b32_e32 v30, v0
	v_mov_b32_e32 v31, v0
	v_mov_b32_e32 v40, v0
	v_mov_b32_e32 v41, v0
	v_mov_b32_e32 v42, v0
	v_mov_b32_e32 v43, v0
	v_mov_b32_e32 v44, v0
	v_mov_b32_e32 v45, v0
	v_mov_b32_e32 v46, v0
	v_mov_b32_e32 v47, v0
	v_mov_b32_e32 v56, v0
	v_mov_b32_e32 v57, v0
	v_mov_b32_e32 v58, v0
	v_mov_b32_e32 v59, v0
	v_mov_b32_e32 v60, v0
	v_mov_b32_e32 v61, v0
	v_mov_b32_e32 v62, v0
	v_mov_b32_e32 v63, v0
	v_mov_b32_e32 v64, v0
	v_mov_b32_e32 v65, v0
	v_mov_b32_e32 v66, v0
	v_mov_b32_e32 v67, v0
	v_mov_b32_e32 v68, v0
	v_mov_b32_e32 v69, v0
	v_mov_b32_e32 v70, v0
	v_mov_b32_e32 v71, v0
	v_mov_b32_e32 v80, v0
	v_mov_b32_e32 v81, v0
	v_mov_b32_e32 v82, v0
	v_mov_b32_e32 v83, v0
	v_mov_b32_e32 v84, v0
	v_mov_b32_e32 v85, v0
	v_mov_b32_e32 v86, v0
	v_mov_b32_e32 v87, v0
	v_mov_b32_e32 v96, v0
	v_mov_b32_e32 v97, v0
	v_mov_b32_e32 v98, v0
	v_mov_b32_e32 v99, v0
	v_mov_b32_e32 v100, v0
	v_mov_b32_e32 v101, v0
	v_mov_b32_e32 v102, v0
	v_mov_b32_e32 v103, v0
	v_mov_b32_e32 v112, v0
	v_mov_b32_e32 v113, v0
	v_mov_b32_e32 v114, v0
	v_mov_b32_e32 v115, v0
	v_mov_b32_e32 v116, v0
	v_mov_b32_e32 v117, v0
	v_mov_b32_e32 v118, v0
	v_mov_b32_e32 v119, v0
	v_mov_b32_e32 v72, v0
	v_mov_b32_e32 v73, v0
	v_mov_b32_e32 v74, v0
	v_mov_b32_e32 v75, v0
	v_mov_b32_e32 v76, v0
	v_mov_b32_e32 v77, v0
	v_mov_b32_e32 v78, v0
	v_mov_b32_e32 v79, v0
	v_mov_b32_e32 v88, v0
	v_mov_b32_e32 v89, v0
	v_mov_b32_e32 v90, v0
	v_mov_b32_e32 v91, v0
	v_mov_b32_e32 v92, v0
	v_mov_b32_e32 v93, v0
	v_mov_b32_e32 v94, v0
	v_mov_b32_e32 v95, v0
	v_mov_b32_e32 v104, v0
	v_mov_b32_e32 v105, v0
	v_mov_b32_e32 v106, v0
	v_mov_b32_e32 v107, v0
	v_mov_b32_e32 v108, v0
	v_mov_b32_e32 v109, v0
	v_mov_b32_e32 v110, v0
	v_mov_b32_e32 v111, v0
	v_mov_b32_e32 v120, v0
	v_mov_b32_e32 v121, v0
	v_mov_b32_e32 v122, v0
	v_mov_b32_e32 v123, v0
	v_mov_b32_e32 v124, v0
	v_mov_b32_e32 v125, v0
	v_mov_b32_e32 v126, v0
	v_mov_b32_e32 v127, v0
	s_branch .LBB0_916
